# GU/INM weights stored K-blocked in LDS-image order (contiguous 16 KB per K-step) + lru_pass1 k-loop weight loads hoisted (16 loads per iteration, counted waits)
# speedup vs baseline: 1.1906x; 1.0230x over previous
.LBB0_24:
	s_ashr_i32 s4, s13, 31
	s_lshr_b32 s4, s4, 28
	s_add_i32 s4, s13, s4
	s_ashr_i32 s14, s4, 4
	s_lshl_b32 s4, s14, 10
	s_lshl_b32 s5, s14, 6
	s_lshl_b32 s14, s14, 5
	v_or_b32_e32 v0, s5, v2
	s_andn2_b32 s14, s14, 63
	v_lshrrev_b32_e32 v0, 1, v0
	v_add_u32_e32 v1, s14, v6
	v_and_or_b32 v0, v0, 48, v1
	s_sub_i32 s4, s12, s4
	v_ashrrev_i32_e32 v1, 31, v0
	v_lshl_add_u64 v[0:1], v[0:1], 2, s[2:3]
	v_add_u32_e32 v11, s4, v3
	v_mad_i64_i32 v[12:13], s[14:15], v11, s74, v[0:1]
	s_barrier
	global_load_dword v30, v[12:13], off
	v_add_u32_e32 v26, s5, v4
	v_and_b32_e32 v47, 0xffffff00, v26
	v_lshlrev_b32_e32 v47, 11, v47
	v_and_b32_e32 v48, 0xff, v26
	v_lshl_add_u32 v47, v48, 6, v47
	s_lshl_b32 s5, s4, 9
	v_add_u32_e32 v47, s5, v47
	v_lshrrev_b32_e32 v48, 5, v200
	v_lshrrev_b32_e32 v49, 1, v48
	v_lshl_add_u32 v47, v49, 14, v47
	v_and_b32_e32 v48, 1, v48
	v_lshlrev_b32_e32 v48, 1, v48
	v_bfe_u32 v49, v26, 3, 1
	v_mul_u32_u24_e32 v49, 3, v49
	v_xor_b32_e32 v48, v48, v49
	v_lshl_add_u32 v26, v48, 4, v47
	v_xor_b32_e32 v48, 1, v48
	v_lshl_add_u32 v46, v48, 4, v47
	v_mov_b32_e32 v27, 0
	v_mov_b32_e32 v47, 0
	v_lshl_add_u64 v[26:27], s[16:17], 0, v[26:27]
	v_lshl_add_u64 v[46:47], s[16:17], 0, v[46:47]
	s_add_i32 s13, s13, s33
	s_add_i32 s12, s12, s68
	s_cmpk_lt_i32 s13, 0x580
	v_add_u32_e32 v12, 4, v11
	v_mad_i64_i32 v[12:13], s[14:15], v12, s74, v[0:1]
	global_load_dword v31, v[12:13], off
	v_add_u32_e32 v12, 8, v11
	v_mad_i64_i32 v[12:13], s[14:15], v12, s74, v[0:1]
	global_load_dword v32, v[12:13], off
	v_add_u32_e32 v12, 12, v11
	v_mad_i64_i32 v[12:13], s[14:15], v12, s74, v[0:1]
	global_load_dword v33, v[12:13], off
	v_add_u32_e32 v12, 16, v11
	v_mad_i64_i32 v[12:13], s[14:15], v12, s74, v[0:1]
	global_load_dword v34, v[12:13], off
	v_add_u32_e32 v12, 20, v11
	v_mad_i64_i32 v[12:13], s[14:15], v12, s74, v[0:1]
	global_load_dword v35, v[12:13], off
	v_add_u32_e32 v12, 24, v11
	v_mad_i64_i32 v[12:13], s[14:15], v12, s74, v[0:1]
	global_load_dword v36, v[12:13], off
	v_add_u32_e32 v12, 28, v11
	v_mad_i64_i32 v[12:13], s[14:15], v12, s74, v[0:1]
	global_load_dword v37, v[12:13], off
	v_add_u32_e32 v12, 32, v11
	v_mad_i64_i32 v[12:13], s[14:15], v12, s74, v[0:1]
	global_load_dword v38, v[12:13], off
	v_add_u32_e32 v12, 36, v11
	v_mad_i64_i32 v[12:13], s[14:15], v12, s74, v[0:1]
	global_load_dword v39, v[12:13], off
	v_add_u32_e32 v12, 40, v11
	v_mad_i64_i32 v[12:13], s[14:15], v12, s74, v[0:1]
	global_load_dword v40, v[12:13], off
	v_add_u32_e32 v12, 44, v11
	v_mad_i64_i32 v[12:13], s[14:15], v12, s74, v[0:1]
	global_load_dword v41, v[12:13], off
	v_add_u32_e32 v12, 48, v11
	v_mad_i64_i32 v[12:13], s[14:15], v12, s74, v[0:1]
	global_load_dword v42, v[12:13], off
	v_add_u32_e32 v12, 52, v11
	v_mad_i64_i32 v[12:13], s[14:15], v12, s74, v[0:1]
	global_load_dword v43, v[12:13], off
	v_add_u32_e32 v12, 56, v11
	v_add_u32_e32 v11, 60, v11
	v_mad_i64_i32 v[12:13], s[14:15], v12, s74, v[0:1]
	v_mad_i64_i32 v[0:1], s[14:15], v11, s74, v[0:1]
	global_load_dword v44, v[12:13], off
	s_nop 0
	global_load_dword v45, v[0:1], off
	s_waitcnt vmcnt(15)
	ds_write_b32 v7, v30
	s_waitcnt vmcnt(14)
	ds_write_b32 v7, v31 offset:1040
	s_waitcnt vmcnt(13)
	ds_write_b32 v7, v32 offset:2080
	s_waitcnt vmcnt(12)
	ds_write_b32 v7, v33 offset:3120
	s_waitcnt vmcnt(11)
	ds_write_b32 v7, v34 offset:4160
	s_waitcnt vmcnt(10)
	ds_write_b32 v7, v35 offset:5200
	s_waitcnt vmcnt(9)
	ds_write_b32 v7, v36 offset:6240
	s_waitcnt vmcnt(8)
	ds_write_b32 v7, v37 offset:7280
	s_waitcnt vmcnt(7)
	ds_write_b32 v7, v38 offset:8320
	s_waitcnt vmcnt(6)
	ds_write_b32 v7, v39 offset:9360
	s_waitcnt vmcnt(5)
	ds_write_b32 v7, v40 offset:10400
	s_waitcnt vmcnt(4)
	ds_write_b32 v7, v41 offset:11440
	s_waitcnt vmcnt(3)
	ds_write_b32 v7, v42 offset:12480
	s_waitcnt vmcnt(2)
	ds_write_b32 v7, v43 offset:13520
	s_waitcnt vmcnt(1)
	ds_write_b32 v7, v44 offset:14560
	s_waitcnt vmcnt(0)
	ds_write_b32 v7, v45 offset:15600
	s_waitcnt lgkmcnt(0)
	s_barrier
	ds_read2_b32 v[0:1], v5 offset1:65
	ds_read2_b32 v[12:13], v5 offset0:130 offset1:195
	ds_read2_b32 v[14:15], v8 offset0:4 offset1:69
	ds_read2_b32 v[16:17], v8 offset0:134 offset1:199
	ds_read2_b32 v[18:19], v9 offset0:8 offset1:73
	ds_read2_b32 v[20:21], v9 offset0:138 offset1:203
	ds_read2_b32 v[22:23], v10 offset0:12 offset1:77
	ds_read2_b32 v[24:25], v10 offset0:142 offset1:207
	s_waitcnt lgkmcnt(6)
	v_and_b32_sdwa v11, v12, v232 dst_sel:DWORD dst_unused:UNUSED_PAD src0_sel:WORD_1 src1_sel:DWORD
	v_and_b32_sdwa v28, v0, v232 dst_sel:DWORD dst_unused:UNUSED_PAD src0_sel:WORD_1 src1_sel:DWORD
	v_add3_u32 v0, v0, v28, s69
	v_add3_u32 v11, v12, v11, s69
	v_and_b32_sdwa v12, v13, v232 dst_sel:DWORD dst_unused:UNUSED_PAD src0_sel:WORD_1 src1_sel:DWORD
	v_and_b32_sdwa v28, v1, v232 dst_sel:DWORD dst_unused:UNUSED_PAD src0_sel:WORD_1 src1_sel:DWORD
	v_add3_u32 v12, v13, v12, s69
	v_add3_u32 v1, v1, v28, s69
	v_and_b32_e32 v12, 0xffff0000, v12
	v_and_b32_e32 v1, 0xffff0000, v1
	v_or_b32_sdwa v13, v12, v11 dst_sel:DWORD dst_unused:UNUSED_PAD src0_sel:DWORD src1_sel:WORD_1
	v_or_b32_sdwa v12, v1, v0 dst_sel:DWORD dst_unused:UNUSED_PAD src0_sel:DWORD src1_sel:WORD_1
	s_waitcnt lgkmcnt(5)
	v_and_b32_sdwa v1, v14, v232 dst_sel:DWORD dst_unused:UNUSED_PAD src0_sel:WORD_1 src1_sel:DWORD
	v_add3_u32 v1, v14, v1, s69
	s_waitcnt lgkmcnt(4)
	v_and_b32_sdwa v11, v17, v232 dst_sel:DWORD dst_unused:UNUSED_PAD src0_sel:WORD_1 src1_sel:DWORD
	v_and_b32_sdwa v14, v15, v232 dst_sel:DWORD dst_unused:UNUSED_PAD src0_sel:WORD_1 src1_sel:DWORD
	v_and_b32_sdwa v0, v16, v232 dst_sel:DWORD dst_unused:UNUSED_PAD src0_sel:WORD_1 src1_sel:DWORD
	v_add3_u32 v11, v17, v11, s69
	v_add3_u32 v14, v15, v14, s69
	v_add3_u32 v0, v16, v0, s69
	v_and_b32_e32 v11, 0xffff0000, v11
	v_and_b32_e32 v14, 0xffff0000, v14
	v_or_b32_sdwa v15, v11, v0 dst_sel:DWORD dst_unused:UNUSED_PAD src0_sel:DWORD src1_sel:WORD_1
	v_or_b32_sdwa v14, v14, v1 dst_sel:DWORD dst_unused:UNUSED_PAD src0_sel:DWORD src1_sel:WORD_1
	s_waitcnt lgkmcnt(2)
	v_and_b32_sdwa v11, v21, v232 dst_sel:DWORD dst_unused:UNUSED_PAD src0_sel:WORD_1 src1_sel:DWORD
	global_store_dwordx4 v[26:27], v[12:15], off
	v_and_b32_sdwa v0, v20, v232 dst_sel:DWORD dst_unused:UNUSED_PAD src0_sel:WORD_1 src1_sel:DWORD
	v_add3_u32 v11, v21, v11, s69
	v_and_b32_sdwa v12, v19, v232 dst_sel:DWORD dst_unused:UNUSED_PAD src0_sel:WORD_1 src1_sel:DWORD
	v_and_b32_sdwa v1, v18, v232 dst_sel:DWORD dst_unused:UNUSED_PAD src0_sel:WORD_1 src1_sel:DWORD
	v_add3_u32 v0, v20, v0, s69
	v_add3_u32 v12, v19, v12, s69
	v_and_b32_e32 v11, 0xffff0000, v11
	v_add3_u32 v1, v18, v1, s69
	v_and_b32_e32 v12, 0xffff0000, v12
	v_or_b32_sdwa v13, v11, v0 dst_sel:DWORD dst_unused:UNUSED_PAD src0_sel:DWORD src1_sel:WORD_1
	s_waitcnt lgkmcnt(0)
	v_and_b32_sdwa v11, v25, v232 dst_sel:DWORD dst_unused:UNUSED_PAD src0_sel:WORD_1 src1_sel:DWORD
	v_and_b32_sdwa v14, v23, v232 dst_sel:DWORD dst_unused:UNUSED_PAD src0_sel:WORD_1 src1_sel:DWORD
	v_or_b32_sdwa v12, v12, v1 dst_sel:DWORD dst_unused:UNUSED_PAD src0_sel:DWORD src1_sel:WORD_1
	v_and_b32_sdwa v0, v24, v232 dst_sel:DWORD dst_unused:UNUSED_PAD src0_sel:WORD_1 src1_sel:DWORD
	v_and_b32_sdwa v1, v22, v232 dst_sel:DWORD dst_unused:UNUSED_PAD src0_sel:WORD_1 src1_sel:DWORD
	v_add3_u32 v11, v25, v11, s69
	v_add3_u32 v14, v23, v14, s69
	v_add3_u32 v1, v22, v1, s69
	v_add3_u32 v0, v24, v0, s69
	v_and_b32_e32 v11, 0xffff0000, v11
	v_and_b32_e32 v14, 0xffff0000, v14
	v_or_b32_sdwa v15, v11, v0 dst_sel:DWORD dst_unused:UNUSED_PAD src0_sel:DWORD src1_sel:WORD_1
	v_or_b32_sdwa v14, v14, v1 dst_sel:DWORD dst_unused:UNUSED_PAD src0_sel:DWORD src1_sel:WORD_1
	global_store_dwordx4 v[46:47], v[12:15], off
	s_cbranch_scc1 .LBB0_24

.LBB0_30:
	s_ashr_i32 s12, s15, 31
	s_lshr_b32 s12, s12, 28
	s_add_i32 s12, s15, s12
	s_ashr_i32 s13, s12, 4
	s_lshl_b32 s12, s13, 10
	s_lshl_b32 s13, s13, 6
	v_or_b32_e32 v0, s13, v4
	v_cmp_gt_i32_e32 vcc, s30, v0
	v_add_u32_e32 v1, 8, v0
	s_sub_i32 s12, s14, s12
	v_cndmask_b32_e32 v0, v1, v0, vcc
	v_ashrrev_i32_e32 v1, 31, v0
	v_lshl_add_u64 v[0:1], v[0:1], 2, s[2:3]
	v_add_u32_e32 v9, s12, v5
	v_mad_i64_i32 v[2:3], s[16:17], v9, s18, v[0:1]
	s_barrier
	global_load_dword v30, v[2:3], off
	v_add_u32_e32 v22, s13, v6
	v_and_b32_e32 v47, 0xffffff00, v22
	v_lshlrev_b32_e32 v47, 11, v47
	v_and_b32_e32 v48, 0xff, v22
	v_lshl_add_u32 v47, v48, 6, v47
	s_lshl_b32 s13, s12, 9
	v_add_u32_e32 v47, s13, v47
	v_lshrrev_b32_e32 v48, 5, v200
	v_lshrrev_b32_e32 v49, 1, v48
	v_lshl_add_u32 v47, v49, 14, v47
	v_and_b32_e32 v48, 1, v48
	v_lshlrev_b32_e32 v48, 1, v48
	v_bfe_u32 v49, v22, 3, 1
	v_mul_u32_u24_e32 v49, 3, v49
	v_xor_b32_e32 v48, v48, v49
	v_lshl_add_u32 v22, v48, 4, v47
	v_xor_b32_e32 v48, 1, v48
	v_lshl_add_u32 v46, v48, 4, v47
	v_mov_b32_e32 v23, 0
	v_mov_b32_e32 v47, 0
	v_lshl_add_u64 v[22:23], s[20:21], 0, v[22:23]
	v_lshl_add_u64 v[46:47], s[20:21], 0, v[46:47]
	s_add_i32 s15, s15, s33
	s_add_i32 s14, s14, s68
	s_cmpk_lt_i32 s15, 0x240
	v_add_u32_e32 v2, 4, v9
	v_mad_i64_i32 v[2:3], s[16:17], v2, s18, v[0:1]
	global_load_dword v31, v[2:3], off
	v_add_u32_e32 v2, 8, v9
	v_mad_i64_i32 v[2:3], s[16:17], v2, s18, v[0:1]
	global_load_dword v32, v[2:3], off
	v_add_u32_e32 v2, 12, v9
	v_mad_i64_i32 v[2:3], s[16:17], v2, s18, v[0:1]
	global_load_dword v33, v[2:3], off
	v_add_u32_e32 v2, 16, v9
	v_mad_i64_i32 v[2:3], s[16:17], v2, s18, v[0:1]
	global_load_dword v34, v[2:3], off
	v_add_u32_e32 v2, 20, v9
	v_mad_i64_i32 v[2:3], s[16:17], v2, s18, v[0:1]
	global_load_dword v35, v[2:3], off
	v_add_u32_e32 v2, 24, v9
	v_mad_i64_i32 v[2:3], s[16:17], v2, s18, v[0:1]
	global_load_dword v36, v[2:3], off
	v_add_u32_e32 v2, 28, v9
	v_mad_i64_i32 v[2:3], s[16:17], v2, s18, v[0:1]
	global_load_dword v37, v[2:3], off
	v_add_u32_e32 v2, 32, v9
	v_mad_i64_i32 v[2:3], s[16:17], v2, s18, v[0:1]
	global_load_dword v38, v[2:3], off
	v_add_u32_e32 v2, 36, v9
	v_mad_i64_i32 v[2:3], s[16:17], v2, s18, v[0:1]
	global_load_dword v39, v[2:3], off
	v_add_u32_e32 v2, 40, v9
	v_mad_i64_i32 v[2:3], s[16:17], v2, s18, v[0:1]
	global_load_dword v40, v[2:3], off
	v_add_u32_e32 v2, 44, v9
	v_mad_i64_i32 v[2:3], s[16:17], v2, s18, v[0:1]
	global_load_dword v41, v[2:3], off
	v_add_u32_e32 v2, 48, v9
	v_mad_i64_i32 v[2:3], s[16:17], v2, s18, v[0:1]
	global_load_dword v42, v[2:3], off
	v_add_u32_e32 v2, 52, v9
	v_mad_i64_i32 v[2:3], s[16:17], v2, s18, v[0:1]
	global_load_dword v43, v[2:3], off
	v_add_u32_e32 v2, 56, v9
	v_mad_i64_i32 v[2:3], s[16:17], v2, s18, v[0:1]
	global_load_dword v44, v[2:3], off
	v_add_u32_e32 v2, 60, v9
	v_mad_i64_i32 v[0:1], s[16:17], v2, s18, v[0:1]
	global_load_dword v45, v[0:1], off
	v_add_u32_e32 v9, 0x400, v7
	s_waitcnt vmcnt(15)
	ds_write_b32 v8, v30
	s_waitcnt vmcnt(14)
	ds_write_b32 v8, v31 offset:1040
	s_waitcnt vmcnt(13)
	ds_write_b32 v8, v32 offset:2080
	s_waitcnt vmcnt(12)
	ds_write_b32 v8, v33 offset:3120
	s_waitcnt vmcnt(11)
	ds_write_b32 v8, v34 offset:4160
	s_waitcnt vmcnt(10)
	ds_write_b32 v8, v35 offset:5200
	s_waitcnt vmcnt(9)
	ds_write_b32 v8, v36 offset:6240
	s_waitcnt vmcnt(8)
	ds_write_b32 v8, v37 offset:7280
	s_waitcnt vmcnt(7)
	ds_write_b32 v8, v38 offset:8320
	s_waitcnt vmcnt(6)
	ds_write_b32 v8, v39 offset:9360
	s_waitcnt vmcnt(5)
	ds_write_b32 v8, v40 offset:10400
	s_waitcnt vmcnt(4)
	ds_write_b32 v8, v41 offset:11440
	s_waitcnt vmcnt(3)
	ds_write_b32 v8, v42 offset:12480
	s_waitcnt vmcnt(2)
	ds_write_b32 v8, v43 offset:13520
	s_waitcnt vmcnt(1)
	ds_write_b32 v8, v44 offset:14560
	s_waitcnt vmcnt(0)
	ds_write_b32 v8, v45 offset:15600
	s_waitcnt lgkmcnt(0)
	s_barrier
	ds_read2_b32 v[0:1], v7 offset1:65
	ds_read2_b32 v[2:3], v7 offset0:130 offset1:195
	ds_read2_b32 v[10:11], v9 offset0:4 offset1:69
	ds_read2_b32 v[12:13], v9 offset0:134 offset1:199
	v_add_u32_e32 v9, 0x800, v7
	ds_read2_b32 v[14:15], v9 offset0:8 offset1:73
	ds_read2_b32 v[16:17], v9 offset0:138 offset1:203
	v_add_u32_e32 v9, 0xc00, v7
	ds_read2_b32 v[18:19], v9 offset0:12 offset1:77
	ds_read2_b32 v[20:21], v9 offset0:142 offset1:207
	s_waitcnt lgkmcnt(6)
	v_and_b32_sdwa v9, v2, v232 dst_sel:DWORD dst_unused:UNUSED_PAD src0_sel:WORD_1 src1_sel:DWORD
	v_and_b32_sdwa v24, v0, v232 dst_sel:DWORD dst_unused:UNUSED_PAD src0_sel:WORD_1 src1_sel:DWORD
	v_add3_u32 v2, v2, v9, s69
	v_and_b32_sdwa v9, v3, v232 dst_sel:DWORD dst_unused:UNUSED_PAD src0_sel:WORD_1 src1_sel:DWORD
	v_add3_u32 v0, v0, v24, s69
	v_and_b32_sdwa v24, v1, v232 dst_sel:DWORD dst_unused:UNUSED_PAD src0_sel:WORD_1 src1_sel:DWORD
	v_add3_u32 v3, v3, v9, s69
	v_add3_u32 v1, v1, v24, s69
	v_and_b32_e32 v3, 0xffff0000, v3
	v_and_b32_e32 v9, 0xffff0000, v1
	v_or_b32_sdwa v1, v3, v2 dst_sel:DWORD dst_unused:UNUSED_PAD src0_sel:DWORD src1_sel:WORD_1
	s_waitcnt lgkmcnt(5)
	v_and_b32_sdwa v3, v10, v232 dst_sel:DWORD dst_unused:UNUSED_PAD src0_sel:WORD_1 src1_sel:DWORD
	v_or_b32_sdwa v0, v9, v0 dst_sel:DWORD dst_unused:UNUSED_PAD src0_sel:DWORD src1_sel:WORD_1
	v_add3_u32 v9, v10, v3, s69
	s_waitcnt lgkmcnt(4)
	v_and_b32_sdwa v3, v13, v232 dst_sel:DWORD dst_unused:UNUSED_PAD src0_sel:WORD_1 src1_sel:DWORD
	v_and_b32_sdwa v10, v11, v232 dst_sel:DWORD dst_unused:UNUSED_PAD src0_sel:WORD_1 src1_sel:DWORD
	v_and_b32_sdwa v2, v12, v232 dst_sel:DWORD dst_unused:UNUSED_PAD src0_sel:WORD_1 src1_sel:DWORD
	v_add3_u32 v3, v13, v3, s69
	v_add3_u32 v10, v11, v10, s69
	v_add3_u32 v2, v12, v2, s69
	v_and_b32_e32 v3, 0xffff0000, v3
	v_and_b32_e32 v10, 0xffff0000, v10
	v_or_b32_sdwa v3, v3, v2 dst_sel:DWORD dst_unused:UNUSED_PAD src0_sel:DWORD src1_sel:WORD_1
	v_or_b32_sdwa v2, v10, v9 dst_sel:DWORD dst_unused:UNUSED_PAD src0_sel:DWORD src1_sel:WORD_1
	global_store_dwordx4 v[22:23], v[0:3], off
	s_waitcnt lgkmcnt(1)
	v_and_b32_sdwa v10, v19, v232 dst_sel:DWORD dst_unused:UNUSED_PAD src0_sel:WORD_1 src1_sel:DWORD
	v_add3_u32 v10, v19, v10, s69
	v_and_b32_sdwa v1, v14, v232 dst_sel:DWORD dst_unused:UNUSED_PAD src0_sel:WORD_1 src1_sel:DWORD
	v_add3_u32 v2, v14, v1, s69
	v_and_b32_sdwa v1, v17, v232 dst_sel:DWORD dst_unused:UNUSED_PAD src0_sel:WORD_1 src1_sel:DWORD
	v_and_b32_sdwa v3, v15, v232 dst_sel:DWORD dst_unused:UNUSED_PAD src0_sel:WORD_1 src1_sel:DWORD
	v_and_b32_sdwa v0, v16, v232 dst_sel:DWORD dst_unused:UNUSED_PAD src0_sel:WORD_1 src1_sel:DWORD
	v_add3_u32 v1, v17, v1, s69
	v_add3_u32 v3, v15, v3, s69
	v_add3_u32 v0, v16, v0, s69
	v_and_b32_e32 v1, 0xffff0000, v1
	v_and_b32_e32 v3, 0xffff0000, v3
	v_or_b32_sdwa v1, v1, v0 dst_sel:DWORD dst_unused:UNUSED_PAD src0_sel:DWORD src1_sel:WORD_1
	v_or_b32_sdwa v0, v3, v2 dst_sel:DWORD dst_unused:UNUSED_PAD src0_sel:DWORD src1_sel:WORD_1
	v_and_b32_sdwa v3, v18, v232 dst_sel:DWORD dst_unused:UNUSED_PAD src0_sel:WORD_1 src1_sel:DWORD
	v_add3_u32 v9, v18, v3, s69
	s_waitcnt lgkmcnt(0)
	v_and_b32_sdwa v3, v21, v232 dst_sel:DWORD dst_unused:UNUSED_PAD src0_sel:WORD_1 src1_sel:DWORD
	v_and_b32_sdwa v2, v20, v232 dst_sel:DWORD dst_unused:UNUSED_PAD src0_sel:WORD_1 src1_sel:DWORD
	v_add3_u32 v3, v21, v3, s69
	v_add3_u32 v2, v20, v2, s69
	v_and_b32_e32 v3, 0xffff0000, v3
	v_and_b32_e32 v10, 0xffff0000, v10
	v_or_b32_sdwa v3, v3, v2 dst_sel:DWORD dst_unused:UNUSED_PAD src0_sel:DWORD src1_sel:WORD_1
	v_or_b32_sdwa v2, v10, v9 dst_sel:DWORD dst_unused:UNUSED_PAD src0_sel:DWORD src1_sel:WORD_1
	global_store_dwordx4 v[46:47], v[0:3], off
	s_cbranch_scc1 .LBB0_30

.LBB0_48:
	s_ashr_i32 s10, s13, 31
	s_lshr_b32 s10, s10, 28
	s_add_i32 s10, s13, s10
	s_ashr_i32 s15, s10, 4
	s_lshl_b32 s10, s15, 10
	s_lshl_b32 s11, s15, 6
	s_lshl_b32 s15, s15, 5
	v_or_b32_e32 v0, s11, v4
	s_andn2_b32 s15, s15, 63
	v_lshrrev_b32_e32 v0, 1, v0
	v_add_u32_e32 v1, s15, v8
	v_and_or_b32 v0, v0, 48, v1
	s_sub_i32 s10, s14, s10
	v_ashrrev_i32_e32 v1, 31, v0
	v_lshl_add_u64 v[0:1], v[0:1], 2, s[2:3]
	v_add_u32_e32 v10, s10, v5
	v_mad_i64_i32 v[2:3], s[16:17], v10, s74, v[0:1]
	s_barrier
	global_load_dword v30, v[2:3], off
	v_add_u32_e32 v12, 0x400, v7
	v_add_u32_e32 v22, s11, v6
	v_add_u32_e32 v16, 0x800, v7
	v_add_u32_e32 v20, 0xc00, v7
	v_and_b32_e32 v47, 0xffffff00, v22
	v_lshlrev_b32_e32 v47, 11, v47
	v_and_b32_e32 v48, 0xff, v22
	v_lshl_add_u32 v47, v48, 6, v47
	s_lshl_b32 s11, s10, 9
	v_add_u32_e32 v47, s11, v47
	v_lshrrev_b32_e32 v48, 5, v200
	v_lshrrev_b32_e32 v49, 1, v48
	v_lshl_add_u32 v47, v49, 14, v47
	v_and_b32_e32 v48, 1, v48
	v_lshlrev_b32_e32 v48, 1, v48
	v_bfe_u32 v49, v22, 3, 1
	v_mul_u32_u24_e32 v49, 3, v49
	v_xor_b32_e32 v48, v48, v49
	v_lshl_add_u32 v22, v48, 4, v47
	v_xor_b32_e32 v48, 1, v48
	v_lshl_add_u32 v46, v48, 4, v47
	v_mov_b32_e32 v23, 0
	v_mov_b32_e32 v47, 0
	v_lshl_add_u64 v[22:23], s[20:21], 0, v[22:23]
	v_lshl_add_u64 v[46:47], s[20:21], 0, v[46:47]
	s_add_i32 s13, s13, s33
	s_add_i32 s14, s14, s68
	s_cmpk_lt_i32 s13, 0x580
	v_add_u32_e32 v2, 4, v10
	v_mad_i64_i32 v[2:3], s[16:17], v2, s74, v[0:1]
	global_load_dword v31, v[2:3], off
	v_add_u32_e32 v2, 8, v10
	v_mad_i64_i32 v[2:3], s[16:17], v2, s74, v[0:1]
	global_load_dword v32, v[2:3], off
	v_add_u32_e32 v2, 12, v10
	v_mad_i64_i32 v[2:3], s[16:17], v2, s74, v[0:1]
	global_load_dword v33, v[2:3], off
	v_add_u32_e32 v2, 16, v10
	v_mad_i64_i32 v[2:3], s[16:17], v2, s74, v[0:1]
	global_load_dword v34, v[2:3], off
	v_add_u32_e32 v2, 20, v10
	v_mad_i64_i32 v[2:3], s[16:17], v2, s74, v[0:1]
	global_load_dword v35, v[2:3], off
	v_add_u32_e32 v2, 24, v10
	v_mad_i64_i32 v[2:3], s[16:17], v2, s74, v[0:1]
	global_load_dword v36, v[2:3], off
	v_add_u32_e32 v2, 28, v10
	v_mad_i64_i32 v[2:3], s[16:17], v2, s74, v[0:1]
	global_load_dword v37, v[2:3], off
	v_add_u32_e32 v2, 32, v10
	v_mad_i64_i32 v[2:3], s[16:17], v2, s74, v[0:1]
	global_load_dword v38, v[2:3], off
	v_add_u32_e32 v2, 36, v10
	v_mad_i64_i32 v[2:3], s[16:17], v2, s74, v[0:1]
	global_load_dword v39, v[2:3], off
	v_add_u32_e32 v2, 40, v10
	v_mad_i64_i32 v[2:3], s[16:17], v2, s74, v[0:1]
	global_load_dword v40, v[2:3], off
	v_add_u32_e32 v2, 44, v10
	v_mad_i64_i32 v[2:3], s[16:17], v2, s74, v[0:1]
	global_load_dword v41, v[2:3], off
	v_add_u32_e32 v2, 48, v10
	v_mad_i64_i32 v[2:3], s[16:17], v2, s74, v[0:1]
	global_load_dword v42, v[2:3], off
	v_add_u32_e32 v2, 52, v10
	v_mad_i64_i32 v[2:3], s[16:17], v2, s74, v[0:1]
	global_load_dword v43, v[2:3], off
	v_add_u32_e32 v2, 56, v10
	v_mad_i64_i32 v[2:3], s[16:17], v2, s74, v[0:1]
	global_load_dword v44, v[2:3], off
	v_add_u32_e32 v2, 60, v10
	v_mad_i64_i32 v[0:1], s[16:17], v2, s74, v[0:1]
	global_load_dword v45, v[0:1], off
	s_waitcnt vmcnt(15)
	ds_write_b32 v9, v30
	s_waitcnt vmcnt(14)
	ds_write_b32 v9, v31 offset:1040
	s_waitcnt vmcnt(13)
	ds_write_b32 v9, v32 offset:2080
	s_waitcnt vmcnt(12)
	ds_write_b32 v9, v33 offset:3120
	s_waitcnt vmcnt(11)
	ds_write_b32 v9, v34 offset:4160
	s_waitcnt vmcnt(10)
	ds_write_b32 v9, v35 offset:5200
	s_waitcnt vmcnt(9)
	ds_write_b32 v9, v36 offset:6240
	s_waitcnt vmcnt(8)
	ds_write_b32 v9, v37 offset:7280
	s_waitcnt vmcnt(7)
	ds_write_b32 v9, v38 offset:8320
	s_waitcnt vmcnt(6)
	ds_write_b32 v9, v39 offset:9360
	s_waitcnt vmcnt(5)
	ds_write_b32 v9, v40 offset:10400
	s_waitcnt vmcnt(4)
	ds_write_b32 v9, v41 offset:11440
	s_waitcnt vmcnt(3)
	ds_write_b32 v9, v42 offset:12480
	s_waitcnt vmcnt(2)
	ds_write_b32 v9, v43 offset:13520
	s_waitcnt vmcnt(1)
	ds_write_b32 v9, v44 offset:14560
	s_waitcnt vmcnt(0)
	ds_write_b32 v9, v45 offset:15600
	s_waitcnt lgkmcnt(0)
	s_barrier
	ds_read2_b32 v[0:1], v7 offset1:65
	ds_read2_b32 v[2:3], v7 offset0:130 offset1:195
	ds_read2_b32 v[10:11], v12 offset0:4 offset1:69
	ds_read2_b32 v[12:13], v12 offset0:134 offset1:199
	ds_read2_b32 v[14:15], v16 offset0:8 offset1:73
	ds_read2_b32 v[16:17], v16 offset0:138 offset1:203
	ds_read2_b32 v[18:19], v20 offset0:12 offset1:77
	ds_read2_b32 v[20:21], v20 offset0:142 offset1:207
	s_waitcnt lgkmcnt(7)
	v_and_b32_sdwa v25, v0, v232 dst_sel:DWORD dst_unused:UNUSED_PAD src0_sel:WORD_1 src1_sel:DWORD
	s_waitcnt lgkmcnt(6)
	v_and_b32_sdwa v24, v2, v232 dst_sel:DWORD dst_unused:UNUSED_PAD src0_sel:WORD_1 src1_sel:DWORD
	v_add3_u32 v2, v2, v24, s69
	v_and_b32_sdwa v24, v3, v232 dst_sel:DWORD dst_unused:UNUSED_PAD src0_sel:WORD_1 src1_sel:DWORD
	v_add3_u32 v0, v0, v25, s69
	v_and_b32_sdwa v25, v1, v232 dst_sel:DWORD dst_unused:UNUSED_PAD src0_sel:WORD_1 src1_sel:DWORD
	v_add3_u32 v3, v3, v24, s69
	v_add3_u32 v1, v1, v25, s69
	v_and_b32_e32 v3, 0xffff0000, v3
	v_and_b32_e32 v24, 0xffff0000, v1
	v_or_b32_sdwa v1, v3, v2 dst_sel:DWORD dst_unused:UNUSED_PAD src0_sel:DWORD src1_sel:WORD_1
	s_waitcnt lgkmcnt(4)
	v_and_b32_sdwa v2, v12, v232 dst_sel:DWORD dst_unused:UNUSED_PAD src0_sel:WORD_1 src1_sel:DWORD
	v_and_b32_sdwa v3, v10, v232 dst_sel:DWORD dst_unused:UNUSED_PAD src0_sel:WORD_1 src1_sel:DWORD
	v_add3_u32 v10, v10, v3, s69
	v_add3_u32 v2, v12, v2, s69
	v_and_b32_sdwa v3, v13, v232 dst_sel:DWORD dst_unused:UNUSED_PAD src0_sel:WORD_1 src1_sel:DWORD
	v_and_b32_sdwa v12, v11, v232 dst_sel:DWORD dst_unused:UNUSED_PAD src0_sel:WORD_1 src1_sel:DWORD
	v_add3_u32 v3, v13, v3, s69
	v_add3_u32 v11, v11, v12, s69
	v_and_b32_e32 v3, 0xffff0000, v3
	v_and_b32_e32 v11, 0xffff0000, v11
	v_or_b32_sdwa v0, v24, v0 dst_sel:DWORD dst_unused:UNUSED_PAD src0_sel:DWORD src1_sel:WORD_1
	v_or_b32_sdwa v3, v3, v2 dst_sel:DWORD dst_unused:UNUSED_PAD src0_sel:DWORD src1_sel:WORD_1
	v_or_b32_sdwa v2, v11, v10 dst_sel:DWORD dst_unused:UNUSED_PAD src0_sel:DWORD src1_sel:WORD_1
	global_store_dwordx4 v[22:23], v[0:3], off
	s_waitcnt lgkmcnt(1)
	v_and_b32_sdwa v11, v19, v232 dst_sel:DWORD dst_unused:UNUSED_PAD src0_sel:WORD_1 src1_sel:DWORD
	v_add3_u32 v11, v19, v11, s69
	v_and_b32_sdwa v1, v14, v232 dst_sel:DWORD dst_unused:UNUSED_PAD src0_sel:WORD_1 src1_sel:DWORD
	v_add3_u32 v2, v14, v1, s69
	v_and_b32_sdwa v1, v17, v232 dst_sel:DWORD dst_unused:UNUSED_PAD src0_sel:WORD_1 src1_sel:DWORD
	v_and_b32_sdwa v3, v15, v232 dst_sel:DWORD dst_unused:UNUSED_PAD src0_sel:WORD_1 src1_sel:DWORD
	v_and_b32_sdwa v0, v16, v232 dst_sel:DWORD dst_unused:UNUSED_PAD src0_sel:WORD_1 src1_sel:DWORD
	v_add3_u32 v1, v17, v1, s69
	v_add3_u32 v3, v15, v3, s69
	v_add3_u32 v0, v16, v0, s69
	v_and_b32_e32 v1, 0xffff0000, v1
	v_and_b32_e32 v3, 0xffff0000, v3
	v_or_b32_sdwa v1, v1, v0 dst_sel:DWORD dst_unused:UNUSED_PAD src0_sel:DWORD src1_sel:WORD_1
	v_or_b32_sdwa v0, v3, v2 dst_sel:DWORD dst_unused:UNUSED_PAD src0_sel:DWORD src1_sel:WORD_1
	v_and_b32_sdwa v3, v18, v232 dst_sel:DWORD dst_unused:UNUSED_PAD src0_sel:WORD_1 src1_sel:DWORD
	v_add3_u32 v10, v18, v3, s69
	s_waitcnt lgkmcnt(0)
	v_and_b32_sdwa v3, v21, v232 dst_sel:DWORD dst_unused:UNUSED_PAD src0_sel:WORD_1 src1_sel:DWORD
	v_and_b32_sdwa v2, v20, v232 dst_sel:DWORD dst_unused:UNUSED_PAD src0_sel:WORD_1 src1_sel:DWORD
	v_add3_u32 v3, v21, v3, s69
	v_add3_u32 v2, v20, v2, s69
	v_and_b32_e32 v3, 0xffff0000, v3
	v_and_b32_e32 v11, 0xffff0000, v11
	v_or_b32_sdwa v3, v3, v2 dst_sel:DWORD dst_unused:UNUSED_PAD src0_sel:DWORD src1_sel:WORD_1
	v_or_b32_sdwa v2, v11, v10 dst_sel:DWORD dst_unused:UNUSED_PAD src0_sel:DWORD src1_sel:WORD_1
	global_store_dwordx4 v[46:47], v[0:3], off
	s_cbranch_scc1 .LBB0_48

.LBB0_96:
	s_andn2_b64 vcc, exec, s[2:3]
	s_cbranch_vccnz .LBB0_90
	v_readlane_b32 s2, v253, 4
	v_readlane_b32 s3, v253, 5
	s_lshl_b32 s13, s54, 18
	s_add_u32 s2, s2, s13
	s_addc_u32 s3, s3, 0
	s_lshl_b32 s13, s56, 19
	s_add_u32 s4, s50, 0x4490000
	s_addc_u32 s5, s51, 0
	s_add_u32 s4, s4, s13
	s_addc_u32 s5, s5, 0
	v_and_b32_e32 v152, 63, v216
	v_lshrrev_b32_e32 v153, 6, v216
	v_lshrrev_b32_e32 v154, 2, v152
	v_and_b32_e32 v155, 3, v152
	v_readfirstlane_b32 s11, v153
	v_lshrrev_b32_e32 v156, 3, v154
	v_mul_u32_u24_e32 v156, 3, v156
	v_xor_b32_e32 v156, v155, v156
	v_lshlrev_b32_e32 v156, 4, v156
	v_lshl_add_u32 v157, v153, 5, v154
	v_lshl_add_u32 v203, v157, 11, v156
	v_add_u32_e32 v204, 0x8000, v203
	v_lshl_add_u32 v157, v153, 6, v154
	v_lshlrev_b32_e32 v163, 4, v152
	v_lshl_add_u32 v205, v153, 12, v163
	v_add_u32_e32 v206, 0x400, v205
	v_add_u32_e32 v207, 0x800, v205
	v_add_u32_e32 v208, 0xc00, v205
	v_and_b32_e32 v158, 15, v152
	v_lshrrev_b32_e32 v159, 4, v152
	v_lshrrev_b32_e32 v160, 3, v158
	v_mul_u32_u24_e32 v160, 3, v160
	v_xor_b32_e32 v160, v159, v160
	v_lshlrev_b32_e32 v160, 4, v160
	v_lshl_add_u32 v160, v158, 6, v160
	v_lshrrev_b32_e32 v161, 1, v153
	v_and_b32_e32 v162, 1, v153
	v_lshl_add_u32 v209, v161, 12, v160
	v_lshl_add_u32 v210, v162, 13, v160
	s_lshl_b32 s12, s11, 12
	s_lshl_b32 s11, s11, 11
	s_barrier
	s_add_u32 m0, s11, 0x0
	s_nop 0
	global_load_lds_dwordx4 v203, s[2:3]
	s_add_u32 m0, s11, 0x400
	s_nop 0
	global_load_lds_dwordx4 v204, s[2:3]
	s_add_u32 m0, s12, 0x2000
	s_nop 0
	global_load_lds_dwordx4 v205, s[4:5]
	s_add_u32 m0, s12, 0x2400
	s_nop 0
	global_load_lds_dwordx4 v206, s[4:5]
	s_add_u32 m0, s12, 0x2800
	s_nop 0
	global_load_lds_dwordx4 v207, s[4:5]
	s_add_u32 m0, s12, 0x2c00
	s_nop 0
	global_load_lds_dwordx4 v208, s[4:5]
	s_add_u32 s2, s2, 0x40
	s_addc_u32 s3, s3, 0
	s_add_u32 s4, s4, 0x4000
	s_addc_u32 s5, s5, 0
	s_add_u32 m0, s11, 0x6000
	s_nop 0
	global_load_lds_dwordx4 v203, s[2:3]
	s_add_u32 m0, s11, 0x6400
	s_nop 0
	global_load_lds_dwordx4 v204, s[2:3]
	s_add_u32 m0, s12, 0x8000
	s_nop 0
	global_load_lds_dwordx4 v205, s[4:5]
	s_add_u32 m0, s12, 0x8400
	s_nop 0
	global_load_lds_dwordx4 v206, s[4:5]
	s_add_u32 m0, s12, 0x8800
	s_nop 0
	global_load_lds_dwordx4 v207, s[4:5]
	s_add_u32 m0, s12, 0x8c00
	s_nop 0
	global_load_lds_dwordx4 v208, s[4:5]
	s_add_u32 s2, s2, 0x40
	s_addc_u32 s3, s3, 0
	s_add_u32 s4, s4, 0x4000
	s_addc_u32 s5, s5, 0
	v_mov_b32_e32 v172, 0
	v_mov_b32_e32 v173, 0
	v_mov_b32_e32 v174, 0
	v_mov_b32_e32 v175, 0
	v_mov_b32_e32 v168, 0
	v_mov_b32_e32 v169, 0
	v_mov_b32_e32 v170, 0
	v_mov_b32_e32 v171, 0
	v_mov_b32_e32 v116, 0
	v_mov_b32_e32 v117, 0
	v_mov_b32_e32 v118, 0
	v_mov_b32_e32 v119, 0
	v_mov_b32_e32 v112, 0
	v_mov_b32_e32 v113, 0
	v_mov_b32_e32 v114, 0
	v_mov_b32_e32 v115, 0
	v_mov_b32_e32 v108, 0
	v_mov_b32_e32 v109, 0
	v_mov_b32_e32 v110, 0
	v_mov_b32_e32 v111, 0
	v_mov_b32_e32 v104, 0
	v_mov_b32_e32 v105, 0
	v_mov_b32_e32 v106, 0
	v_mov_b32_e32 v107, 0
	v_mov_b32_e32 v100, 0
	v_mov_b32_e32 v101, 0
	v_mov_b32_e32 v102, 0
	v_mov_b32_e32 v103, 0
	v_mov_b32_e32 v96, 0
	v_mov_b32_e32 v97, 0
	v_mov_b32_e32 v98, 0
	v_mov_b32_e32 v99, 0
	v_mov_b32_e32 v92, 0
	v_mov_b32_e32 v93, 0
	v_mov_b32_e32 v94, 0
	v_mov_b32_e32 v95, 0
	v_mov_b32_e32 v88, 0
	v_mov_b32_e32 v89, 0
	v_mov_b32_e32 v90, 0
	v_mov_b32_e32 v91, 0
	v_mov_b32_e32 v84, 0
	v_mov_b32_e32 v85, 0
	v_mov_b32_e32 v86, 0
	v_mov_b32_e32 v87, 0
	v_mov_b32_e32 v80, 0
	v_mov_b32_e32 v81, 0
	v_mov_b32_e32 v82, 0
	v_mov_b32_e32 v83, 0
	v_mov_b32_e32 v76, 0
	v_mov_b32_e32 v77, 0
	v_mov_b32_e32 v78, 0
	v_mov_b32_e32 v79, 0
	v_mov_b32_e32 v72, 0
	v_mov_b32_e32 v73, 0
	v_mov_b32_e32 v74, 0
	v_mov_b32_e32 v75, 0
	v_mov_b32_e32 v68, 0
	v_mov_b32_e32 v69, 0
	v_mov_b32_e32 v70, 0
	v_mov_b32_e32 v71, 0
	v_mov_b32_e32 v64, 0
	v_mov_b32_e32 v65, 0
	v_mov_b32_e32 v66, 0
	v_mov_b32_e32 v67, 0
	v_mov_b32_e32 v60, 0
	v_mov_b32_e32 v61, 0
	v_mov_b32_e32 v62, 0
	v_mov_b32_e32 v63, 0
	v_mov_b32_e32 v56, 0
	v_mov_b32_e32 v57, 0
	v_mov_b32_e32 v58, 0
	v_mov_b32_e32 v59, 0
	v_mov_b32_e32 v52, 0
	v_mov_b32_e32 v53, 0
	v_mov_b32_e32 v54, 0
	v_mov_b32_e32 v55, 0
	v_mov_b32_e32 v48, 0
	v_mov_b32_e32 v49, 0
	v_mov_b32_e32 v50, 0
	v_mov_b32_e32 v51, 0
	v_mov_b32_e32 v44, 0
	v_mov_b32_e32 v45, 0
	v_mov_b32_e32 v46, 0
	v_mov_b32_e32 v47, 0
	v_mov_b32_e32 v40, 0
	v_mov_b32_e32 v41, 0
	v_mov_b32_e32 v42, 0
	v_mov_b32_e32 v43, 0
	v_mov_b32_e32 v36, 0
	v_mov_b32_e32 v37, 0
	v_mov_b32_e32 v38, 0
	v_mov_b32_e32 v39, 0
	v_mov_b32_e32 v32, 0
	v_mov_b32_e32 v33, 0
	v_mov_b32_e32 v34, 0
	v_mov_b32_e32 v35, 0
	v_mov_b32_e32 v28, 0
	v_mov_b32_e32 v29, 0
	v_mov_b32_e32 v30, 0
	v_mov_b32_e32 v31, 0
	v_mov_b32_e32 v24, 0
	v_mov_b32_e32 v25, 0
	v_mov_b32_e32 v26, 0
	v_mov_b32_e32 v27, 0
	v_mov_b32_e32 v20, 0
	v_mov_b32_e32 v21, 0
	v_mov_b32_e32 v22, 0
	v_mov_b32_e32 v23, 0
	v_mov_b32_e32 v16, 0
	v_mov_b32_e32 v17, 0
	v_mov_b32_e32 v18, 0
	v_mov_b32_e32 v19, 0
	v_mov_b32_e32 v12, 0
	v_mov_b32_e32 v13, 0
	v_mov_b32_e32 v14, 0
	v_mov_b32_e32 v15, 0
	v_mov_b32_e32 v8, 0
	v_mov_b32_e32 v9, 0
	v_mov_b32_e32 v10, 0
	v_mov_b32_e32 v11, 0
	v_mov_b32_e32 v4, 0
	v_mov_b32_e32 v5, 0
	v_mov_b32_e32 v6, 0
	v_mov_b32_e32 v7, 0
	v_mov_b32_e32 v0, 0
	v_mov_b32_e32 v1, 0
	v_mov_b32_e32 v2, 0
	v_mov_b32_e32 v3, 0
	s_waitcnt vmcnt(6)
	s_barrier
	ds_read_b128 v[120:123], v209 offset:0
	ds_read_b128 v[124:127], v209 offset:1024
	ds_read_b128 v[128:131], v209 offset:2048
	ds_read_b128 v[132:135], v209 offset:3072
	ds_read_b128 v[152:155], v210 offset:8192
	ds_read_b128 v[156:159], v210 offset:9216
	ds_read_b128 v[160:163], v210 offset:10240
	ds_read_b128 v[164:167], v210 offset:11264
	ds_read_b128 v[176:179], v210 offset:12288
	ds_read_b128 v[180:183], v210 offset:13312
	s_add_u32 m0, s11, 0xc000
	s_nop 0
	global_load_lds_dwordx4 v203, s[2:3]
	s_add_u32 m0, s11, 0xc400
	s_nop 0
	global_load_lds_dwordx4 v204, s[2:3]
	s_add_u32 m0, s12, 0xe000
	s_nop 0
	global_load_lds_dwordx4 v205, s[4:5]
	s_add_u32 m0, s12, 0xe400
	s_nop 0
	global_load_lds_dwordx4 v206, s[4:5]
	s_add_u32 m0, s12, 0xe800
	s_nop 0
	global_load_lds_dwordx4 v207, s[4:5]
	s_add_u32 m0, s12, 0xec00
	s_nop 0
	global_load_lds_dwordx4 v208, s[4:5]
	s_add_u32 s2, s2, 0x40
	s_addc_u32 s3, s3, 0
	s_add_u32 s4, s4, 0x4000
	s_addc_u32 s5, s5, 0
	ds_read_b128 v[184:187], v210 offset:14336
	ds_read_b128 v[188:191], v210 offset:15360
	s_waitcnt lgkmcnt(7)
	v_mfma_f32_16x16x32_bf16 v[172:175], v[152:155], v[120:123], v[172:175]
	v_mfma_f32_16x16x32_bf16 v[92:95], v[152:155], v[124:127], v[92:95]
	v_mfma_f32_16x16x32_bf16 v[60:63], v[152:155], v[128:131], v[60:63]
	v_mfma_f32_16x16x32_bf16 v[28:31], v[152:155], v[132:135], v[28:31]
	s_waitcnt lgkmcnt(6)
	v_mfma_f32_16x16x32_bf16 v[168:171], v[156:159], v[120:123], v[168:171]
	v_mfma_f32_16x16x32_bf16 v[88:91], v[156:159], v[124:127], v[88:91]
	v_mfma_f32_16x16x32_bf16 v[56:59], v[156:159], v[128:131], v[56:59]
	v_mfma_f32_16x16x32_bf16 v[24:27], v[156:159], v[132:135], v[24:27]
	s_waitcnt lgkmcnt(5)
	v_mfma_f32_16x16x32_bf16 v[116:119], v[160:163], v[120:123], v[116:119]
	v_mfma_f32_16x16x32_bf16 v[84:87], v[160:163], v[124:127], v[84:87]
	v_mfma_f32_16x16x32_bf16 v[52:55], v[160:163], v[128:131], v[52:55]
	v_mfma_f32_16x16x32_bf16 v[20:23], v[160:163], v[132:135], v[20:23]
	s_waitcnt lgkmcnt(4)
	v_mfma_f32_16x16x32_bf16 v[112:115], v[164:167], v[120:123], v[112:115]
	v_mfma_f32_16x16x32_bf16 v[80:83], v[164:167], v[124:127], v[80:83]
	v_mfma_f32_16x16x32_bf16 v[48:51], v[164:167], v[128:131], v[48:51]
	v_mfma_f32_16x16x32_bf16 v[16:19], v[164:167], v[132:135], v[16:19]
	s_waitcnt lgkmcnt(3)
	v_mfma_f32_16x16x32_bf16 v[108:111], v[176:179], v[120:123], v[108:111]
	v_mfma_f32_16x16x32_bf16 v[76:79], v[176:179], v[124:127], v[76:79]
	v_mfma_f32_16x16x32_bf16 v[44:47], v[176:179], v[128:131], v[44:47]
	v_mfma_f32_16x16x32_bf16 v[12:15], v[176:179], v[132:135], v[12:15]
	s_waitcnt lgkmcnt(2)
	v_mfma_f32_16x16x32_bf16 v[104:107], v[180:183], v[120:123], v[104:107]
	v_mfma_f32_16x16x32_bf16 v[72:75], v[180:183], v[124:127], v[72:75]
	v_mfma_f32_16x16x32_bf16 v[40:43], v[180:183], v[128:131], v[40:43]
	v_mfma_f32_16x16x32_bf16 v[8:11], v[180:183], v[132:135], v[8:11]
	s_waitcnt lgkmcnt(0)
	s_mov_b32 s13, 5
.Lg1_loop:
	s_waitcnt vmcnt(6)
	s_barrier
	ds_read_b128 v[136:139], v209 offset:24576
	ds_read_b128 v[140:143], v209 offset:25600
	ds_read_b128 v[144:147], v209 offset:26624
	ds_read_b128 v[148:151], v209 offset:27648
	ds_read_b128 v[152:155], v210 offset:32768
	ds_read_b128 v[156:159], v210 offset:33792
	ds_read_b128 v[160:163], v210 offset:34816
	ds_read_b128 v[164:167], v210 offset:35840
	ds_read_b128 v[176:179], v210 offset:36864
	ds_read_b128 v[180:183], v210 offset:37888
	v_mfma_f32_16x16x32_bf16 v[100:103], v[184:187], v[120:123], v[100:103]
	s_add_u32 m0, s11, 0x0
	v_mfma_f32_16x16x32_bf16 v[68:71], v[184:187], v[124:127], v[68:71]
	global_load_lds_dwordx4 v203, s[2:3]
	s_add_u32 m0, s11, 0x400
	v_mfma_f32_16x16x32_bf16 v[36:39], v[184:187], v[128:131], v[36:39]
	global_load_lds_dwordx4 v204, s[2:3]
	s_add_u32 m0, s12, 0x2000
	v_mfma_f32_16x16x32_bf16 v[4:7], v[184:187], v[132:135], v[4:7]
	global_load_lds_dwordx4 v205, s[4:5]
	s_add_u32 m0, s12, 0x2400
	v_mfma_f32_16x16x32_bf16 v[96:99], v[188:191], v[120:123], v[96:99]
	global_load_lds_dwordx4 v206, s[4:5]
	s_add_u32 m0, s12, 0x2800
	v_mfma_f32_16x16x32_bf16 v[64:67], v[188:191], v[124:127], v[64:67]
	global_load_lds_dwordx4 v207, s[4:5]
	s_add_u32 m0, s12, 0x2c00
	v_mfma_f32_16x16x32_bf16 v[32:35], v[188:191], v[128:131], v[32:35]
	global_load_lds_dwordx4 v208, s[4:5]
	v_mfma_f32_16x16x32_bf16 v[0:3], v[188:191], v[132:135], v[0:3]
	s_add_u32 s2, s2, 0x40
	s_addc_u32 s3, s3, 0
	s_add_u32 s4, s4, 0x4000
	s_addc_u32 s5, s5, 0
	ds_read_b128 v[184:187], v210 offset:38912
	ds_read_b128 v[188:191], v210 offset:39936
	s_waitcnt lgkmcnt(7)
	v_mfma_f32_16x16x32_bf16 v[172:175], v[152:155], v[136:139], v[172:175]
	v_mfma_f32_16x16x32_bf16 v[92:95], v[152:155], v[140:143], v[92:95]
	v_mfma_f32_16x16x32_bf16 v[60:63], v[152:155], v[144:147], v[60:63]
	v_mfma_f32_16x16x32_bf16 v[28:31], v[152:155], v[148:151], v[28:31]
	s_waitcnt lgkmcnt(6)
	v_mfma_f32_16x16x32_bf16 v[168:171], v[156:159], v[136:139], v[168:171]
	v_mfma_f32_16x16x32_bf16 v[88:91], v[156:159], v[140:143], v[88:91]
	v_mfma_f32_16x16x32_bf16 v[56:59], v[156:159], v[144:147], v[56:59]
	v_mfma_f32_16x16x32_bf16 v[24:27], v[156:159], v[148:151], v[24:27]
	s_waitcnt lgkmcnt(5)
	v_mfma_f32_16x16x32_bf16 v[116:119], v[160:163], v[136:139], v[116:119]
	v_mfma_f32_16x16x32_bf16 v[84:87], v[160:163], v[140:143], v[84:87]
	v_mfma_f32_16x16x32_bf16 v[52:55], v[160:163], v[144:147], v[52:55]
	v_mfma_f32_16x16x32_bf16 v[20:23], v[160:163], v[148:151], v[20:23]
	s_waitcnt lgkmcnt(4)
	v_mfma_f32_16x16x32_bf16 v[112:115], v[164:167], v[136:139], v[112:115]
	v_mfma_f32_16x16x32_bf16 v[80:83], v[164:167], v[140:143], v[80:83]
	v_mfma_f32_16x16x32_bf16 v[48:51], v[164:167], v[144:147], v[48:51]
	v_mfma_f32_16x16x32_bf16 v[16:19], v[164:167], v[148:151], v[16:19]
	s_waitcnt lgkmcnt(3)
	v_mfma_f32_16x16x32_bf16 v[108:111], v[176:179], v[136:139], v[108:111]
	v_mfma_f32_16x16x32_bf16 v[76:79], v[176:179], v[140:143], v[76:79]
	v_mfma_f32_16x16x32_bf16 v[44:47], v[176:179], v[144:147], v[44:47]
	v_mfma_f32_16x16x32_bf16 v[12:15], v[176:179], v[148:151], v[12:15]
	s_waitcnt lgkmcnt(2)
	v_mfma_f32_16x16x32_bf16 v[104:107], v[180:183], v[136:139], v[104:107]
	v_mfma_f32_16x16x32_bf16 v[72:75], v[180:183], v[140:143], v[72:75]
	v_mfma_f32_16x16x32_bf16 v[40:43], v[180:183], v[144:147], v[40:43]
	v_mfma_f32_16x16x32_bf16 v[8:11], v[180:183], v[148:151], v[8:11]
	s_waitcnt lgkmcnt(0)
	s_waitcnt vmcnt(6)
	s_barrier
	ds_read_b128 v[120:123], v209 offset:49152
	ds_read_b128 v[124:127], v209 offset:50176
	ds_read_b128 v[128:131], v209 offset:51200
	ds_read_b128 v[132:135], v209 offset:52224
	ds_read_b128 v[152:155], v210 offset:57344
	ds_read_b128 v[156:159], v210 offset:58368
	ds_read_b128 v[160:163], v210 offset:59392
	ds_read_b128 v[164:167], v210 offset:60416
	ds_read_b128 v[176:179], v210 offset:61440
	ds_read_b128 v[180:183], v210 offset:62464
	v_mfma_f32_16x16x32_bf16 v[100:103], v[184:187], v[136:139], v[100:103]
	s_add_u32 m0, s11, 0x6000
	v_mfma_f32_16x16x32_bf16 v[68:71], v[184:187], v[140:143], v[68:71]
	global_load_lds_dwordx4 v203, s[2:3]
	s_add_u32 m0, s11, 0x6400
	v_mfma_f32_16x16x32_bf16 v[36:39], v[184:187], v[144:147], v[36:39]
	global_load_lds_dwordx4 v204, s[2:3]
	s_add_u32 m0, s12, 0x8000
	v_mfma_f32_16x16x32_bf16 v[4:7], v[184:187], v[148:151], v[4:7]
	global_load_lds_dwordx4 v205, s[4:5]
	s_add_u32 m0, s12, 0x8400
	v_mfma_f32_16x16x32_bf16 v[96:99], v[188:191], v[136:139], v[96:99]
	global_load_lds_dwordx4 v206, s[4:5]
	s_add_u32 m0, s12, 0x8800
	v_mfma_f32_16x16x32_bf16 v[64:67], v[188:191], v[140:143], v[64:67]
	global_load_lds_dwordx4 v207, s[4:5]
	s_add_u32 m0, s12, 0x8c00
	v_mfma_f32_16x16x32_bf16 v[32:35], v[188:191], v[144:147], v[32:35]
	global_load_lds_dwordx4 v208, s[4:5]
	v_mfma_f32_16x16x32_bf16 v[0:3], v[188:191], v[148:151], v[0:3]
	s_add_u32 s2, s2, 0x40
	s_addc_u32 s3, s3, 0
	s_add_u32 s4, s4, 0x4000
	s_addc_u32 s5, s5, 0
	ds_read_b128 v[184:187], v210 offset:63488
	ds_read_b128 v[188:191], v210 offset:64512
	s_waitcnt lgkmcnt(7)
	v_mfma_f32_16x16x32_bf16 v[172:175], v[152:155], v[120:123], v[172:175]
	v_mfma_f32_16x16x32_bf16 v[92:95], v[152:155], v[124:127], v[92:95]
	v_mfma_f32_16x16x32_bf16 v[60:63], v[152:155], v[128:131], v[60:63]
	v_mfma_f32_16x16x32_bf16 v[28:31], v[152:155], v[132:135], v[28:31]
	s_waitcnt lgkmcnt(6)
	v_mfma_f32_16x16x32_bf16 v[168:171], v[156:159], v[120:123], v[168:171]
	v_mfma_f32_16x16x32_bf16 v[88:91], v[156:159], v[124:127], v[88:91]
	v_mfma_f32_16x16x32_bf16 v[56:59], v[156:159], v[128:131], v[56:59]
	v_mfma_f32_16x16x32_bf16 v[24:27], v[156:159], v[132:135], v[24:27]
	s_waitcnt lgkmcnt(5)
	v_mfma_f32_16x16x32_bf16 v[116:119], v[160:163], v[120:123], v[116:119]
	v_mfma_f32_16x16x32_bf16 v[84:87], v[160:163], v[124:127], v[84:87]
	v_mfma_f32_16x16x32_bf16 v[52:55], v[160:163], v[128:131], v[52:55]
	v_mfma_f32_16x16x32_bf16 v[20:23], v[160:163], v[132:135], v[20:23]
	s_waitcnt lgkmcnt(4)
	v_mfma_f32_16x16x32_bf16 v[112:115], v[164:167], v[120:123], v[112:115]
	v_mfma_f32_16x16x32_bf16 v[80:83], v[164:167], v[124:127], v[80:83]
	v_mfma_f32_16x16x32_bf16 v[48:51], v[164:167], v[128:131], v[48:51]
	v_mfma_f32_16x16x32_bf16 v[16:19], v[164:167], v[132:135], v[16:19]
	s_waitcnt lgkmcnt(3)
	v_mfma_f32_16x16x32_bf16 v[108:111], v[176:179], v[120:123], v[108:111]
	v_mfma_f32_16x16x32_bf16 v[76:79], v[176:179], v[124:127], v[76:79]
	v_mfma_f32_16x16x32_bf16 v[44:47], v[176:179], v[128:131], v[44:47]
	v_mfma_f32_16x16x32_bf16 v[12:15], v[176:179], v[132:135], v[12:15]
	s_waitcnt lgkmcnt(2)
	v_mfma_f32_16x16x32_bf16 v[104:107], v[180:183], v[120:123], v[104:107]
	v_mfma_f32_16x16x32_bf16 v[72:75], v[180:183], v[124:127], v[72:75]
	v_mfma_f32_16x16x32_bf16 v[40:43], v[180:183], v[128:131], v[40:43]
	v_mfma_f32_16x16x32_bf16 v[8:11], v[180:183], v[132:135], v[8:11]
	s_waitcnt lgkmcnt(0)
	s_waitcnt vmcnt(6)
	s_barrier
	ds_read_b128 v[136:139], v209 offset:0
	ds_read_b128 v[140:143], v209 offset:1024
	ds_read_b128 v[144:147], v209 offset:2048
	ds_read_b128 v[148:151], v209 offset:3072
	ds_read_b128 v[152:155], v210 offset:8192
	ds_read_b128 v[156:159], v210 offset:9216
	ds_read_b128 v[160:163], v210 offset:10240
	ds_read_b128 v[164:167], v210 offset:11264
	ds_read_b128 v[176:179], v210 offset:12288
	ds_read_b128 v[180:183], v210 offset:13312
	v_mfma_f32_16x16x32_bf16 v[100:103], v[184:187], v[120:123], v[100:103]
	s_add_u32 m0, s11, 0xc000
	v_mfma_f32_16x16x32_bf16 v[68:71], v[184:187], v[124:127], v[68:71]
	global_load_lds_dwordx4 v203, s[2:3]
	s_add_u32 m0, s11, 0xc400
	v_mfma_f32_16x16x32_bf16 v[36:39], v[184:187], v[128:131], v[36:39]
	global_load_lds_dwordx4 v204, s[2:3]
	s_add_u32 m0, s12, 0xe000
	v_mfma_f32_16x16x32_bf16 v[4:7], v[184:187], v[132:135], v[4:7]
	global_load_lds_dwordx4 v205, s[4:5]
	s_add_u32 m0, s12, 0xe400
	v_mfma_f32_16x16x32_bf16 v[96:99], v[188:191], v[120:123], v[96:99]
	global_load_lds_dwordx4 v206, s[4:5]
	s_add_u32 m0, s12, 0xe800
	v_mfma_f32_16x16x32_bf16 v[64:67], v[188:191], v[124:127], v[64:67]
	global_load_lds_dwordx4 v207, s[4:5]
	s_add_u32 m0, s12, 0xec00
	v_mfma_f32_16x16x32_bf16 v[32:35], v[188:191], v[128:131], v[32:35]
	global_load_lds_dwordx4 v208, s[4:5]
	v_mfma_f32_16x16x32_bf16 v[0:3], v[188:191], v[132:135], v[0:3]
	s_add_u32 s2, s2, 0x40
	s_addc_u32 s3, s3, 0
	s_add_u32 s4, s4, 0x4000
	s_addc_u32 s5, s5, 0
	ds_read_b128 v[184:187], v210 offset:14336
	ds_read_b128 v[188:191], v210 offset:15360
	s_waitcnt lgkmcnt(7)
	v_mfma_f32_16x16x32_bf16 v[172:175], v[152:155], v[136:139], v[172:175]
	v_mfma_f32_16x16x32_bf16 v[92:95], v[152:155], v[140:143], v[92:95]
	v_mfma_f32_16x16x32_bf16 v[60:63], v[152:155], v[144:147], v[60:63]
	v_mfma_f32_16x16x32_bf16 v[28:31], v[152:155], v[148:151], v[28:31]
	s_waitcnt lgkmcnt(6)
	v_mfma_f32_16x16x32_bf16 v[168:171], v[156:159], v[136:139], v[168:171]
	v_mfma_f32_16x16x32_bf16 v[88:91], v[156:159], v[140:143], v[88:91]
	v_mfma_f32_16x16x32_bf16 v[56:59], v[156:159], v[144:147], v[56:59]
	v_mfma_f32_16x16x32_bf16 v[24:27], v[156:159], v[148:151], v[24:27]
	s_waitcnt lgkmcnt(5)
	v_mfma_f32_16x16x32_bf16 v[116:119], v[160:163], v[136:139], v[116:119]
	v_mfma_f32_16x16x32_bf16 v[84:87], v[160:163], v[140:143], v[84:87]
	v_mfma_f32_16x16x32_bf16 v[52:55], v[160:163], v[144:147], v[52:55]
	v_mfma_f32_16x16x32_bf16 v[20:23], v[160:163], v[148:151], v[20:23]
	s_waitcnt lgkmcnt(4)
	v_mfma_f32_16x16x32_bf16 v[112:115], v[164:167], v[136:139], v[112:115]
	v_mfma_f32_16x16x32_bf16 v[80:83], v[164:167], v[140:143], v[80:83]
	v_mfma_f32_16x16x32_bf16 v[48:51], v[164:167], v[144:147], v[48:51]
	v_mfma_f32_16x16x32_bf16 v[16:19], v[164:167], v[148:151], v[16:19]
	s_waitcnt lgkmcnt(3)
	v_mfma_f32_16x16x32_bf16 v[108:111], v[176:179], v[136:139], v[108:111]
	v_mfma_f32_16x16x32_bf16 v[76:79], v[176:179], v[140:143], v[76:79]
	v_mfma_f32_16x16x32_bf16 v[44:47], v[176:179], v[144:147], v[44:47]
	v_mfma_f32_16x16x32_bf16 v[12:15], v[176:179], v[148:151], v[12:15]
	s_waitcnt lgkmcnt(2)
	v_mfma_f32_16x16x32_bf16 v[104:107], v[180:183], v[136:139], v[104:107]
	v_mfma_f32_16x16x32_bf16 v[72:75], v[180:183], v[140:143], v[72:75]
	v_mfma_f32_16x16x32_bf16 v[40:43], v[180:183], v[144:147], v[40:43]
	v_mfma_f32_16x16x32_bf16 v[8:11], v[180:183], v[148:151], v[8:11]
	s_waitcnt lgkmcnt(0)
	s_waitcnt vmcnt(6)
	s_barrier
	ds_read_b128 v[120:123], v209 offset:24576
	ds_read_b128 v[124:127], v209 offset:25600
	ds_read_b128 v[128:131], v209 offset:26624
	ds_read_b128 v[132:135], v209 offset:27648
	ds_read_b128 v[152:155], v210 offset:32768
	ds_read_b128 v[156:159], v210 offset:33792
	ds_read_b128 v[160:163], v210 offset:34816
	ds_read_b128 v[164:167], v210 offset:35840
	ds_read_b128 v[176:179], v210 offset:36864
	ds_read_b128 v[180:183], v210 offset:37888
	v_mfma_f32_16x16x32_bf16 v[100:103], v[184:187], v[136:139], v[100:103]
	s_add_u32 m0, s11, 0x0
	v_mfma_f32_16x16x32_bf16 v[68:71], v[184:187], v[140:143], v[68:71]
	global_load_lds_dwordx4 v203, s[2:3]
	s_add_u32 m0, s11, 0x400
	v_mfma_f32_16x16x32_bf16 v[36:39], v[184:187], v[144:147], v[36:39]
	global_load_lds_dwordx4 v204, s[2:3]
	s_add_u32 m0, s12, 0x2000
	v_mfma_f32_16x16x32_bf16 v[4:7], v[184:187], v[148:151], v[4:7]
	global_load_lds_dwordx4 v205, s[4:5]
	s_add_u32 m0, s12, 0x2400
	v_mfma_f32_16x16x32_bf16 v[96:99], v[188:191], v[136:139], v[96:99]
	global_load_lds_dwordx4 v206, s[4:5]
	s_add_u32 m0, s12, 0x2800
	v_mfma_f32_16x16x32_bf16 v[64:67], v[188:191], v[140:143], v[64:67]
	global_load_lds_dwordx4 v207, s[4:5]
	s_add_u32 m0, s12, 0x2c00
	v_mfma_f32_16x16x32_bf16 v[32:35], v[188:191], v[144:147], v[32:35]
	global_load_lds_dwordx4 v208, s[4:5]
	v_mfma_f32_16x16x32_bf16 v[0:3], v[188:191], v[148:151], v[0:3]
	s_add_u32 s2, s2, 0x40
	s_addc_u32 s3, s3, 0
	s_add_u32 s4, s4, 0x4000
	s_addc_u32 s5, s5, 0
	ds_read_b128 v[184:187], v210 offset:38912
	ds_read_b128 v[188:191], v210 offset:39936
	s_waitcnt lgkmcnt(7)
	v_mfma_f32_16x16x32_bf16 v[172:175], v[152:155], v[120:123], v[172:175]
	v_mfma_f32_16x16x32_bf16 v[92:95], v[152:155], v[124:127], v[92:95]
	v_mfma_f32_16x16x32_bf16 v[60:63], v[152:155], v[128:131], v[60:63]
	v_mfma_f32_16x16x32_bf16 v[28:31], v[152:155], v[132:135], v[28:31]
	s_waitcnt lgkmcnt(6)
	v_mfma_f32_16x16x32_bf16 v[168:171], v[156:159], v[120:123], v[168:171]
	v_mfma_f32_16x16x32_bf16 v[88:91], v[156:159], v[124:127], v[88:91]
	v_mfma_f32_16x16x32_bf16 v[56:59], v[156:159], v[128:131], v[56:59]
	v_mfma_f32_16x16x32_bf16 v[24:27], v[156:159], v[132:135], v[24:27]
	s_waitcnt lgkmcnt(5)
	v_mfma_f32_16x16x32_bf16 v[116:119], v[160:163], v[120:123], v[116:119]
	v_mfma_f32_16x16x32_bf16 v[84:87], v[160:163], v[124:127], v[84:87]
	v_mfma_f32_16x16x32_bf16 v[52:55], v[160:163], v[128:131], v[52:55]
	v_mfma_f32_16x16x32_bf16 v[20:23], v[160:163], v[132:135], v[20:23]
	s_waitcnt lgkmcnt(4)
	v_mfma_f32_16x16x32_bf16 v[112:115], v[164:167], v[120:123], v[112:115]
	v_mfma_f32_16x16x32_bf16 v[80:83], v[164:167], v[124:127], v[80:83]
	v_mfma_f32_16x16x32_bf16 v[48:51], v[164:167], v[128:131], v[48:51]
	v_mfma_f32_16x16x32_bf16 v[16:19], v[164:167], v[132:135], v[16:19]
	s_waitcnt lgkmcnt(3)
	v_mfma_f32_16x16x32_bf16 v[108:111], v[176:179], v[120:123], v[108:111]
	v_mfma_f32_16x16x32_bf16 v[76:79], v[176:179], v[124:127], v[76:79]
	v_mfma_f32_16x16x32_bf16 v[44:47], v[176:179], v[128:131], v[44:47]
	v_mfma_f32_16x16x32_bf16 v[12:15], v[176:179], v[132:135], v[12:15]
	s_waitcnt lgkmcnt(2)
	v_mfma_f32_16x16x32_bf16 v[104:107], v[180:183], v[120:123], v[104:107]
	v_mfma_f32_16x16x32_bf16 v[72:75], v[180:183], v[124:127], v[72:75]
	v_mfma_f32_16x16x32_bf16 v[40:43], v[180:183], v[128:131], v[40:43]
	v_mfma_f32_16x16x32_bf16 v[8:11], v[180:183], v[132:135], v[8:11]
	s_waitcnt lgkmcnt(0)
	s_waitcnt vmcnt(6)
	s_barrier
	ds_read_b128 v[136:139], v209 offset:49152
	ds_read_b128 v[140:143], v209 offset:50176
	ds_read_b128 v[144:147], v209 offset:51200
	ds_read_b128 v[148:151], v209 offset:52224
	ds_read_b128 v[152:155], v210 offset:57344
	ds_read_b128 v[156:159], v210 offset:58368
	ds_read_b128 v[160:163], v210 offset:59392
	ds_read_b128 v[164:167], v210 offset:60416
	ds_read_b128 v[176:179], v210 offset:61440
	ds_read_b128 v[180:183], v210 offset:62464
	v_mfma_f32_16x16x32_bf16 v[100:103], v[184:187], v[120:123], v[100:103]
	s_add_u32 m0, s11, 0x6000
	v_mfma_f32_16x16x32_bf16 v[68:71], v[184:187], v[124:127], v[68:71]
	global_load_lds_dwordx4 v203, s[2:3]
	s_add_u32 m0, s11, 0x6400
	v_mfma_f32_16x16x32_bf16 v[36:39], v[184:187], v[128:131], v[36:39]
	global_load_lds_dwordx4 v204, s[2:3]
	s_add_u32 m0, s12, 0x8000
	v_mfma_f32_16x16x32_bf16 v[4:7], v[184:187], v[132:135], v[4:7]
	global_load_lds_dwordx4 v205, s[4:5]
	s_add_u32 m0, s12, 0x8400
	v_mfma_f32_16x16x32_bf16 v[96:99], v[188:191], v[120:123], v[96:99]
	global_load_lds_dwordx4 v206, s[4:5]
	s_add_u32 m0, s12, 0x8800
	v_mfma_f32_16x16x32_bf16 v[64:67], v[188:191], v[124:127], v[64:67]
	global_load_lds_dwordx4 v207, s[4:5]
	s_add_u32 m0, s12, 0x8c00
	v_mfma_f32_16x16x32_bf16 v[32:35], v[188:191], v[128:131], v[32:35]
	global_load_lds_dwordx4 v208, s[4:5]
	v_mfma_f32_16x16x32_bf16 v[0:3], v[188:191], v[132:135], v[0:3]
	s_add_u32 s2, s2, 0x40
	s_addc_u32 s3, s3, 0
	s_add_u32 s4, s4, 0x4000
	s_addc_u32 s5, s5, 0
	ds_read_b128 v[184:187], v210 offset:63488
	ds_read_b128 v[188:191], v210 offset:64512
	s_waitcnt lgkmcnt(7)
	v_mfma_f32_16x16x32_bf16 v[172:175], v[152:155], v[136:139], v[172:175]
	v_mfma_f32_16x16x32_bf16 v[92:95], v[152:155], v[140:143], v[92:95]
	v_mfma_f32_16x16x32_bf16 v[60:63], v[152:155], v[144:147], v[60:63]
	v_mfma_f32_16x16x32_bf16 v[28:31], v[152:155], v[148:151], v[28:31]
	s_waitcnt lgkmcnt(6)
	v_mfma_f32_16x16x32_bf16 v[168:171], v[156:159], v[136:139], v[168:171]
	v_mfma_f32_16x16x32_bf16 v[88:91], v[156:159], v[140:143], v[88:91]
	v_mfma_f32_16x16x32_bf16 v[56:59], v[156:159], v[144:147], v[56:59]
	v_mfma_f32_16x16x32_bf16 v[24:27], v[156:159], v[148:151], v[24:27]
	s_waitcnt lgkmcnt(5)
	v_mfma_f32_16x16x32_bf16 v[116:119], v[160:163], v[136:139], v[116:119]
	v_mfma_f32_16x16x32_bf16 v[84:87], v[160:163], v[140:143], v[84:87]
	v_mfma_f32_16x16x32_bf16 v[52:55], v[160:163], v[144:147], v[52:55]
	v_mfma_f32_16x16x32_bf16 v[20:23], v[160:163], v[148:151], v[20:23]
	s_waitcnt lgkmcnt(4)
	v_mfma_f32_16x16x32_bf16 v[112:115], v[164:167], v[136:139], v[112:115]
	v_mfma_f32_16x16x32_bf16 v[80:83], v[164:167], v[140:143], v[80:83]
	v_mfma_f32_16x16x32_bf16 v[48:51], v[164:167], v[144:147], v[48:51]
	v_mfma_f32_16x16x32_bf16 v[16:19], v[164:167], v[148:151], v[16:19]
	s_waitcnt lgkmcnt(3)
	v_mfma_f32_16x16x32_bf16 v[108:111], v[176:179], v[136:139], v[108:111]
	v_mfma_f32_16x16x32_bf16 v[76:79], v[176:179], v[140:143], v[76:79]
	v_mfma_f32_16x16x32_bf16 v[44:47], v[176:179], v[144:147], v[44:47]
	v_mfma_f32_16x16x32_bf16 v[12:15], v[176:179], v[148:151], v[12:15]
	s_waitcnt lgkmcnt(2)
	v_mfma_f32_16x16x32_bf16 v[104:107], v[180:183], v[136:139], v[104:107]
	v_mfma_f32_16x16x32_bf16 v[72:75], v[180:183], v[140:143], v[72:75]
	v_mfma_f32_16x16x32_bf16 v[40:43], v[180:183], v[144:147], v[40:43]
	v_mfma_f32_16x16x32_bf16 v[8:11], v[180:183], v[148:151], v[8:11]
	s_waitcnt lgkmcnt(0)
	s_waitcnt vmcnt(6)
	s_barrier
	ds_read_b128 v[120:123], v209 offset:0
	ds_read_b128 v[124:127], v209 offset:1024
	ds_read_b128 v[128:131], v209 offset:2048
	ds_read_b128 v[132:135], v209 offset:3072
	ds_read_b128 v[152:155], v210 offset:8192
	ds_read_b128 v[156:159], v210 offset:9216
	ds_read_b128 v[160:163], v210 offset:10240
	ds_read_b128 v[164:167], v210 offset:11264
	ds_read_b128 v[176:179], v210 offset:12288
	ds_read_b128 v[180:183], v210 offset:13312
	v_mfma_f32_16x16x32_bf16 v[100:103], v[184:187], v[136:139], v[100:103]
	s_add_u32 m0, s11, 0xc000
	v_mfma_f32_16x16x32_bf16 v[68:71], v[184:187], v[140:143], v[68:71]
	global_load_lds_dwordx4 v203, s[2:3]
	s_add_u32 m0, s11, 0xc400
	v_mfma_f32_16x16x32_bf16 v[36:39], v[184:187], v[144:147], v[36:39]
	global_load_lds_dwordx4 v204, s[2:3]
	s_add_u32 m0, s12, 0xe000
	v_mfma_f32_16x16x32_bf16 v[4:7], v[184:187], v[148:151], v[4:7]
	global_load_lds_dwordx4 v205, s[4:5]
	s_add_u32 m0, s12, 0xe400
	v_mfma_f32_16x16x32_bf16 v[96:99], v[188:191], v[136:139], v[96:99]
	global_load_lds_dwordx4 v206, s[4:5]
	s_add_u32 m0, s12, 0xe800
	v_mfma_f32_16x16x32_bf16 v[64:67], v[188:191], v[140:143], v[64:67]
	global_load_lds_dwordx4 v207, s[4:5]
	s_add_u32 m0, s12, 0xec00
	v_mfma_f32_16x16x32_bf16 v[32:35], v[188:191], v[144:147], v[32:35]
	global_load_lds_dwordx4 v208, s[4:5]
	v_mfma_f32_16x16x32_bf16 v[0:3], v[188:191], v[148:151], v[0:3]
	s_add_u32 s2, s2, 0x40
	s_addc_u32 s3, s3, 0
	s_add_u32 s4, s4, 0x4000
	s_addc_u32 s5, s5, 0
	ds_read_b128 v[184:187], v210 offset:14336
	ds_read_b128 v[188:191], v210 offset:15360
	s_waitcnt lgkmcnt(7)
	v_mfma_f32_16x16x32_bf16 v[172:175], v[152:155], v[120:123], v[172:175]
	v_mfma_f32_16x16x32_bf16 v[92:95], v[152:155], v[124:127], v[92:95]
	v_mfma_f32_16x16x32_bf16 v[60:63], v[152:155], v[128:131], v[60:63]
	v_mfma_f32_16x16x32_bf16 v[28:31], v[152:155], v[132:135], v[28:31]
	s_waitcnt lgkmcnt(6)
	v_mfma_f32_16x16x32_bf16 v[168:171], v[156:159], v[120:123], v[168:171]
	v_mfma_f32_16x16x32_bf16 v[88:91], v[156:159], v[124:127], v[88:91]
	v_mfma_f32_16x16x32_bf16 v[56:59], v[156:159], v[128:131], v[56:59]
	v_mfma_f32_16x16x32_bf16 v[24:27], v[156:159], v[132:135], v[24:27]
	s_waitcnt lgkmcnt(5)
	v_mfma_f32_16x16x32_bf16 v[116:119], v[160:163], v[120:123], v[116:119]
	v_mfma_f32_16x16x32_bf16 v[84:87], v[160:163], v[124:127], v[84:87]
	v_mfma_f32_16x16x32_bf16 v[52:55], v[160:163], v[128:131], v[52:55]
	v_mfma_f32_16x16x32_bf16 v[20:23], v[160:163], v[132:135], v[20:23]
	s_waitcnt lgkmcnt(4)
	v_mfma_f32_16x16x32_bf16 v[112:115], v[164:167], v[120:123], v[112:115]
	v_mfma_f32_16x16x32_bf16 v[80:83], v[164:167], v[124:127], v[80:83]
	v_mfma_f32_16x16x32_bf16 v[48:51], v[164:167], v[128:131], v[48:51]
	v_mfma_f32_16x16x32_bf16 v[16:19], v[164:167], v[132:135], v[16:19]
	s_waitcnt lgkmcnt(3)
	v_mfma_f32_16x16x32_bf16 v[108:111], v[176:179], v[120:123], v[108:111]
	v_mfma_f32_16x16x32_bf16 v[76:79], v[176:179], v[124:127], v[76:79]
	v_mfma_f32_16x16x32_bf16 v[44:47], v[176:179], v[128:131], v[44:47]
	v_mfma_f32_16x16x32_bf16 v[12:15], v[176:179], v[132:135], v[12:15]
	s_waitcnt lgkmcnt(2)
	v_mfma_f32_16x16x32_bf16 v[104:107], v[180:183], v[120:123], v[104:107]
	v_mfma_f32_16x16x32_bf16 v[72:75], v[180:183], v[124:127], v[72:75]
	v_mfma_f32_16x16x32_bf16 v[40:43], v[180:183], v[128:131], v[40:43]
	v_mfma_f32_16x16x32_bf16 v[8:11], v[180:183], v[132:135], v[8:11]
	s_waitcnt lgkmcnt(0)
	s_sub_u32 s13, s13, 1
	s_cmp_lg_u32 s13, 0
	s_cbranch_scc1 .Lg1_loop
	s_waitcnt vmcnt(6)
	s_barrier
	ds_read_b128 v[136:139], v209 offset:24576
	ds_read_b128 v[140:143], v209 offset:25600
	ds_read_b128 v[144:147], v209 offset:26624
	ds_read_b128 v[148:151], v209 offset:27648
	ds_read_b128 v[152:155], v210 offset:32768
	ds_read_b128 v[156:159], v210 offset:33792
	ds_read_b128 v[160:163], v210 offset:34816
	ds_read_b128 v[164:167], v210 offset:35840
	ds_read_b128 v[176:179], v210 offset:36864
	ds_read_b128 v[180:183], v210 offset:37888
	v_mfma_f32_16x16x32_bf16 v[100:103], v[184:187], v[120:123], v[100:103]
	v_mfma_f32_16x16x32_bf16 v[68:71], v[184:187], v[124:127], v[68:71]
	v_mfma_f32_16x16x32_bf16 v[36:39], v[184:187], v[128:131], v[36:39]
	v_mfma_f32_16x16x32_bf16 v[4:7], v[184:187], v[132:135], v[4:7]
	v_mfma_f32_16x16x32_bf16 v[96:99], v[188:191], v[120:123], v[96:99]
	v_mfma_f32_16x16x32_bf16 v[64:67], v[188:191], v[124:127], v[64:67]
	v_mfma_f32_16x16x32_bf16 v[32:35], v[188:191], v[128:131], v[32:35]
	v_mfma_f32_16x16x32_bf16 v[0:3], v[188:191], v[132:135], v[0:3]
	ds_read_b128 v[184:187], v210 offset:38912
	ds_read_b128 v[188:191], v210 offset:39936
	s_waitcnt lgkmcnt(7)
	v_mfma_f32_16x16x32_bf16 v[172:175], v[152:155], v[136:139], v[172:175]
	v_mfma_f32_16x16x32_bf16 v[92:95], v[152:155], v[140:143], v[92:95]
	v_mfma_f32_16x16x32_bf16 v[60:63], v[152:155], v[144:147], v[60:63]
	v_mfma_f32_16x16x32_bf16 v[28:31], v[152:155], v[148:151], v[28:31]
	s_waitcnt lgkmcnt(6)
	v_mfma_f32_16x16x32_bf16 v[168:171], v[156:159], v[136:139], v[168:171]
	v_mfma_f32_16x16x32_bf16 v[88:91], v[156:159], v[140:143], v[88:91]
	v_mfma_f32_16x16x32_bf16 v[56:59], v[156:159], v[144:147], v[56:59]
	v_mfma_f32_16x16x32_bf16 v[24:27], v[156:159], v[148:151], v[24:27]
	s_waitcnt lgkmcnt(5)
	v_mfma_f32_16x16x32_bf16 v[116:119], v[160:163], v[136:139], v[116:119]
	v_mfma_f32_16x16x32_bf16 v[84:87], v[160:163], v[140:143], v[84:87]
	v_mfma_f32_16x16x32_bf16 v[52:55], v[160:163], v[144:147], v[52:55]
	v_mfma_f32_16x16x32_bf16 v[20:23], v[160:163], v[148:151], v[20:23]
	s_waitcnt lgkmcnt(4)
	v_mfma_f32_16x16x32_bf16 v[112:115], v[164:167], v[136:139], v[112:115]
	v_mfma_f32_16x16x32_bf16 v[80:83], v[164:167], v[140:143], v[80:83]
	v_mfma_f32_16x16x32_bf16 v[48:51], v[164:167], v[144:147], v[48:51]
	v_mfma_f32_16x16x32_bf16 v[16:19], v[164:167], v[148:151], v[16:19]
	s_waitcnt lgkmcnt(3)
	v_mfma_f32_16x16x32_bf16 v[108:111], v[176:179], v[136:139], v[108:111]
	v_mfma_f32_16x16x32_bf16 v[76:79], v[176:179], v[140:143], v[76:79]
	v_mfma_f32_16x16x32_bf16 v[44:47], v[176:179], v[144:147], v[44:47]
	v_mfma_f32_16x16x32_bf16 v[12:15], v[176:179], v[148:151], v[12:15]
	s_waitcnt lgkmcnt(2)
	v_mfma_f32_16x16x32_bf16 v[104:107], v[180:183], v[136:139], v[104:107]
	v_mfma_f32_16x16x32_bf16 v[72:75], v[180:183], v[140:143], v[72:75]
	v_mfma_f32_16x16x32_bf16 v[40:43], v[180:183], v[144:147], v[40:43]
	v_mfma_f32_16x16x32_bf16 v[8:11], v[180:183], v[148:151], v[8:11]
	s_waitcnt lgkmcnt(0)
	v_mfma_f32_16x16x32_bf16 v[100:103], v[184:187], v[136:139], v[100:103]
	v_mfma_f32_16x16x32_bf16 v[68:71], v[184:187], v[140:143], v[68:71]
	v_mfma_f32_16x16x32_bf16 v[36:39], v[184:187], v[144:147], v[36:39]
	v_mfma_f32_16x16x32_bf16 v[4:7], v[184:187], v[148:151], v[4:7]
	v_mfma_f32_16x16x32_bf16 v[96:99], v[188:191], v[136:139], v[96:99]
	v_mfma_f32_16x16x32_bf16 v[64:67], v[188:191], v[140:143], v[64:67]
	v_mfma_f32_16x16x32_bf16 v[32:35], v[188:191], v[144:147], v[32:35]
	v_mfma_f32_16x16x32_bf16 v[0:3], v[188:191], v[148:151], v[0:3]
	s_waitcnt vmcnt(0)
	s_nop 7
	s_nop 7
	s_branch .LBB0_89

.LBB0_170:
	v_lshl_add_u64 v[38:39], v[14:15], 0, s[2:3]
	v_lshl_add_u64 v[90:91], v[16:17], 0, s[2:3]
	global_load_dword v88, v[38:39], off
	global_load_dword v92, v[90:91], off
	global_load_dword v132, v[38:39], off offset:256
	global_load_dword v133, v[90:91], off offset:256
	global_load_dword v134, v[38:39], off offset:512
	global_load_dword v135, v[90:91], off offset:512
	global_load_dword v136, v[38:39], off offset:768
	global_load_dword v137, v[90:91], off offset:768
	global_load_dword v138, v[38:39], off offset:1024
	global_load_dword v139, v[90:91], off offset:1024
	global_load_dword v140, v[38:39], off offset:1280
	global_load_dword v141, v[90:91], off offset:1280
	global_load_dword v142, v[38:39], off offset:1536
	global_load_dword v143, v[90:91], off offset:1536
	global_load_dword v144, v[38:39], off offset:1792
	global_load_dword v145, v[90:91], off offset:1792
	v_mov_b32_e32 v120, s8
	ds_read_b128 v[44:47], v120
	ds_read_b128 v[48:51], v120 offset:16
	ds_read_b128 v[52:55], v120 offset:1024
	s_add_i32 s8, s8, 32
	s_add_u32 s2, s2, 0x800
	s_waitcnt lgkmcnt(2)
	v_mov_b32_e32 v56, v44
	s_addc_u32 s3, s3, 0
	s_waitcnt lgkmcnt(0)
	v_mov_b32_e32 v57, v52
	v_mov_b32_e32 v52, v45
	s_cmpk_lg_i32 s2, 0x4000
	s_waitcnt vmcnt(15)
	v_pk_fma_f32 v[94:95], v[88:89], v[56:57], v[18:19] op_sel_hi:[0,1,1]
	s_waitcnt vmcnt(14)
	v_pk_fma_f32 v[96:97], v[92:93], v[56:57], v[20:21] op_sel_hi:[0,1,1]
	ds_read_b128 v[18:21], v120 offset:2048
	ds_read_b128 v[56:59], v120 offset:3072
	s_waitcnt lgkmcnt(1)
	v_mov_b32_e32 v60, v18
	s_waitcnt lgkmcnt(0)
	v_mov_b32_e32 v61, v56
	v_pk_fma_f32 v[98:99], v[88:89], v[60:61], v[10:11] op_sel_hi:[0,1,1]
	v_pk_fma_f32 v[100:101], v[92:93], v[60:61], v[12:13] op_sel_hi:[0,1,1]
	ds_read_b128 v[10:13], v120 offset:4096
	ds_read_b128 v[60:63], v120 offset:5120
	v_mov_b32_e32 v56, v19
	s_waitcnt lgkmcnt(1)
	v_mov_b32_e32 v64, v10
	s_waitcnt lgkmcnt(0)
	v_mov_b32_e32 v65, v60
	v_pk_fma_f32 v[102:103], v[88:89], v[64:65], v[6:7] op_sel_hi:[0,1,1]
	v_pk_fma_f32 v[104:105], v[92:93], v[64:65], v[8:9] op_sel_hi:[0,1,1]
	ds_read_b128 v[6:9], v120 offset:6144
	ds_read_b128 v[64:67], v120 offset:7168
	v_mov_b32_e32 v60, v11
	s_waitcnt lgkmcnt(1)
	v_mov_b32_e32 v68, v6
	s_waitcnt lgkmcnt(0)
	v_mov_b32_e32 v69, v64
	v_pk_fma_f32 v[106:107], v[88:89], v[68:69], v[2:3] op_sel_hi:[0,1,1]
	v_pk_fma_f32 v[108:109], v[92:93], v[68:69], v[4:5] op_sel_hi:[0,1,1]
	ds_read_b128 v[2:5], v120 offset:8192
	ds_read_b128 v[68:71], v120 offset:9216
	v_mov_b32_e32 v64, v7
	s_waitcnt lgkmcnt(1)
	v_mov_b32_e32 v72, v2
	s_waitcnt lgkmcnt(0)
	v_mov_b32_e32 v73, v68
	v_pk_fma_f32 v[110:111], v[88:89], v[72:73], v[30:31] op_sel_hi:[0,1,1]
	v_pk_fma_f32 v[112:113], v[92:93], v[72:73], v[36:37] op_sel_hi:[0,1,1]
	ds_read_b128 v[72:75], v120 offset:10240
	ds_read_b128 v[76:79], v120 offset:11264
	v_mov_b32_e32 v68, v3
	s_waitcnt lgkmcnt(1)
	v_mov_b32_e32 v30, v72
	s_waitcnt lgkmcnt(0)
	v_mov_b32_e32 v31, v76
	v_pk_fma_f32 v[114:115], v[88:89], v[30:31], v[28:29] op_sel_hi:[0,1,1]
	v_pk_fma_f32 v[116:117], v[92:93], v[30:31], v[34:35] op_sel_hi:[0,1,1]
	ds_read_b128 v[28:31], v120 offset:12288
	ds_read_b128 v[34:37], v120 offset:13312
	v_mov_b32_e32 v76, v73
	s_waitcnt lgkmcnt(1)
	v_mov_b32_e32 v80, v28
	s_waitcnt lgkmcnt(0)
	v_mov_b32_e32 v81, v34
	v_pk_fma_f32 v[26:27], v[88:89], v[80:81], v[26:27] op_sel_hi:[0,1,1]
	v_pk_fma_f32 v[32:33], v[92:93], v[80:81], v[32:33] op_sel_hi:[0,1,1]
	ds_read_b128 v[80:83], v120 offset:14336
	ds_read_b128 v[84:87], v120 offset:15360
	s_waitcnt vmcnt(13)
	v_mov_b32_e32 v2, v132
	s_waitcnt vmcnt(12)
	v_mov_b32_e32 v6, v133
	v_mov_b32_e32 v34, v29
	s_waitcnt lgkmcnt(1)
	v_mov_b32_e32 v118, v80
	s_waitcnt lgkmcnt(0)
	v_mov_b32_e32 v119, v84
	v_pk_fma_f32 v[22:23], v[88:89], v[118:119], v[22:23] op_sel_hi:[0,1,1]
	v_pk_fma_f32 v[24:25], v[92:93], v[118:119], v[24:25] op_sel_hi:[0,1,1]
	v_mov_b32_e32 v84, v81
	v_pk_fma_f32 v[44:45], v[2:3], v[52:53], v[94:95] op_sel_hi:[0,1,1]
	v_pk_fma_f32 v[52:53], v[6:7], v[52:53], v[96:97] op_sel_hi:[0,1,1]
	v_pk_fma_f32 v[18:19], v[2:3], v[56:57], v[98:99] op_sel_hi:[0,1,1]
	v_pk_fma_f32 v[56:57], v[6:7], v[56:57], v[100:101] op_sel_hi:[0,1,1]
	v_pk_fma_f32 v[10:11], v[2:3], v[60:61], v[102:103] op_sel_hi:[0,1,1]
	v_pk_fma_f32 v[60:61], v[6:7], v[60:61], v[104:105] op_sel_hi:[0,1,1]
	v_pk_fma_f32 v[88:89], v[2:3], v[64:65], v[106:107] op_sel_hi:[0,1,1]
	v_pk_fma_f32 v[64:65], v[6:7], v[64:65], v[108:109] op_sel_hi:[0,1,1]
	v_pk_fma_f32 v[92:93], v[2:3], v[68:69], v[110:111] op_sel_hi:[0,1,1]
	v_pk_fma_f32 v[68:69], v[6:7], v[68:69], v[112:113] op_sel_hi:[0,1,1]
	v_pk_fma_f32 v[72:73], v[2:3], v[76:77], v[114:115] op_sel_hi:[0,1,1]
	v_pk_fma_f32 v[76:77], v[6:7], v[76:77], v[116:117] op_sel_hi:[0,1,1]
	v_pk_fma_f32 v[26:27], v[2:3], v[34:35], v[26:27] op_sel_hi:[0,1,1]
	v_pk_fma_f32 v[28:29], v[6:7], v[34:35], v[32:33] op_sel_hi:[0,1,1]
	v_pk_fma_f32 v[2:3], v[2:3], v[84:85], v[22:23] op_sel_hi:[0,1,1]
	v_pk_fma_f32 v[6:7], v[6:7], v[84:85], v[24:25] op_sel_hi:[0,1,1]
	s_waitcnt vmcnt(11)
	v_mov_b32_e32 v22, v134
	s_waitcnt vmcnt(10)
	v_mov_b32_e32 v24, v135
	v_mov_b32_e32 v32, v46
	v_mov_b32_e32 v33, v54
	v_mov_b32_e32 v54, v47
	v_pk_fma_f32 v[34:35], v[22:23], v[32:33], v[44:45] op_sel_hi:[0,1,1]
	v_mov_b32_e32 v44, v20
	v_mov_b32_e32 v45, v58
	v_pk_fma_f32 v[32:33], v[24:25], v[32:33], v[52:53] op_sel_hi:[0,1,1]
	v_pk_fma_f32 v[18:19], v[22:23], v[44:45], v[18:19] op_sel_hi:[0,1,1]
	v_pk_fma_f32 v[44:45], v[24:25], v[44:45], v[56:57] op_sel_hi:[0,1,1]
	v_mov_b32_e32 v52, v12
	v_mov_b32_e32 v53, v62
	v_mov_b32_e32 v56, v8
	v_mov_b32_e32 v57, v66
	v_pk_fma_f32 v[10:11], v[22:23], v[52:53], v[10:11] op_sel_hi:[0,1,1]
	v_pk_fma_f32 v[52:53], v[24:25], v[52:53], v[60:61] op_sel_hi:[0,1,1]
	v_pk_fma_f32 v[60:61], v[22:23], v[56:57], v[88:89] op_sel_hi:[0,1,1]
	v_pk_fma_f32 v[56:57], v[24:25], v[56:57], v[64:65] op_sel_hi:[0,1,1]
	v_mov_b32_e32 v64, v4
	s_waitcnt vmcnt(9)
	v_mov_b32_e32 v4, v136
	s_waitcnt vmcnt(8)
	v_mov_b32_e32 v8, v137
	v_mov_b32_e32 v65, v70
	v_pk_fma_f32 v[80:81], v[22:23], v[64:65], v[92:93] op_sel_hi:[0,1,1]
	v_pk_fma_f32 v[64:65], v[24:25], v[64:65], v[68:69] op_sel_hi:[0,1,1]
	v_mov_b32_e32 v68, v74
	v_mov_b32_e32 v69, v78
	v_pk_fma_f32 v[72:73], v[22:23], v[68:69], v[72:73] op_sel_hi:[0,1,1]
	v_pk_fma_f32 v[68:69], v[24:25], v[68:69], v[76:77] op_sel_hi:[0,1,1]
	v_mov_b32_e32 v76, v30
	v_mov_b32_e32 v77, v36
	v_pk_fma_f32 v[26:27], v[22:23], v[76:77], v[26:27] op_sel_hi:[0,1,1]
	v_pk_fma_f32 v[28:29], v[24:25], v[76:77], v[28:29] op_sel_hi:[0,1,1]
	v_mov_b32_e32 v76, v82
	v_mov_b32_e32 v77, v86
	v_pk_fma_f32 v[2:3], v[22:23], v[76:77], v[2:3] op_sel_hi:[0,1,1]
	v_pk_fma_f32 v[6:7], v[24:25], v[76:77], v[6:7] op_sel_hi:[0,1,1]
	v_mov_b32_e32 v66, v9
	v_mov_b32_e32 v70, v5
	v_mov_b32_e32 v86, v83
	v_mov_b32_e32 v58, v21
	v_mov_b32_e32 v62, v13
	v_mov_b32_e32 v78, v75
	v_mov_b32_e32 v36, v31
	v_pk_fma_f32 v[22:23], v[4:5], v[54:55], v[34:35] op_sel_hi:[0,1,1]
	v_pk_fma_f32 v[46:47], v[8:9], v[66:67], v[56:57] op_sel_hi:[0,1,1]
	v_pk_fma_f32 v[56:57], v[4:5], v[70:71], v[80:81] op_sel_hi:[0,1,1]
	v_pk_fma_f32 v[80:81], v[4:5], v[86:87], v[2:3] op_sel_hi:[0,1,1]
	v_pk_fma_f32 v[82:83], v[8:9], v[86:87], v[6:7] op_sel_hi:[0,1,1]
	s_waitcnt vmcnt(7)
	v_mov_b32_e32 v84, v138
	s_waitcnt vmcnt(6)
	v_mov_b32_e32 v86, v139
	v_pk_fma_f32 v[24:25], v[8:9], v[54:55], v[32:33] op_sel_hi:[0,1,1]
	v_pk_fma_f32 v[18:19], v[4:5], v[58:59], v[18:19] op_sel_hi:[0,1,1]
	v_pk_fma_f32 v[20:21], v[8:9], v[58:59], v[44:45] op_sel_hi:[0,1,1]
	v_pk_fma_f32 v[32:33], v[4:5], v[62:63], v[10:11] op_sel_hi:[0,1,1]
	v_pk_fma_f32 v[44:45], v[4:5], v[66:67], v[60:61] op_sel_hi:[0,1,1]
	v_pk_fma_f32 v[58:59], v[8:9], v[70:71], v[64:65] op_sel_hi:[0,1,1]
	v_pk_fma_f32 v[64:65], v[4:5], v[78:79], v[72:73] op_sel_hi:[0,1,1]
	v_pk_fma_f32 v[72:73], v[4:5], v[36:37], v[26:27] op_sel_hi:[0,1,1]
	ds_read_b128 v[2:5], v120 offset:1040
	v_mov_b32_e32 v6, v48
	v_pk_fma_f32 v[34:35], v[8:9], v[62:63], v[52:53] op_sel_hi:[0,1,1]
	v_pk_fma_f32 v[66:67], v[8:9], v[78:79], v[68:69] op_sel_hi:[0,1,1]
	v_pk_fma_f32 v[36:37], v[8:9], v[36:37], v[28:29] op_sel_hi:[0,1,1]
	s_waitcnt lgkmcnt(0)
	v_mov_b32_e32 v7, v2
	v_mov_b32_e32 v2, v49
	v_pk_fma_f32 v[88:89], v[84:85], v[6:7], v[22:23] op_sel_hi:[0,1,1]
	v_pk_fma_f32 v[92:93], v[86:87], v[6:7], v[24:25] op_sel_hi:[0,1,1]
	ds_read_b128 v[6:9], v120 offset:2064
	ds_read_b128 v[10:13], v120 offset:3088
	s_waitcnt lgkmcnt(1)
	v_mov_b32_e32 v22, v6
	s_waitcnt lgkmcnt(0)
	v_mov_b32_e32 v23, v10
	v_pk_fma_f32 v[18:19], v[84:85], v[22:23], v[18:19] op_sel_hi:[0,1,1]
	v_pk_fma_f32 v[94:95], v[86:87], v[22:23], v[20:21] op_sel_hi:[0,1,1]
	ds_read_b128 v[20:23], v120 offset:4112
	ds_read_b128 v[24:27], v120 offset:5136
	v_mov_b32_e32 v10, v7
	s_waitcnt lgkmcnt(1)
	v_mov_b32_e32 v28, v20
	s_waitcnt lgkmcnt(0)
	v_mov_b32_e32 v29, v24
	v_pk_fma_f32 v[96:97], v[84:85], v[28:29], v[32:33] op_sel_hi:[0,1,1]
	v_pk_fma_f32 v[98:99], v[86:87], v[28:29], v[34:35] op_sel_hi:[0,1,1]
	ds_read_b128 v[28:31], v120 offset:6160
	ds_read_b128 v[32:35], v120 offset:7184
	v_mov_b32_e32 v24, v21
	s_waitcnt lgkmcnt(1)
	v_mov_b32_e32 v52, v28
	s_waitcnt lgkmcnt(0)
	v_mov_b32_e32 v53, v32
	v_pk_fma_f32 v[100:101], v[84:85], v[52:53], v[44:45] op_sel_hi:[0,1,1]
	v_pk_fma_f32 v[102:103], v[86:87], v[52:53], v[46:47] op_sel_hi:[0,1,1]
	ds_read_b128 v[44:47], v120 offset:8208
	ds_read_b128 v[52:55], v120 offset:9232
	v_mov_b32_e32 v32, v29
	s_waitcnt lgkmcnt(1)
	v_mov_b32_e32 v60, v44
	s_waitcnt lgkmcnt(0)
	v_mov_b32_e32 v61, v52
	v_pk_fma_f32 v[104:105], v[84:85], v[60:61], v[56:57] op_sel_hi:[0,1,1]
	v_pk_fma_f32 v[106:107], v[86:87], v[60:61], v[58:59] op_sel_hi:[0,1,1]
	ds_read_b128 v[56:59], v120 offset:10256
	ds_read_b128 v[60:63], v120 offset:11280
	v_mov_b32_e32 v52, v45
	s_waitcnt lgkmcnt(1)
	v_mov_b32_e32 v68, v56
	s_waitcnt lgkmcnt(0)
	v_mov_b32_e32 v69, v60
	v_pk_fma_f32 v[108:109], v[84:85], v[68:69], v[64:65] op_sel_hi:[0,1,1]
	v_pk_fma_f32 v[110:111], v[86:87], v[68:69], v[66:67] op_sel_hi:[0,1,1]
	ds_read_b128 v[64:67], v120 offset:12304
	ds_read_b128 v[68:71], v120 offset:13328
	v_mov_b32_e32 v60, v57
	s_waitcnt lgkmcnt(1)
	v_mov_b32_e32 v74, v64
	s_waitcnt lgkmcnt(0)
	v_mov_b32_e32 v75, v68
	v_pk_fma_f32 v[112:113], v[84:85], v[74:75], v[72:73] op_sel_hi:[0,1,1]
	v_pk_fma_f32 v[36:37], v[86:87], v[74:75], v[36:37] op_sel_hi:[0,1,1]
	ds_read_b128 v[72:75], v120 offset:14352
	ds_read_b128 v[76:79], v120 offset:15376
	s_waitcnt vmcnt(5)
	v_mov_b32_e32 v6, v140
	s_waitcnt vmcnt(4)
	v_mov_b32_e32 v20, v141
	v_mov_b32_e32 v68, v65
	s_waitcnt lgkmcnt(1)
	v_mov_b32_e32 v114, v72
	s_waitcnt lgkmcnt(0)
	v_mov_b32_e32 v115, v76
	v_pk_fma_f32 v[80:81], v[84:85], v[114:115], v[80:81] op_sel_hi:[0,1,1]
	v_pk_fma_f32 v[82:83], v[86:87], v[114:115], v[82:83] op_sel_hi:[0,1,1]
	v_mov_b32_e32 v76, v73
	v_pk_fma_f32 v[64:65], v[6:7], v[68:69], v[112:113] op_sel_hi:[0,1,1]
	v_pk_fma_f32 v[36:37], v[20:21], v[68:69], v[36:37] op_sel_hi:[0,1,1]
	s_waitcnt vmcnt(3)
	v_mov_b32_e32 v68, v142
	s_waitcnt vmcnt(2)
	v_mov_b32_e32 v72, v143
	v_pk_fma_f32 v[48:49], v[6:7], v[2:3], v[88:89] op_sel_hi:[0,1,1]
	v_pk_fma_f32 v[2:3], v[20:21], v[2:3], v[92:93] op_sel_hi:[0,1,1]
	v_pk_fma_f32 v[18:19], v[6:7], v[10:11], v[18:19] op_sel_hi:[0,1,1]
	v_pk_fma_f32 v[10:11], v[20:21], v[10:11], v[94:95] op_sel_hi:[0,1,1]
	v_pk_fma_f32 v[84:85], v[6:7], v[24:25], v[96:97] op_sel_hi:[0,1,1]
	v_pk_fma_f32 v[24:25], v[20:21], v[24:25], v[98:99] op_sel_hi:[0,1,1]
	v_pk_fma_f32 v[28:29], v[6:7], v[32:33], v[100:101] op_sel_hi:[0,1,1]
	v_pk_fma_f32 v[32:33], v[20:21], v[32:33], v[102:103] op_sel_hi:[0,1,1]
	v_pk_fma_f32 v[44:45], v[6:7], v[52:53], v[104:105] op_sel_hi:[0,1,1]
	v_pk_fma_f32 v[52:53], v[20:21], v[52:53], v[106:107] op_sel_hi:[0,1,1]
	v_pk_fma_f32 v[56:57], v[6:7], v[60:61], v[108:109] op_sel_hi:[0,1,1]
	v_pk_fma_f32 v[60:61], v[20:21], v[60:61], v[110:111] op_sel_hi:[0,1,1]
	v_pk_fma_f32 v[6:7], v[6:7], v[76:77], v[80:81] op_sel_hi:[0,1,1]
	v_pk_fma_f32 v[20:21], v[20:21], v[76:77], v[82:83] op_sel_hi:[0,1,1]
	v_mov_b32_e32 v76, v50
	v_mov_b32_e32 v77, v4
	v_mov_b32_e32 v4, v51
	v_pk_fma_f32 v[48:49], v[68:69], v[76:77], v[48:49] op_sel_hi:[0,1,1]
	v_pk_fma_f32 v[2:3], v[72:73], v[76:77], v[2:3] op_sel_hi:[0,1,1]
	v_mov_b32_e32 v76, v8
	v_mov_b32_e32 v77, v12
	v_pk_fma_f32 v[80:81], v[68:69], v[76:77], v[18:19] op_sel_hi:[0,1,1]
	v_pk_fma_f32 v[76:77], v[72:73], v[76:77], v[10:11] op_sel_hi:[0,1,1]
	v_mov_b32_e32 v10, v22
	s_waitcnt vmcnt(1)
	v_mov_b32_e32 v22, v144
	s_nop 0
	s_waitcnt vmcnt(0)
	v_mov_b32_e32 v38, v145
	v_mov_b32_e32 v11, v26
	v_pk_fma_f32 v[82:83], v[68:69], v[10:11], v[84:85] op_sel_hi:[0,1,1]
	v_pk_fma_f32 v[24:25], v[72:73], v[10:11], v[24:25] op_sel_hi:[0,1,1]
	v_mov_b32_e32 v10, v30
	v_mov_b32_e32 v11, v34
	v_pk_fma_f32 v[28:29], v[68:69], v[10:11], v[28:29] op_sel_hi:[0,1,1]
	v_pk_fma_f32 v[32:33], v[72:73], v[10:11], v[32:33] op_sel_hi:[0,1,1]
	v_mov_b32_e32 v10, v46
	v_mov_b32_e32 v11, v54
	v_pk_fma_f32 v[44:45], v[68:69], v[10:11], v[44:45] op_sel_hi:[0,1,1]
	v_pk_fma_f32 v[52:53], v[72:73], v[10:11], v[52:53] op_sel_hi:[0,1,1]
	v_mov_b32_e32 v10, v58
	v_mov_b32_e32 v11, v62
	v_pk_fma_f32 v[56:57], v[68:69], v[10:11], v[56:57] op_sel_hi:[0,1,1]
	v_pk_fma_f32 v[60:61], v[72:73], v[10:11], v[60:61] op_sel_hi:[0,1,1]
	v_mov_b32_e32 v10, v66
	v_mov_b32_e32 v11, v70
	v_pk_fma_f32 v[64:65], v[68:69], v[10:11], v[64:65] op_sel_hi:[0,1,1]
	v_pk_fma_f32 v[84:85], v[72:73], v[10:11], v[36:37] op_sel_hi:[0,1,1]
	v_mov_b32_e32 v10, v74
	v_mov_b32_e32 v11, v78
	v_pk_fma_f32 v[68:69], v[68:69], v[10:11], v[6:7] op_sel_hi:[0,1,1]
	v_pk_fma_f32 v[72:73], v[72:73], v[10:11], v[20:21] op_sel_hi:[0,1,1]
	v_mov_b32_e32 v12, v9
	v_mov_b32_e32 v26, v23
	v_mov_b32_e32 v34, v31
	v_mov_b32_e32 v54, v47
	v_mov_b32_e32 v62, v59
	v_mov_b32_e32 v70, v67
	v_mov_b32_e32 v78, v75
	v_pk_fma_f32 v[18:19], v[22:23], v[4:5], v[48:49] op_sel_hi:[0,1,1]
	v_pk_fma_f32 v[20:21], v[38:39], v[4:5], v[2:3] op_sel_hi:[0,1,1]
	v_pk_fma_f32 v[10:11], v[22:23], v[12:13], v[80:81] op_sel_hi:[0,1,1]
	v_pk_fma_f32 v[12:13], v[38:39], v[12:13], v[76:77] op_sel_hi:[0,1,1]
	v_pk_fma_f32 v[6:7], v[22:23], v[26:27], v[82:83] op_sel_hi:[0,1,1]
	v_pk_fma_f32 v[8:9], v[38:39], v[26:27], v[24:25] op_sel_hi:[0,1,1]
	v_pk_fma_f32 v[2:3], v[22:23], v[34:35], v[28:29] op_sel_hi:[0,1,1]
	v_pk_fma_f32 v[4:5], v[38:39], v[34:35], v[32:33] op_sel_hi:[0,1,1]
	v_pk_fma_f32 v[30:31], v[22:23], v[54:55], v[44:45] op_sel_hi:[0,1,1]
	v_pk_fma_f32 v[36:37], v[38:39], v[54:55], v[52:53] op_sel_hi:[0,1,1]
	v_pk_fma_f32 v[28:29], v[22:23], v[62:63], v[56:57] op_sel_hi:[0,1,1]
	v_pk_fma_f32 v[34:35], v[38:39], v[62:63], v[60:61] op_sel_hi:[0,1,1]
	v_pk_fma_f32 v[26:27], v[22:23], v[70:71], v[64:65] op_sel_hi:[0,1,1]
	v_pk_fma_f32 v[32:33], v[38:39], v[70:71], v[84:85] op_sel_hi:[0,1,1]
	v_pk_fma_f32 v[22:23], v[22:23], v[78:79], v[68:69] op_sel_hi:[0,1,1]
	v_pk_fma_f32 v[24:25], v[38:39], v[78:79], v[72:73] op_sel_hi:[0,1,1]
	s_cbranch_scc1 .LBB0_170
	s_mov_b32 s2, 0xbfb8aa3b
	v_mul_f32_e64 v14, |v43|, s2
	v_exp_f32_e32 v16, v14
	v_max_f32_e64 v14, -v43, -v43
	v_max_f32_e32 v17, 0, v14
	s_mov_b32 s2, 0x3f2aaaab
	v_add_f32_e32 v22, 1.0, v16
	v_add_f32_e32 v14, -1.0, v22
	v_sub_f32_e32 v15, v14, v22
	v_sub_f32_e32 v14, v16, v14
	v_add_f32_e32 v15, 1.0, v15
	v_add_f32_e32 v23, v14, v15
	v_frexp_mant_f32_e32 v24, v22
	v_cvt_f64_f32_e32 v[14:15], v22
	v_frexp_exp_i32_f64_e32 v14, v[14:15]
	v_cmp_gt_f32_e32 vcc, s2, v24
	s_mov_b32 s2, 0x3f317218
	s_mov_b32 s12, 0xc1000000
	v_subbrev_co_u32_e32 v14, vcc, 0, v14, vcc
	v_sub_u32_e32 v15, 0, v14
	v_ldexp_f32 v22, v22, v15
	v_ldexp_f32 v15, v23, v15
	v_add_f32_e32 v23, -1.0, v22
	v_add_f32_e32 v26, 1.0, v22
	v_add_f32_e32 v24, 1.0, v23
	v_add_f32_e32 v27, -1.0, v26
	v_sub_f32_e32 v24, v22, v24
	v_sub_f32_e32 v22, v22, v27
	v_add_f32_e32 v24, v15, v24
	v_add_f32_e32 v15, v15, v22
	v_add_f32_e32 v22, v26, v15
	v_rcp_f32_e32 v27, v22
	v_add_f32_e32 v25, v23, v24
	v_sub_f32_e32 v23, v25, v23
	v_sub_f32_e32 v23, v24, v23
	v_sub_f32_e32 v24, v22, v26
	v_sub_f32_e32 v15, v15, v24
	v_mul_f32_e32 v24, v25, v27
	v_mul_f32_e32 v26, v22, v24
	v_fma_f32 v28, v24, v22, -v26
	v_fmac_f32_e32 v28, v24, v15
	v_add_f32_e32 v29, v26, v28
	v_sub_f32_e32 v30, v25, v29
	v_sub_f32_e32 v25, v25, v30
	v_sub_f32_e32 v26, v29, v26
	v_sub_f32_e32 v25, v25, v29
	v_add_f32_e32 v23, v23, v25
	v_sub_f32_e32 v25, v26, v28
	v_add_f32_e32 v23, v25, v23
	v_add_f32_e32 v25, v30, v23
	v_mul_f32_e32 v26, v27, v25
	v_mul_f32_e32 v28, v22, v26
	v_fma_f32 v22, v26, v22, -v28
	v_fmac_f32_e32 v22, v26, v15
	v_sub_f32_e32 v15, v30, v25
	v_add_f32_e32 v15, v23, v15
	v_add_f32_e32 v23, v28, v22
	v_sub_f32_e32 v29, v25, v23
	v_sub_f32_e32 v25, v25, v29
	v_sub_f32_e32 v28, v23, v28
	v_sub_f32_e32 v23, v25, v23
	v_add_f32_e32 v15, v15, v23
	v_sub_f32_e32 v22, v28, v22
	v_cvt_f32_i32_e32 v14, v14
	v_add_f32_e32 v15, v22, v15
	v_add_f32_e32 v22, v24, v26
	v_add_f32_e32 v15, v29, v15
	v_sub_f32_e32 v23, v22, v24
	v_mul_f32_e32 v15, v27, v15
	v_sub_f32_e32 v23, v26, v23
	v_add_f32_e32 v15, v23, v15
	v_mul_f32_e32 v26, 0x3f317218, v14
	v_add_f32_e32 v23, v22, v15
	v_fma_f32 v27, v14, s2, -v26
	v_mul_f32_e32 v24, v23, v23
	v_fmac_f32_e32 v27, 0xb102e308, v14
	v_sub_f32_e32 v14, v23, v22
	v_fmamk_f32 v25, v24, 0x3e9b6dac, v229
	v_sub_f32_e32 v14, v15, v14
	v_add_f32_e32 v15, v26, v27
	v_fmaak_f32 v25, v24, v25, 0x3f2aaada
	v_sub_f32_e32 v22, v15, v26
	v_ldexp_f32 v26, v23, 1
	v_mul_f32_e32 v23, v23, v24
	v_mul_f32_e32 v23, v23, v25
	v_add_f32_e32 v24, v26, v23
	v_sub_f32_e32 v25, v24, v26
	v_ldexp_f32 v14, v14, 1
	v_sub_f32_e32 v23, v23, v25
	v_add_f32_e32 v14, v14, v23
	v_add_f32_e32 v23, v24, v14
	v_sub_f32_e32 v24, v23, v24
	v_sub_f32_e32 v14, v14, v24
	v_add_f32_e32 v24, v15, v23
	v_sub_f32_e32 v25, v24, v15
	v_sub_f32_e32 v26, v24, v25
	v_sub_f32_e32 v22, v27, v22
	v_sub_f32_e32 v15, v15, v26
	v_sub_f32_e32 v23, v23, v25
	v_add_f32_e32 v15, v23, v15
	v_add_f32_e32 v23, v22, v14
	v_sub_f32_e32 v25, v23, v22
	v_sub_f32_e32 v26, v23, v25
	v_sub_f32_e32 v22, v22, v26
	v_sub_f32_e32 v14, v14, v25
	v_add_f32_e32 v15, v23, v15
	v_add_f32_e32 v14, v14, v22
	v_add_f32_e32 v22, v24, v15
	v_sub_f32_e32 v23, v22, v24
	v_sub_f32_e32 v15, v15, v23
	v_add_f32_e32 v14, v14, v15
	v_add_f32_e32 v15, v42, v20
	v_mul_f32_e32 v15, 0xbfb8aa3b, v15
	s_mov_b32 s2, 0x7f800000
	v_exp_f32_e32 v15, v15
	v_add_f32_e32 v14, v22, v14
	v_cmp_neq_f32_e32 vcc, s2, v16
	s_mov_b32 s2, 0x33800000
	v_add_f32_e32 v15, 1.0, v15
	v_cndmask_b32_e32 v14, v233, v14, vcc
	v_cmp_ngt_f32_e32 vcc, -1.0, v16
	v_add_f32_e32 v12, v42, v12
	v_mul_f32_e32 v12, 0xbfb8aa3b, v12
	v_cndmask_b32_e32 v14, v236, v14, vcc
	v_cmp_neq_f32_e32 vcc, -1.0, v16
	v_exp_f32_e32 v12, v12
	v_add_f32_e32 v10, v41, v10
	v_cndmask_b32_e32 v14, v237, v14, vcc
	v_cmp_lt_f32_e64 vcc, |v16|, s2
	v_add_f32_e32 v12, 1.0, v12
	v_mul_f32_e32 v10, 0xbfb8aa3b, v10
	v_cndmask_b32_e32 v14, v14, v16, vcc
	v_div_scale_f32 v16, s[2:3], v15, v15, 1.0
	v_rcp_f32_e32 v20, v16
	v_add_f32_e32 v14, v17, v14
	v_add_f32_e32 v17, v41, v18
	s_lshl_b64 s[2:3], s[94:95], 8
	v_fma_f32 v18, -v16, v20, 1.0
	v_fmac_f32_e32 v20, v18, v20
	v_div_scale_f32 v18, vcc, 1.0, v15, 1.0
	v_mul_f32_e32 v24, v18, v20
	v_fma_f32 v22, -v16, v24, v18
	v_fmac_f32_e32 v24, v22, v20
	v_fma_f32 v16, -v16, v24, v18
	v_div_fmas_f32 v16, v16, v20, v24
	v_div_fixup_f32 v15, v16, v15, 1.0
	v_add_f32_e32 v16, v42, v21
	ds_read2st64_b32 v[22:23], v40 offset1:4
	v_mul_f32_e32 v16, 0xbfb8aa3b, v16
	v_exp_f32_e32 v16, v16
	v_lshl_add_u64 v[20:21], s[2:3], 0, v[0:1]
	v_mul_f32_e32 v17, 0xbfb8aa3b, v17
	s_waitcnt lgkmcnt(0)
	v_mul_f32_e32 v15, v15, v22
	v_add_f32_e32 v22, 1.0, v16
	v_div_scale_f32 v18, s[2:3], v22, v22, 1.0
	v_rcp_f32_e32 v24, v18
	v_add_f32_e32 v16, v41, v19
	v_mul_f32_e32 v16, 0xbfb8aa3b, v16
	v_exp_f32_e32 v17, v17
	v_exp_f32_e32 v16, v16
	v_fma_f32 v19, -v18, v24, 1.0
	v_fmac_f32_e32 v24, v19, v24
	v_div_scale_f32 v19, vcc, 1.0, v22, 1.0
	v_mul_f32_e32 v25, v19, v24
	v_fma_f32 v26, -v18, v25, v19
	v_pk_add_f32 v[16:17], v[16:17], 1.0 op_sel_hi:[1,0]
	v_fmac_f32_e32 v25, v26, v24
	v_div_scale_f32 v26, s[2:3], v17, v17, 1.0
	v_rcp_f32_e32 v27, v26
	v_fma_f32 v18, -v18, v25, v19
	v_div_fmas_f32 v28, v18, v24, v25
	v_div_fixup_f32 v22, v28, v22, 1.0
	v_fma_f32 v18, -v26, v27, 1.0
	v_fmac_f32_e32 v27, v18, v27
	v_div_scale_f32 v18, vcc, 1.0, v17, 1.0
	v_mul_f32_e32 v19, v18, v27
	v_fma_f32 v24, -v26, v19, v18
	v_fmac_f32_e32 v19, v24, v27
	v_div_scale_f32 v24, s[2:3], v16, v16, 1.0
	v_rcp_f32_e32 v25, v24
	v_fma_f32 v18, -v26, v19, v18
	v_div_fmas_f32 v18, v18, v27, v19
	v_div_fixup_f32 v17, v18, v17, 1.0
	v_fma_f32 v18, -v24, v25, 1.0
	v_fmac_f32_e32 v25, v18, v25
	v_div_scale_f32 v18, vcc, 1.0, v16, 1.0
	v_mul_f32_e32 v19, v18, v25
	v_fma_f32 v26, -v24, v19, v18
	v_fmac_f32_e32 v19, v26, v25
	v_fma_f32 v18, -v24, v19, v18
	v_div_fmas_f32 v18, v18, v25, v19
	v_div_fixup_f32 v16, v18, v16, 1.0
	v_pk_mul_f32 v[16:17], v[16:17], s[12:13] op_sel_hi:[1,0]
	v_lshlrev_b64 v[20:21], 1, v[20:21]
	v_pk_mul_f32 v[16:17], v[14:15], v[16:17] op_sel_hi:[0,1]
	v_pk_add_f32 v[18:19], v[16:17], v[16:17]
	s_add_i32 s94, s4, 0xfffffb41
	v_mul_f32_e32 v24, 0x3fb8aa3b, v19
	v_rndne_f32_e32 v24, v24
	v_fmamk_f32 v25, v24, 0xbf317218, v19
	v_fmac_f32_e32 v25, 0x3102e308, v24
	v_fmamk_f32 v26, v25, 0x395133b1, v230
	v_fmaak_f32 v26, v25, v26, 0x3c0887f9
	v_fmaak_f32 v26, v25, v26, 0x3d2aaa81
	v_cvt_i32_f32_e32 v27, v24
	v_fmaak_f32 v26, v25, v26, 0x3e2aaaab
	v_fma_f32 v26, v25, v26, 0.5
	v_mul_f32_e32 v26, v25, v26
	v_fmac_f32_e32 v25, v25, v26
	v_ldexp_f32 v26, 1.0, v27
	v_cmp_eq_f32_e32 vcc, s25, v24
	s_lshl_b64 s[2:3], s[94:95], 8
	s_add_i32 s94, s4, 0xfffffb42
	v_cndmask_b32_e32 v24, v26, v238, vcc
	v_add_f32_e32 v26, -1.0, v24
	v_fmac_f32_e32 v26, v24, v25
	v_add_f32_e32 v24, v26, v26
	v_cndmask_b32_e32 v24, v26, v24, vcc
	v_cmp_nlt_f32_e32 vcc, s70, v19
	v_add_f32_e32 v8, v42, v8
	v_mul_f32_e32 v8, 0xbfb8aa3b, v8
	v_cndmask_b32_e64 v24, v237, -v24, vcc
	v_mul_f32_e32 v25, 0x4f800000, v24
	v_cmp_gt_f32_e32 vcc, s26, v24
	v_exp_f32_e32 v8, v8
	v_add_f32_e32 v6, v41, v6
	v_cndmask_b32_e32 v26, v24, v25, vcc
	v_sqrt_f32_e32 v27, v26
	v_lshl_add_u64 v[24:25], s[6:7], 0, v[20:21]
	v_lshl_add_u64 v[20:21], s[22:23], 0, v[20:21]
	v_add_f32_e32 v8, 1.0, v8
	v_add_u32_e32 v28, -1, v27
	v_fma_f32 v29, -v28, v27, v26
	v_cmp_ge_f32_e64 s[8:9], 0, v29
	v_add_u32_e32 v29, 1, v27
	v_mul_f32_e32 v6, 0xbfb8aa3b, v6
	v_cndmask_b32_e64 v28, v27, v28, s[8:9]
	v_fma_f32 v27, -v29, v27, v26
	v_cmp_lt_f32_e64 s[8:9], 0, v27
	v_add_f32_e32 v4, v42, v4
	v_mul_f32_e32 v4, 0xbfb8aa3b, v4
	v_cndmask_b32_e64 v27, v28, v29, s[8:9]
	v_mul_f32_e32 v28, 0x37800000, v27
	v_cndmask_b32_e32 v27, v27, v28, vcc
	v_cmp_class_f32_e32 vcc, v26, v231
	v_exp_f32_e32 v4, v4
	v_add_f32_e32 v2, v41, v2
	v_cndmask_b32_e32 v26, v27, v26, vcc
	v_cmp_ngt_f32_e32 vcc, s27, v19
	v_add_f32_e32 v4, 1.0, v4
	v_mul_f32_e32 v2, 0xbfb8aa3b, v2
	v_cndmask_b32_e32 v19, 1.0, v26, vcc
	v_mul_f32_e32 v15, v19, v15
	v_bfe_u32 v19, v17, 16, 1
	v_add3_u32 v17, v17, v19, s69
	global_store_short_d16_hi v[24:25], v17, off
	v_mul_f32_e32 v17, 0x3fb8aa3b, v18
	v_rndne_f32_e32 v17, v17
	v_fmamk_f32 v19, v17, 0xbf317218, v18
	v_fmac_f32_e32 v19, 0x3102e308, v17
	v_fmamk_f32 v24, v19, 0x395133b1, v230
	v_fmaak_f32 v24, v19, v24, 0x3c0887f9
	v_fmaak_f32 v24, v19, v24, 0x3d2aaa81
	v_cvt_i32_f32_e32 v25, v17
	v_fmaak_f32 v24, v19, v24, 0x3e2aaaab
	v_fma_f32 v24, v19, v24, 0.5
	v_mul_f32_e32 v24, v19, v24
	v_fmac_f32_e32 v19, v19, v24
	v_ldexp_f32 v24, 1.0, v25
	v_cmp_eq_f32_e32 vcc, s25, v17
	s_nop 1
	v_cndmask_b32_e32 v17, v24, v238, vcc
	v_add_f32_e32 v24, -1.0, v17
	v_fmac_f32_e32 v24, v17, v19
	v_add_f32_e32 v17, v24, v24
	v_cndmask_b32_e32 v17, v24, v17, vcc
	v_cmp_nlt_f32_e32 vcc, s70, v18
	v_bfe_u32 v24, v15, 16, 1
	v_add3_u32 v15, v15, v24, s69
	v_cndmask_b32_e64 v17, v237, -v17, vcc
	v_mul_f32_e32 v19, 0x4f800000, v17
	v_cmp_gt_f32_e32 vcc, s26, v17
	global_store_short_d16_hi v[20:21], v15, off
	s_nop 0
	v_cndmask_b32_e32 v17, v17, v19, vcc
	v_sqrt_f32_e32 v19, v17
	s_nop 0
	v_add_u32_e32 v15, -1, v19
	v_fma_f32 v20, -v15, v19, v17
	v_cmp_ge_f32_e64 s[8:9], 0, v20
	v_add_u32_e32 v20, 1, v19
	s_nop 0
	v_cndmask_b32_e64 v15, v19, v15, s[8:9]
	v_fma_f32 v19, -v20, v19, v17
	v_cmp_lt_f32_e64 s[8:9], 0, v19
	s_nop 1
	v_cndmask_b32_e64 v15, v15, v20, s[8:9]
	v_mul_f32_e32 v19, 0x37800000, v15
	v_cndmask_b32_e32 v15, v15, v19, vcc
	v_cmp_class_f32_e32 vcc, v17, v231
	s_nop 1
	v_cndmask_b32_e32 v15, v15, v17, vcc
	v_cmp_ngt_f32_e32 vcc, s27, v18
	v_mul_f32_e32 v17, v22, v23
	s_nop 0
	v_cndmask_b32_e32 v15, 1.0, v15, vcc
	v_mul_f32_e32 v15, v15, v17
	v_bfe_u32 v17, v16, 16, 1
	v_add3_u32 v20, v16, v17, s69
	v_lshl_add_u64 v[16:17], s[2:3], 0, v[0:1]
	v_lshlrev_b64 v[16:17], 1, v[16:17]
	v_lshl_add_u64 v[18:19], s[6:7], 0, v[16:17]
	global_store_short_d16_hi v[18:19], v20, off
	v_bfe_u32 v18, v15, 16, 1
	v_add3_u32 v15, v15, v18, s69
	v_lshl_add_u64 v[16:17], s[22:23], 0, v[16:17]
	global_store_short_d16_hi v[16:17], v15, off
	v_div_scale_f32 v15, s[2:3], v12, v12, 1.0
	v_rcp_f32_e32 v16, v15
	v_exp_f32_e32 v17, v10
	s_lshl_b64 s[2:3], s[94:95], 8
	s_add_i32 s94, s4, 0xfffffb43
	v_fma_f32 v10, -v15, v16, 1.0
	v_fmac_f32_e32 v16, v10, v16
	v_div_scale_f32 v10, vcc, 1.0, v12, 1.0
	v_mul_f32_e32 v20, v10, v16
	v_fma_f32 v18, -v15, v20, v10
	v_fmac_f32_e32 v20, v18, v16
	ds_read2st64_b32 v[18:19], v40 offset0:8 offset1:12
	v_fma_f32 v10, -v15, v20, v10
	v_div_fmas_f32 v10, v10, v16, v20
	v_div_fixup_f32 v10, v10, v12, 1.0
	s_waitcnt lgkmcnt(0)
	v_mul_f32_e32 v15, v10, v18
	v_add_f32_e32 v10, v42, v13
	v_mul_f32_e32 v10, 0xbfb8aa3b, v10
	v_exp_f32_e32 v10, v10
	v_lshl_add_u64 v[12:13], s[2:3], 0, v[0:1]
	v_lshlrev_b64 v[12:13], 1, v[12:13]
	v_add_f32_e32 v18, 1.0, v10
	v_div_scale_f32 v20, s[2:3], v18, v18, 1.0
	v_rcp_f32_e32 v21, v20
	v_add_f32_e32 v10, v41, v11
	v_mul_f32_e32 v10, 0xbfb8aa3b, v10
	v_exp_f32_e32 v16, v10
	v_fma_f32 v10, -v20, v21, 1.0
	v_fmac_f32_e32 v21, v10, v21
	v_div_scale_f32 v22, vcc, 1.0, v18, 1.0
	v_mul_f32_e32 v23, v22, v21
	v_fma_f32 v10, -v20, v23, v22
	v_fmac_f32_e32 v23, v10, v21
	v_pk_add_f32 v[10:11], v[16:17], 1.0 op_sel_hi:[1,0]
	v_fma_f32 v20, -v20, v23, v22
	v_div_scale_f32 v16, s[2:3], v11, v11, 1.0
	v_rcp_f32_e32 v17, v16
	v_div_fmas_f32 v22, v20, v21, v23
	v_div_fixup_f32 v18, v22, v18, 1.0
	v_fma_f32 v20, -v16, v17, 1.0
	v_fmac_f32_e32 v17, v20, v17
	v_div_scale_f32 v20, vcc, 1.0, v11, 1.0
	v_mul_f32_e32 v21, v20, v17
	v_fma_f32 v23, -v16, v21, v20
	v_fmac_f32_e32 v21, v23, v17
	v_fma_f32 v16, -v16, v21, v20
	v_div_scale_f32 v20, s[2:3], v10, v10, 1.0
	v_rcp_f32_e32 v23, v20
	v_div_fmas_f32 v16, v16, v17, v21
	v_div_fixup_f32 v11, v16, v11, 1.0
	s_lshl_b64 s[2:3], s[94:95], 8
	v_fma_f32 v16, -v20, v23, 1.0
	v_fmac_f32_e32 v23, v16, v23
	v_div_scale_f32 v16, vcc, 1.0, v10, 1.0
	v_mul_f32_e32 v17, v16, v23
	v_fma_f32 v21, -v20, v17, v16
	v_fmac_f32_e32 v17, v21, v23
	v_fma_f32 v16, -v20, v17, v16
	v_div_fmas_f32 v16, v16, v23, v17
	v_div_fixup_f32 v10, v16, v10, 1.0
	v_pk_mul_f32 v[10:11], v[10:11], s[12:13] op_sel_hi:[1,0]
	s_add_i32 s94, s4, 0xfffffb44
	v_pk_mul_f32 v[10:11], v[14:15], v[10:11] op_sel_hi:[0,1]
	v_pk_add_f32 v[16:17], v[10:11], v[10:11]
	s_nop 0
	v_mul_f32_e32 v20, 0x3fb8aa3b, v17
	v_rndne_f32_e32 v20, v20
	v_fmamk_f32 v21, v20, 0xbf317218, v17
	v_fmac_f32_e32 v21, 0x3102e308, v20
	v_fmamk_f32 v23, v21, 0x395133b1, v230
	v_fmaak_f32 v23, v21, v23, 0x3c0887f9
	v_fmaak_f32 v23, v21, v23, 0x3d2aaa81
	v_cvt_i32_f32_e32 v24, v20
	v_fmaak_f32 v23, v21, v23, 0x3e2aaaab
	v_fma_f32 v23, v21, v23, 0.5
	v_mul_f32_e32 v23, v21, v23
	v_fmac_f32_e32 v21, v21, v23
	v_ldexp_f32 v23, 1.0, v24
	v_cmp_eq_f32_e32 vcc, s25, v20
	s_nop 1
	v_cndmask_b32_e32 v20, v23, v238, vcc
	v_add_f32_e32 v23, -1.0, v20
	v_fmac_f32_e32 v23, v20, v21
	v_add_f32_e32 v20, v23, v23
	v_cndmask_b32_e32 v20, v23, v20, vcc
	v_cmp_nlt_f32_e32 vcc, s70, v17
	s_nop 1
	v_cndmask_b32_e64 v20, v237, -v20, vcc
	v_mul_f32_e32 v21, 0x4f800000, v20
	v_cmp_gt_f32_e32 vcc, s26, v20
	s_nop 1
	v_cndmask_b32_e32 v23, v20, v21, vcc
	v_sqrt_f32_e32 v24, v23
	v_lshl_add_u64 v[20:21], s[6:7], 0, v[12:13]
	v_lshl_add_u64 v[12:13], s[22:23], 0, v[12:13]
	v_add_u32_e32 v22, -1, v24
	v_fma_f32 v25, -v22, v24, v23
	v_cmp_ge_f32_e64 s[8:9], 0, v25
	v_add_u32_e32 v25, 1, v24
	s_nop 0
	v_cndmask_b32_e64 v22, v24, v22, s[8:9]
	v_fma_f32 v24, -v25, v24, v23
	v_cmp_lt_f32_e64 s[8:9], 0, v24
	s_nop 1
	v_cndmask_b32_e64 v22, v22, v25, s[8:9]
	v_mul_f32_e32 v24, 0x37800000, v22
	v_cndmask_b32_e32 v22, v22, v24, vcc
	v_cmp_class_f32_e32 vcc, v23, v231
	s_nop 1
	v_cndmask_b32_e32 v22, v22, v23, vcc
	v_cmp_ngt_f32_e32 vcc, s27, v17
	s_nop 1
	v_cndmask_b32_e32 v17, 1.0, v22, vcc
	v_mul_f32_e32 v15, v17, v15
	v_bfe_u32 v17, v11, 16, 1
	v_add3_u32 v11, v11, v17, s69
	global_store_short_d16_hi v[20:21], v11, off
	v_mul_f32_e32 v11, 0x3fb8aa3b, v16
	v_rndne_f32_e32 v11, v11
	v_fmamk_f32 v17, v11, 0xbf317218, v16
	v_fmac_f32_e32 v17, 0x3102e308, v11
	v_fmamk_f32 v20, v17, 0x395133b1, v230
	v_fmaak_f32 v20, v17, v20, 0x3c0887f9
	v_fmaak_f32 v20, v17, v20, 0x3d2aaa81
	v_cvt_i32_f32_e32 v21, v11
	v_fmaak_f32 v20, v17, v20, 0x3e2aaaab
	v_fma_f32 v20, v17, v20, 0.5
	v_mul_f32_e32 v20, v17, v20
	v_fmac_f32_e32 v17, v17, v20
	v_ldexp_f32 v20, 1.0, v21
	v_cmp_eq_f32_e32 vcc, s25, v11
	s_nop 1
	v_cndmask_b32_e32 v11, v20, v238, vcc
	v_add_f32_e32 v20, -1.0, v11
	v_fmac_f32_e32 v20, v11, v17
	v_add_f32_e32 v11, v20, v20
	v_cndmask_b32_e32 v11, v20, v11, vcc
	v_cmp_nlt_f32_e32 vcc, s70, v16
	v_bfe_u32 v20, v15, 16, 1
	v_add3_u32 v15, v15, v20, s69
	v_cndmask_b32_e64 v11, v237, -v11, vcc
	v_mul_f32_e32 v17, 0x4f800000, v11
	v_cmp_gt_f32_e32 vcc, s26, v11
	global_store_short_d16_hi v[12:13], v15, off
	s_nop 0
	v_cndmask_b32_e32 v11, v11, v17, vcc
	v_sqrt_f32_e32 v17, v11
	s_nop 0
	v_add_u32_e32 v12, -1, v17
	v_fma_f32 v13, -v12, v17, v11
	v_cmp_ge_f32_e64 s[8:9], 0, v13
	v_add_u32_e32 v13, 1, v17
	v_fma_f32 v15, -v13, v17, v11
	v_cndmask_b32_e64 v12, v17, v12, s[8:9]
	v_cmp_lt_f32_e64 s[8:9], 0, v15
	s_nop 1
	v_cndmask_b32_e64 v12, v12, v13, s[8:9]
	v_mul_f32_e32 v13, 0x37800000, v12
	v_cndmask_b32_e32 v12, v12, v13, vcc
	v_cmp_class_f32_e32 vcc, v11, v231
	s_nop 1
	v_cndmask_b32_e32 v11, v12, v11, vcc
	v_cmp_ngt_f32_e32 vcc, s27, v16
	v_mul_f32_e32 v12, v18, v19
	s_nop 0
	v_cndmask_b32_e32 v11, 1.0, v11, vcc
	v_mul_f32_e32 v15, v11, v12
	v_bfe_u32 v11, v10, 16, 1
	v_add3_u32 v16, v10, v11, s69
	v_lshl_add_u64 v[10:11], s[2:3], 0, v[0:1]
	v_lshlrev_b64 v[10:11], 1, v[10:11]
	v_lshl_add_u64 v[12:13], s[6:7], 0, v[10:11]
	global_store_short_d16_hi v[12:13], v16, off
	v_bfe_u32 v12, v15, 16, 1
	v_add3_u32 v12, v15, v12, s69
	v_lshl_add_u64 v[10:11], s[22:23], 0, v[10:11]
	global_store_short_d16_hi v[10:11], v12, off
	v_div_scale_f32 v10, s[2:3], v8, v8, 1.0
	v_rcp_f32_e32 v15, v10
	v_exp_f32_e32 v11, v6
	s_lshl_b64 s[2:3], s[94:95], 8
	s_add_i32 s94, s4, 0xfffffb45
	v_fma_f32 v6, -v10, v15, 1.0
	v_fmac_f32_e32 v15, v6, v15
	v_div_scale_f32 v6, vcc, 1.0, v8, 1.0
	v_mul_f32_e32 v16, v6, v15
	v_fma_f32 v12, -v10, v16, v6
	v_fmac_f32_e32 v16, v12, v15
	ds_read2st64_b32 v[12:13], v40 offset0:16 offset1:20
	v_fma_f32 v6, -v10, v16, v6
	v_div_fmas_f32 v6, v6, v15, v16
	v_div_fixup_f32 v6, v6, v8, 1.0
	s_waitcnt lgkmcnt(0)
	v_mul_f32_e32 v12, v6, v12
	v_add_f32_e32 v6, v42, v9
	v_mul_f32_e32 v6, 0xbfb8aa3b, v6
	v_exp_f32_e32 v6, v6
	v_lshl_add_u64 v[8:9], s[2:3], 0, v[0:1]
	v_lshlrev_b64 v[8:9], 1, v[8:9]
	v_add_f32_e32 v15, 1.0, v6
	v_div_scale_f32 v16, s[2:3], v15, v15, 1.0
	v_rcp_f32_e32 v17, v16
	v_add_f32_e32 v6, v41, v7
	v_mul_f32_e32 v6, 0xbfb8aa3b, v6
	v_exp_f32_e32 v10, v6
	v_fma_f32 v6, -v16, v17, 1.0
	v_fmac_f32_e32 v17, v6, v17
	v_div_scale_f32 v18, vcc, 1.0, v15, 1.0
	v_mul_f32_e32 v19, v18, v17
	v_fma_f32 v6, -v16, v19, v18
	v_fmac_f32_e32 v19, v6, v17
	v_pk_add_f32 v[6:7], v[10:11], 1.0 op_sel_hi:[1,0]
	v_fma_f32 v16, -v16, v19, v18
	v_div_scale_f32 v10, s[2:3], v7, v7, 1.0
	v_rcp_f32_e32 v11, v10
	v_div_fmas_f32 v18, v16, v17, v19
	v_fma_f32 v16, -v10, v11, 1.0
	v_fmac_f32_e32 v11, v16, v11
	v_div_scale_f32 v16, vcc, 1.0, v7, 1.0
	v_mul_f32_e32 v17, v16, v11
	v_fma_f32 v19, -v10, v17, v16
	v_fmac_f32_e32 v17, v19, v11
	v_fma_f32 v10, -v10, v17, v16
	v_div_scale_f32 v16, s[2:3], v6, v6, 1.0
	v_rcp_f32_e32 v19, v16
	v_div_fmas_f32 v10, v10, v11, v17
	v_div_fixup_f32 v7, v10, v7, 1.0
	s_lshl_b64 s[2:3], s[94:95], 8
	v_fma_f32 v10, -v16, v19, 1.0
	v_fmac_f32_e32 v19, v10, v19
	v_div_scale_f32 v10, vcc, 1.0, v6, 1.0
	v_mul_f32_e32 v11, v10, v19
	v_fma_f32 v17, -v16, v11, v10
	v_fmac_f32_e32 v11, v17, v19
	v_fma_f32 v10, -v16, v11, v10
	v_div_fmas_f32 v10, v10, v19, v11
	v_div_fixup_f32 v6, v10, v6, 1.0
	v_pk_mul_f32 v[6:7], v[6:7], s[12:13] op_sel_hi:[1,0]
	s_add_i32 s94, s4, 0xfffffb46
	v_pk_mul_f32 v[6:7], v[14:15], v[6:7] op_sel_hi:[0,1]
	v_pk_add_f32 v[10:11], v[6:7], v[6:7]
	v_div_fixup_f32 v15, v18, v15, 1.0
	v_mul_f32_e32 v16, 0x3fb8aa3b, v11
	v_rndne_f32_e32 v16, v16
	v_fmamk_f32 v17, v16, 0xbf317218, v11
	v_fmac_f32_e32 v17, 0x3102e308, v16
	v_fmamk_f32 v19, v17, 0x395133b1, v230
	v_fmaak_f32 v19, v17, v19, 0x3c0887f9
	v_fmaak_f32 v19, v17, v19, 0x3d2aaa81
	v_cvt_i32_f32_e32 v20, v16
	v_fmaak_f32 v19, v17, v19, 0x3e2aaaab
	v_fma_f32 v19, v17, v19, 0.5
	v_mul_f32_e32 v19, v17, v19
	v_fmac_f32_e32 v17, v17, v19
	v_ldexp_f32 v19, 1.0, v20
	v_cmp_eq_f32_e32 vcc, s25, v16
	s_nop 1
	v_cndmask_b32_e32 v16, v19, v238, vcc
	v_add_f32_e32 v19, -1.0, v16
	v_fmac_f32_e32 v19, v16, v17
	v_add_f32_e32 v16, v19, v19
	v_cndmask_b32_e32 v16, v19, v16, vcc
	v_cmp_nlt_f32_e32 vcc, s70, v11
	s_nop 1
	v_cndmask_b32_e64 v16, v237, -v16, vcc
	v_mul_f32_e32 v17, 0x4f800000, v16
	v_cmp_gt_f32_e32 vcc, s26, v16
	s_nop 1
	v_cndmask_b32_e32 v19, v16, v17, vcc
	v_sqrt_f32_e32 v20, v19
	v_lshl_add_u64 v[16:17], s[6:7], 0, v[8:9]
	v_lshl_add_u64 v[8:9], s[22:23], 0, v[8:9]
	v_add_u32_e32 v18, -1, v20
	v_fma_f32 v21, -v18, v20, v19
	v_cmp_ge_f32_e64 s[8:9], 0, v21
	v_add_u32_e32 v21, 1, v20
	s_nop 0
	v_cndmask_b32_e64 v18, v20, v18, s[8:9]
	v_fma_f32 v20, -v21, v20, v19
	v_cmp_lt_f32_e64 s[8:9], 0, v20
	s_nop 1
	v_cndmask_b32_e64 v18, v18, v21, s[8:9]
	v_mul_f32_e32 v20, 0x37800000, v18
	v_cndmask_b32_e32 v18, v18, v20, vcc
	v_cmp_class_f32_e32 vcc, v19, v231
	s_nop 1
	v_cndmask_b32_e32 v18, v18, v19, vcc
	v_cmp_ngt_f32_e32 vcc, s27, v11
	s_nop 1
	v_cndmask_b32_e32 v11, 1.0, v18, vcc
	v_mul_f32_e32 v11, v11, v12
	v_bfe_u32 v12, v7, 16, 1
	v_add3_u32 v7, v7, v12, s69
	global_store_short_d16_hi v[16:17], v7, off
	v_mul_f32_e32 v7, 0x3fb8aa3b, v10
	v_rndne_f32_e32 v7, v7
	v_fmamk_f32 v12, v7, 0xbf317218, v10
	v_fmac_f32_e32 v12, 0x3102e308, v7
	v_fmamk_f32 v16, v12, 0x395133b1, v230
	v_fmaak_f32 v16, v12, v16, 0x3c0887f9
	v_fmaak_f32 v16, v12, v16, 0x3d2aaa81
	v_cvt_i32_f32_e32 v17, v7
	v_fmaak_f32 v16, v12, v16, 0x3e2aaaab
	v_fma_f32 v16, v12, v16, 0.5
	v_mul_f32_e32 v16, v12, v16
	v_fmac_f32_e32 v12, v12, v16
	v_ldexp_f32 v16, 1.0, v17
	v_cmp_eq_f32_e32 vcc, s25, v7
	s_nop 1
	v_cndmask_b32_e32 v7, v16, v238, vcc
	v_add_f32_e32 v16, -1.0, v7
	v_fmac_f32_e32 v16, v7, v12
	v_add_f32_e32 v7, v16, v16
	v_cndmask_b32_e32 v7, v16, v7, vcc
	v_cmp_nlt_f32_e32 vcc, s70, v10
	v_bfe_u32 v16, v11, 16, 1
	v_add3_u32 v11, v11, v16, s69
	v_cndmask_b32_e64 v7, v237, -v7, vcc
	v_mul_f32_e32 v12, 0x4f800000, v7
	v_cmp_gt_f32_e32 vcc, s26, v7
	global_store_short_d16_hi v[8:9], v11, off
	s_nop 0
	v_cndmask_b32_e32 v7, v7, v12, vcc
	v_sqrt_f32_e32 v12, v7
	s_nop 0
	v_add_u32_e32 v8, -1, v12
	v_fma_f32 v9, -v8, v12, v7
	v_cmp_ge_f32_e64 s[8:9], 0, v9
	v_add_u32_e32 v9, 1, v12
	v_fma_f32 v11, -v9, v12, v7
	v_cndmask_b32_e64 v8, v12, v8, s[8:9]
	v_cmp_lt_f32_e64 s[8:9], 0, v11
	s_nop 1
	v_cndmask_b32_e64 v8, v8, v9, s[8:9]
	v_mul_f32_e32 v9, 0x37800000, v8
	v_cndmask_b32_e32 v8, v8, v9, vcc
	v_cmp_class_f32_e32 vcc, v7, v231
	s_nop 1
	v_cndmask_b32_e32 v7, v8, v7, vcc
	v_cmp_ngt_f32_e32 vcc, s27, v10
	v_mul_f32_e32 v8, v15, v13
	s_nop 0
	v_cndmask_b32_e32 v7, 1.0, v7, vcc
	v_mul_f32_e32 v10, v7, v8
	v_bfe_u32 v7, v6, 16, 1
	v_add3_u32 v11, v6, v7, s69
	v_lshl_add_u64 v[6:7], s[2:3], 0, v[0:1]
	v_lshlrev_b64 v[6:7], 1, v[6:7]
	v_lshl_add_u64 v[8:9], s[6:7], 0, v[6:7]
	global_store_short_d16_hi v[8:9], v11, off
	v_bfe_u32 v8, v10, 16, 1
	v_add3_u32 v8, v10, v8, s69
	v_lshl_add_u64 v[6:7], s[22:23], 0, v[6:7]
	global_store_short_d16_hi v[6:7], v8, off
	v_div_scale_f32 v6, s[2:3], v4, v4, 1.0
	v_rcp_f32_e32 v10, v6
	v_exp_f32_e32 v7, v2
	s_lshl_b64 s[2:3], s[94:95], 8
	s_add_i32 s94, s4, 0xfffffb47
	v_fma_f32 v2, -v6, v10, 1.0
	v_fmac_f32_e32 v10, v2, v10
	v_div_scale_f32 v2, vcc, 1.0, v4, 1.0
	v_mul_f32_e32 v11, v2, v10
	v_fma_f32 v8, -v6, v11, v2
	v_fmac_f32_e32 v11, v8, v10
	ds_read2st64_b32 v[8:9], v40 offset0:24 offset1:28
	v_fma_f32 v2, -v6, v11, v2
	v_div_fmas_f32 v2, v2, v10, v11
	v_div_fixup_f32 v2, v2, v4, 1.0
	s_mul_i32 s4, s31, 0x9000
	s_waitcnt lgkmcnt(0)
	v_mul_f32_e32 v8, v2, v8
	v_add_f32_e32 v2, v42, v5
	v_mul_f32_e32 v2, 0xbfb8aa3b, v2
	v_exp_f32_e32 v2, v2
	v_lshl_add_u64 v[4:5], s[2:3], 0, v[0:1]
	v_lshlrev_b64 v[4:5], 1, v[4:5]
	v_add_f32_e32 v12, 1.0, v2
	v_div_scale_f32 v10, s[2:3], v12, v12, 1.0
	v_rcp_f32_e32 v11, v10
	v_add_f32_e32 v2, v41, v3
	v_mul_f32_e32 v2, 0xbfb8aa3b, v2
	v_exp_f32_e32 v6, v2
	v_fma_f32 v2, -v10, v11, 1.0
	v_fmac_f32_e32 v11, v2, v11
	v_div_scale_f32 v13, vcc, 1.0, v12, 1.0
	v_mul_f32_e32 v15, v13, v11
	v_fma_f32 v2, -v10, v15, v13
	v_fmac_f32_e32 v15, v2, v11
	v_pk_add_f32 v[2:3], v[6:7], 1.0 op_sel_hi:[1,0]
	v_fma_f32 v10, -v10, v15, v13
	v_div_scale_f32 v6, s[2:3], v3, v3, 1.0
	v_rcp_f32_e32 v7, v6
	v_div_fmas_f32 v13, v10, v11, v15
	v_div_fixup_f32 v12, v13, v12, 1.0
	v_fma_f32 v10, -v6, v7, 1.0
	v_fmac_f32_e32 v7, v10, v7
	v_div_scale_f32 v10, vcc, 1.0, v3, 1.0
	v_mul_f32_e32 v11, v10, v7
	v_fma_f32 v15, -v6, v11, v10
	v_fmac_f32_e32 v11, v15, v7
	v_fma_f32 v6, -v6, v11, v10
	v_div_scale_f32 v10, s[2:3], v2, v2, 1.0
	v_rcp_f32_e32 v15, v10
	v_div_fmas_f32 v6, v6, v7, v11
	v_div_fixup_f32 v3, v6, v3, 1.0
	s_lshl_b64 s[2:3], s[94:95], 8
	v_fma_f32 v6, -v10, v15, 1.0
	v_fmac_f32_e32 v15, v6, v15
	v_div_scale_f32 v6, vcc, 1.0, v2, 1.0
	v_mul_f32_e32 v7, v6, v15
	v_fma_f32 v11, -v10, v7, v6
	v_fmac_f32_e32 v7, v11, v15
	v_fma_f32 v6, -v10, v7, v6
	v_div_fmas_f32 v6, v6, v15, v7
	v_div_fixup_f32 v2, v6, v2, 1.0
	v_pk_mul_f32 v[2:3], v[2:3], s[12:13] op_sel_hi:[1,0]
	s_nop 0
	v_pk_mul_f32 v[2:3], v[14:15], v[2:3] op_sel_hi:[0,1]
	v_pk_add_f32 v[6:7], v[2:3], v[2:3]
	s_nop 0
	v_mul_f32_e32 v10, 0x3fb8aa3b, v7
	v_rndne_f32_e32 v10, v10
	v_fmamk_f32 v11, v10, 0xbf317218, v7
	v_fmac_f32_e32 v11, 0x3102e308, v10
	v_fmamk_f32 v14, v11, 0x395133b1, v230
	v_fmaak_f32 v14, v11, v14, 0x3c0887f9
	v_fmaak_f32 v14, v11, v14, 0x3d2aaa81
	v_cvt_i32_f32_e32 v15, v10
	v_fmaak_f32 v14, v11, v14, 0x3e2aaaab
	v_fma_f32 v14, v11, v14, 0.5
	v_mul_f32_e32 v14, v11, v14
	v_fmac_f32_e32 v11, v11, v14
	v_ldexp_f32 v14, 1.0, v15
	v_cmp_eq_f32_e32 vcc, s25, v10
	s_nop 1
	v_cndmask_b32_e32 v10, v14, v238, vcc
	v_add_f32_e32 v14, -1.0, v10
	v_fmac_f32_e32 v14, v10, v11
	v_add_f32_e32 v10, v14, v14
	v_cndmask_b32_e32 v10, v14, v10, vcc
	v_cmp_nlt_f32_e32 vcc, s70, v7
	s_nop 1
	v_cndmask_b32_e64 v10, v237, -v10, vcc
	v_mul_f32_e32 v11, 0x4f800000, v10
	v_cmp_gt_f32_e32 vcc, s26, v10
	s_nop 1
	v_cndmask_b32_e32 v14, v10, v11, vcc
	v_sqrt_f32_e32 v15, v14
	v_lshl_add_u64 v[10:11], s[6:7], 0, v[4:5]
	v_lshl_add_u64 v[4:5], s[22:23], 0, v[4:5]
	v_add_u32_e32 v13, -1, v15
	v_fma_f32 v16, -v13, v15, v14
	v_cmp_ge_f32_e64 s[8:9], 0, v16
	v_add_u32_e32 v16, 1, v15
	s_nop 0
	v_cndmask_b32_e64 v13, v15, v13, s[8:9]
	v_fma_f32 v15, -v16, v15, v14
	v_cmp_lt_f32_e64 s[8:9], 0, v15
	s_nop 1
	v_cndmask_b32_e64 v13, v13, v16, s[8:9]
	v_mul_f32_e32 v15, 0x37800000, v13
	v_cndmask_b32_e32 v13, v13, v15, vcc
	v_cmp_class_f32_e32 vcc, v14, v231
	s_nop 1
	v_cndmask_b32_e32 v13, v13, v14, vcc
	v_cmp_ngt_f32_e32 vcc, s27, v7
	s_nop 1
	v_cndmask_b32_e32 v7, 1.0, v13, vcc
	v_mul_f32_e32 v7, v7, v8
	v_bfe_u32 v8, v3, 16, 1
	v_add3_u32 v3, v3, v8, s69
	global_store_short_d16_hi v[10:11], v3, off
	v_mul_f32_e32 v3, 0x3fb8aa3b, v6
	v_rndne_f32_e32 v3, v3
	v_fmamk_f32 v8, v3, 0xbf317218, v6
	v_fmac_f32_e32 v8, 0x3102e308, v3
	v_fmamk_f32 v10, v8, 0x395133b1, v230
	v_fmaak_f32 v10, v8, v10, 0x3c0887f9
	v_fmaak_f32 v10, v8, v10, 0x3d2aaa81
	v_cvt_i32_f32_e32 v11, v3
	v_fmaak_f32 v10, v8, v10, 0x3e2aaaab
	v_fma_f32 v10, v8, v10, 0.5
	v_mul_f32_e32 v10, v8, v10
	v_fmac_f32_e32 v8, v8, v10
	v_ldexp_f32 v10, 1.0, v11
	v_cmp_eq_f32_e32 vcc, s25, v3
	s_nop 1
	v_cndmask_b32_e32 v3, v10, v238, vcc
	v_add_f32_e32 v10, -1.0, v3
	v_fmac_f32_e32 v10, v3, v8
	v_add_f32_e32 v3, v10, v10
	v_cndmask_b32_e32 v3, v10, v3, vcc
	v_cmp_nlt_f32_e32 vcc, s70, v6
	v_bfe_u32 v10, v7, 16, 1
	v_add3_u32 v7, v7, v10, s69
	v_cndmask_b32_e64 v3, v237, -v3, vcc
	v_mul_f32_e32 v8, 0x4f800000, v3
	v_cmp_gt_f32_e32 vcc, s26, v3
	global_store_short_d16_hi v[4:5], v7, off
	s_nop 0
	v_cndmask_b32_e32 v3, v3, v8, vcc
	v_sqrt_f32_e32 v8, v3
	s_nop 0
	v_add_u32_e32 v4, -1, v8
	v_fma_f32 v5, -v4, v8, v3
	v_cmp_ge_f32_e64 s[8:9], 0, v5
	v_add_u32_e32 v5, 1, v8
	v_fma_f32 v7, -v5, v8, v3
	v_cndmask_b32_e64 v4, v8, v4, s[8:9]
	v_cmp_lt_f32_e64 s[8:9], 0, v7
	s_nop 1
	v_cndmask_b32_e64 v4, v4, v5, s[8:9]
	v_mul_f32_e32 v5, 0x37800000, v4
	v_cndmask_b32_e32 v4, v4, v5, vcc
	v_cmp_class_f32_e32 vcc, v3, v231
	s_nop 1
	v_cndmask_b32_e32 v3, v4, v3, vcc
	v_cmp_ngt_f32_e32 vcc, s27, v6
	v_mul_f32_e32 v4, v12, v9
	s_nop 0
	v_cndmask_b32_e32 v3, 1.0, v3, vcc
	v_mul_f32_e32 v6, v3, v4
	v_bfe_u32 v3, v2, 16, 1
	v_add3_u32 v7, v2, v3, s69
	v_lshl_add_u64 v[2:3], s[2:3], 0, v[0:1]
	v_readlane_b32 s2, v253, 38
	v_lshlrev_b64 v[2:3], 1, v[2:3]
	s_add_u32 s2, s2, s10
	v_readlane_b32 s3, v253, 39
	v_lshl_add_u64 v[4:5], s[6:7], 0, v[2:3]
	s_addc_u32 s3, s3, s5
	global_store_short_d16_hi v[4:5], v7, off
	v_bfe_u32 v4, v6, 16, 1
	s_add_u32 s4, s28, s4
	v_add3_u32 v4, v6, v4, s69
	v_lshl_add_u64 v[2:3], s[22:23], 0, v[2:3]
	s_addc_u32 s5, s29, 0
	global_store_short_d16_hi v[2:3], v4, off
	v_lshl_add_u64 v[2:3], v[0:1], 1, s[4:5]
	s_mov_b32 s4, 0xffaaf000
	v_add_co_u32_e32 v4, vcc, s4, v2
	v_lshl_add_u64 v[0:1], v[0:1], 2, s[2:3]
	s_nop 0
	v_addc_co_u32_e32 v5, vcc, -1, v3, vcc
	v_add_co_u32_e32 v6, vcc, 0xffab0000, v2
	s_nop 1
	v_addc_co_u32_e32 v7, vcc, -1, v3, vcc
	v_add_co_u32_e32 v2, vcc, 0xffab1000, v2
	global_load_ushort v4, v[4:5], off offset:-3072
	s_nop 0
	global_load_ushort v5, v[6:7], off offset:-2560
	v_addc_co_u32_e32 v3, vcc, -1, v3, vcc
	global_load_ushort v2, v[2:3], off offset:-2048
	s_waitcnt vmcnt(2)
	v_lshlrev_b32_e32 v3, 16, v4
	global_store_dword v[0:1], v3, off
	s_waitcnt vmcnt(2)
	v_lshlrev_b32_e32 v3, 16, v5
	global_store_dword v[0:1], v3, off offset:1024
	s_waitcnt vmcnt(2)
	v_lshlrev_b32_e32 v2, 16, v2
	global_store_dword v[0:1], v2, off offset:2048

.LBB0_216:
	v_lshl_add_u64 v[38:39], v[2:3], 0, s[2:3]
	v_lshl_add_u64 v[88:89], v[4:5], 0, s[2:3]
	global_load_dword v84, v[38:39], off
	global_load_dword v86, v[88:89], off
	global_load_dword v132, v[38:39], off offset:256
	global_load_dword v133, v[88:89], off offset:256
	global_load_dword v134, v[38:39], off offset:512
	global_load_dword v135, v[88:89], off offset:512
	global_load_dword v136, v[38:39], off offset:768
	global_load_dword v137, v[88:89], off offset:768
	global_load_dword v138, v[38:39], off offset:1024
	global_load_dword v139, v[88:89], off offset:1024
	global_load_dword v140, v[38:39], off offset:1280
	global_load_dword v141, v[88:89], off offset:1280
	global_load_dword v142, v[38:39], off offset:1536
	global_load_dword v143, v[88:89], off offset:1536
	global_load_dword v144, v[38:39], off offset:1792
	global_load_dword v145, v[88:89], off offset:1792
	v_mov_b32_e32 v120, s8
	ds_read_b128 v[44:47], v120
	ds_read_b128 v[48:51], v120 offset:16
	ds_read_b128 v[52:55], v120 offset:1024
	s_add_i32 s8, s8, 32
	s_add_u32 s2, s2, 0x800
	s_waitcnt lgkmcnt(2)
	v_mov_b32_e32 v56, v44
	s_addc_u32 s3, s3, 0
	s_waitcnt lgkmcnt(0)
	v_mov_b32_e32 v57, v52
	v_mov_b32_e32 v52, v45
	s_cmpk_eq_i32 s2, 0x4000
	s_waitcnt vmcnt(15)
	v_pk_fma_f32 v[90:91], v[84:85], v[56:57], v[36:37] op_sel_hi:[0,1,1]
	s_waitcnt vmcnt(14)
	v_pk_fma_f32 v[92:93], v[86:87], v[56:57], v[34:35] op_sel_hi:[0,1,1]
	ds_read_b128 v[34:37], v120 offset:2048
	ds_read_b128 v[56:59], v120 offset:3072
	s_waitcnt lgkmcnt(1)
	v_mov_b32_e32 v60, v34
	s_waitcnt lgkmcnt(0)
	v_mov_b32_e32 v61, v56
	v_pk_fma_f32 v[94:95], v[84:85], v[60:61], v[32:33] op_sel_hi:[0,1,1]
	v_pk_fma_f32 v[96:97], v[86:87], v[60:61], v[30:31] op_sel_hi:[0,1,1]
	ds_read_b128 v[30:33], v120 offset:4096
	ds_read_b128 v[60:63], v120 offset:5120
	v_mov_b32_e32 v56, v35
	s_waitcnt lgkmcnt(1)
	v_mov_b32_e32 v64, v30
	s_waitcnt lgkmcnt(0)
	v_mov_b32_e32 v65, v60
	v_pk_fma_f32 v[98:99], v[84:85], v[64:65], v[28:29] op_sel_hi:[0,1,1]
	v_pk_fma_f32 v[100:101], v[86:87], v[64:65], v[26:27] op_sel_hi:[0,1,1]
	ds_read_b128 v[26:29], v120 offset:6144
	ds_read_b128 v[64:67], v120 offset:7168
	v_mov_b32_e32 v60, v31
	s_waitcnt lgkmcnt(1)
	v_mov_b32_e32 v68, v26
	s_waitcnt lgkmcnt(0)
	v_mov_b32_e32 v69, v64
	v_pk_fma_f32 v[102:103], v[84:85], v[68:69], v[24:25] op_sel_hi:[0,1,1]
	v_pk_fma_f32 v[104:105], v[86:87], v[68:69], v[22:23] op_sel_hi:[0,1,1]
	ds_read_b128 v[22:25], v120 offset:8192
	ds_read_b128 v[68:71], v120 offset:9216
	v_mov_b32_e32 v64, v27
	s_waitcnt lgkmcnt(1)
	v_mov_b32_e32 v72, v22
	s_waitcnt lgkmcnt(0)
	v_mov_b32_e32 v73, v68
	v_pk_fma_f32 v[106:107], v[84:85], v[72:73], v[20:21] op_sel_hi:[0,1,1]
	v_pk_fma_f32 v[108:109], v[86:87], v[72:73], v[18:19] op_sel_hi:[0,1,1]
	ds_read_b128 v[18:21], v120 offset:10240
	ds_read_b128 v[72:75], v120 offset:11264
	v_mov_b32_e32 v68, v23
	s_waitcnt lgkmcnt(1)
	v_mov_b32_e32 v76, v18
	s_waitcnt lgkmcnt(0)
	v_mov_b32_e32 v77, v72
	v_pk_fma_f32 v[110:111], v[84:85], v[76:77], v[16:17] op_sel_hi:[0,1,1]
	v_pk_fma_f32 v[112:113], v[86:87], v[76:77], v[14:15] op_sel_hi:[0,1,1]
	ds_read_b128 v[14:17], v120 offset:12288
	ds_read_b128 v[76:79], v120 offset:13312
	v_mov_b32_e32 v72, v19
	s_waitcnt lgkmcnt(1)
	v_mov_b32_e32 v80, v14
	s_waitcnt lgkmcnt(0)
	v_mov_b32_e32 v81, v76
	v_pk_fma_f32 v[114:115], v[84:85], v[80:81], v[12:13] op_sel_hi:[0,1,1]
	v_pk_fma_f32 v[116:117], v[86:87], v[80:81], v[10:11] op_sel_hi:[0,1,1]
	ds_read_b128 v[10:13], v120 offset:14336
	ds_read_b128 v[80:83], v120 offset:15360
	v_mov_b32_e32 v76, v15
	s_waitcnt lgkmcnt(1)
	v_mov_b32_e32 v118, v10
	s_waitcnt vmcnt(13)
	v_mov_b32_e32 v10, v132
	s_waitcnt vmcnt(12)
	v_mov_b32_e32 v14, v133
	s_waitcnt lgkmcnt(0)
	v_mov_b32_e32 v119, v80
	v_pk_fma_f32 v[8:9], v[84:85], v[118:119], v[8:9] op_sel_hi:[0,1,1]
	v_pk_fma_f32 v[6:7], v[86:87], v[118:119], v[6:7] op_sel_hi:[0,1,1]
	v_mov_b32_e32 v80, v11
	v_pk_fma_f32 v[44:45], v[10:11], v[52:53], v[90:91] op_sel_hi:[0,1,1]
	v_pk_fma_f32 v[52:53], v[14:15], v[52:53], v[92:93] op_sel_hi:[0,1,1]
	v_pk_fma_f32 v[34:35], v[10:11], v[56:57], v[94:95] op_sel_hi:[0,1,1]
	v_pk_fma_f32 v[56:57], v[14:15], v[56:57], v[96:97] op_sel_hi:[0,1,1]
	v_pk_fma_f32 v[30:31], v[10:11], v[60:61], v[98:99] op_sel_hi:[0,1,1]
	v_pk_fma_f32 v[60:61], v[14:15], v[60:61], v[100:101] op_sel_hi:[0,1,1]
	v_pk_fma_f32 v[26:27], v[10:11], v[64:65], v[102:103] op_sel_hi:[0,1,1]
	v_pk_fma_f32 v[64:65], v[14:15], v[64:65], v[104:105] op_sel_hi:[0,1,1]
	v_pk_fma_f32 v[22:23], v[10:11], v[68:69], v[106:107] op_sel_hi:[0,1,1]
	v_pk_fma_f32 v[68:69], v[14:15], v[68:69], v[108:109] op_sel_hi:[0,1,1]
	v_pk_fma_f32 v[18:19], v[10:11], v[72:73], v[110:111] op_sel_hi:[0,1,1]
	v_pk_fma_f32 v[72:73], v[14:15], v[72:73], v[112:113] op_sel_hi:[0,1,1]
	v_pk_fma_f32 v[84:85], v[10:11], v[76:77], v[114:115] op_sel_hi:[0,1,1]
	v_pk_fma_f32 v[76:77], v[14:15], v[76:77], v[116:117] op_sel_hi:[0,1,1]
	v_pk_fma_f32 v[8:9], v[10:11], v[80:81], v[8:9] op_sel_hi:[0,1,1]
	v_pk_fma_f32 v[6:7], v[14:15], v[80:81], v[6:7] op_sel_hi:[0,1,1]
	s_waitcnt vmcnt(11)
	v_mov_b32_e32 v10, v134
	s_waitcnt vmcnt(10)
	v_mov_b32_e32 v14, v135
	v_mov_b32_e32 v80, v46
	v_mov_b32_e32 v81, v54
	v_mov_b32_e32 v54, v47
	v_pk_fma_f32 v[44:45], v[10:11], v[80:81], v[44:45] op_sel_hi:[0,1,1]
	v_pk_fma_f32 v[52:53], v[14:15], v[80:81], v[52:53] op_sel_hi:[0,1,1]
	v_mov_b32_e32 v80, v36
	v_mov_b32_e32 v81, v58
	v_pk_fma_f32 v[34:35], v[10:11], v[80:81], v[34:35] op_sel_hi:[0,1,1]
	v_pk_fma_f32 v[56:57], v[14:15], v[80:81], v[56:57] op_sel_hi:[0,1,1]
	v_mov_b32_e32 v80, v32
	v_mov_b32_e32 v81, v62
	v_pk_fma_f32 v[30:31], v[10:11], v[80:81], v[30:31] op_sel_hi:[0,1,1]
	v_pk_fma_f32 v[60:61], v[14:15], v[80:81], v[60:61] op_sel_hi:[0,1,1]
	v_mov_b32_e32 v80, v28
	v_mov_b32_e32 v81, v66
	v_pk_fma_f32 v[26:27], v[10:11], v[80:81], v[26:27] op_sel_hi:[0,1,1]
	v_pk_fma_f32 v[64:65], v[14:15], v[80:81], v[64:65] op_sel_hi:[0,1,1]
	v_mov_b32_e32 v80, v24
	v_mov_b32_e32 v81, v70
	v_pk_fma_f32 v[22:23], v[10:11], v[80:81], v[22:23] op_sel_hi:[0,1,1]
	v_pk_fma_f32 v[68:69], v[14:15], v[80:81], v[68:69] op_sel_hi:[0,1,1]
	v_mov_b32_e32 v80, v20
	v_mov_b32_e32 v81, v74
	v_pk_fma_f32 v[18:19], v[10:11], v[80:81], v[18:19] op_sel_hi:[0,1,1]
	v_pk_fma_f32 v[72:73], v[14:15], v[80:81], v[72:73] op_sel_hi:[0,1,1]
	v_mov_b32_e32 v80, v16
	v_mov_b32_e32 v81, v78
	v_pk_fma_f32 v[84:85], v[10:11], v[80:81], v[84:85] op_sel_hi:[0,1,1]
	v_pk_fma_f32 v[76:77], v[14:15], v[80:81], v[76:77] op_sel_hi:[0,1,1]
	v_mov_b32_e32 v80, v12
	v_mov_b32_e32 v81, v82
	v_pk_fma_f32 v[8:9], v[10:11], v[80:81], v[8:9] op_sel_hi:[0,1,1]
	s_waitcnt vmcnt(9)
	v_mov_b32_e32 v10, v136
	s_waitcnt vmcnt(8)
	v_mov_b32_e32 v12, v137
	s_waitcnt vmcnt(7)
	v_mov_b32_e32 v94, v138
	s_waitcnt vmcnt(6)
	v_mov_b32_e32 v96, v139
	v_pk_fma_f32 v[6:7], v[14:15], v[80:81], v[6:7] op_sel_hi:[0,1,1]
	v_mov_b32_e32 v82, v13
	v_mov_b32_e32 v58, v37
	v_mov_b32_e32 v62, v33
	v_mov_b32_e32 v66, v29
	v_mov_b32_e32 v70, v25
	v_mov_b32_e32 v74, v21
	v_mov_b32_e32 v78, v17
	v_pk_fma_f32 v[90:91], v[10:11], v[82:83], v[8:9] op_sel_hi:[0,1,1]
	v_pk_fma_f32 v[92:93], v[12:13], v[82:83], v[6:7] op_sel_hi:[0,1,1]
	ds_read_b128 v[6:9], v120 offset:1040
	v_pk_fma_f32 v[14:15], v[10:11], v[54:55], v[44:45] op_sel_hi:[0,1,1]
	v_pk_fma_f32 v[44:45], v[12:13], v[54:55], v[52:53] op_sel_hi:[0,1,1]
	v_pk_fma_f32 v[34:35], v[10:11], v[58:59], v[34:35] op_sel_hi:[0,1,1]
	v_pk_fma_f32 v[30:31], v[10:11], v[62:63], v[30:31] op_sel_hi:[0,1,1]
	v_pk_fma_f32 v[26:27], v[10:11], v[66:67], v[26:27] op_sel_hi:[0,1,1]
	v_pk_fma_f32 v[28:29], v[12:13], v[66:67], v[64:65] op_sel_hi:[0,1,1]
	v_pk_fma_f32 v[64:65], v[10:11], v[70:71], v[22:23] op_sel_hi:[0,1,1]
	v_pk_fma_f32 v[80:81], v[10:11], v[74:75], v[18:19] op_sel_hi:[0,1,1]
	v_pk_fma_f32 v[84:85], v[10:11], v[78:79], v[84:85] op_sel_hi:[0,1,1]
	v_mov_b32_e32 v10, v48
	s_waitcnt lgkmcnt(0)
	v_mov_b32_e32 v11, v6
	v_pk_fma_f32 v[36:37], v[12:13], v[58:59], v[56:57] op_sel_hi:[0,1,1]
	v_pk_fma_f32 v[32:33], v[12:13], v[62:63], v[60:61] op_sel_hi:[0,1,1]
	v_pk_fma_f32 v[66:67], v[12:13], v[70:71], v[68:69] op_sel_hi:[0,1,1]
	v_pk_fma_f32 v[72:73], v[12:13], v[74:75], v[72:73] op_sel_hi:[0,1,1]
	v_pk_fma_f32 v[86:87], v[12:13], v[78:79], v[76:77] op_sel_hi:[0,1,1]
	v_pk_fma_f32 v[98:99], v[94:95], v[10:11], v[14:15] op_sel_hi:[0,1,1]
	v_pk_fma_f32 v[100:101], v[96:97], v[10:11], v[44:45] op_sel_hi:[0,1,1]
	ds_read_b128 v[10:13], v120 offset:2064
	ds_read_b128 v[14:17], v120 offset:3088
	v_mov_b32_e32 v6, v49
	s_waitcnt lgkmcnt(1)
	v_mov_b32_e32 v18, v10
	s_waitcnt lgkmcnt(0)
	v_mov_b32_e32 v19, v14
	v_pk_fma_f32 v[34:35], v[94:95], v[18:19], v[34:35] op_sel_hi:[0,1,1]
	v_pk_fma_f32 v[36:37], v[96:97], v[18:19], v[36:37] op_sel_hi:[0,1,1]
	ds_read_b128 v[18:21], v120 offset:4112
	ds_read_b128 v[22:25], v120 offset:5136
	v_mov_b32_e32 v14, v11
	s_waitcnt lgkmcnt(1)
	v_mov_b32_e32 v44, v18
	s_waitcnt lgkmcnt(0)
	v_mov_b32_e32 v45, v22
	v_pk_fma_f32 v[30:31], v[94:95], v[44:45], v[30:31] op_sel_hi:[0,1,1]
	v_pk_fma_f32 v[32:33], v[96:97], v[44:45], v[32:33] op_sel_hi:[0,1,1]
	ds_read_b128 v[44:47], v120 offset:6160
	ds_read_b128 v[52:55], v120 offset:7184
	v_mov_b32_e32 v22, v19
	s_waitcnt lgkmcnt(1)
	v_mov_b32_e32 v56, v44
	s_waitcnt lgkmcnt(0)
	v_mov_b32_e32 v57, v52
	v_pk_fma_f32 v[26:27], v[94:95], v[56:57], v[26:27] op_sel_hi:[0,1,1]
	v_pk_fma_f32 v[28:29], v[96:97], v[56:57], v[28:29] op_sel_hi:[0,1,1]
	ds_read_b128 v[56:59], v120 offset:8208
	ds_read_b128 v[60:63], v120 offset:9232
	v_mov_b32_e32 v52, v45
	s_waitcnt lgkmcnt(1)
	v_mov_b32_e32 v68, v56
	s_waitcnt lgkmcnt(0)
	v_mov_b32_e32 v69, v60
	v_pk_fma_f32 v[102:103], v[94:95], v[68:69], v[64:65] op_sel_hi:[0,1,1]
	v_pk_fma_f32 v[104:105], v[96:97], v[68:69], v[66:67] op_sel_hi:[0,1,1]
	ds_read_b128 v[64:67], v120 offset:10256
	ds_read_b128 v[68:71], v120 offset:11280
	v_mov_b32_e32 v60, v57
	s_waitcnt lgkmcnt(1)
	v_mov_b32_e32 v74, v64
	s_waitcnt lgkmcnt(0)
	v_mov_b32_e32 v75, v68
	v_pk_fma_f32 v[106:107], v[94:95], v[74:75], v[80:81] op_sel_hi:[0,1,1]
	v_pk_fma_f32 v[108:109], v[96:97], v[74:75], v[72:73] op_sel_hi:[0,1,1]
	ds_read_b128 v[72:75], v120 offset:12304
	ds_read_b128 v[76:79], v120 offset:13328
	v_mov_b32_e32 v68, v65
	s_waitcnt lgkmcnt(1)
	v_mov_b32_e32 v80, v72
	s_waitcnt lgkmcnt(0)
	v_mov_b32_e32 v81, v76
	v_pk_fma_f32 v[110:111], v[94:95], v[80:81], v[84:85] op_sel_hi:[0,1,1]
	v_pk_fma_f32 v[112:113], v[96:97], v[80:81], v[86:87] op_sel_hi:[0,1,1]
	ds_read_b128 v[80:83], v120 offset:14352
	ds_read_b128 v[84:87], v120 offset:15376
	s_waitcnt vmcnt(5)
	v_mov_b32_e32 v10, v140
	s_waitcnt vmcnt(4)
	v_mov_b32_e32 v18, v141
	v_mov_b32_e32 v76, v73
	v_mov_b32_e32 v72, v50
	v_mov_b32_e32 v73, v8
	s_waitcnt lgkmcnt(1)
	v_mov_b32_e32 v114, v80
	s_waitcnt lgkmcnt(0)
	v_mov_b32_e32 v115, v84
	v_pk_fma_f32 v[90:91], v[94:95], v[114:115], v[90:91] op_sel_hi:[0,1,1]
	v_pk_fma_f32 v[92:93], v[96:97], v[114:115], v[92:93] op_sel_hi:[0,1,1]
	v_mov_b32_e32 v84, v81
	v_mov_b32_e32 v8, v51
	v_pk_fma_f32 v[26:27], v[10:11], v[52:53], v[26:27] op_sel_hi:[0,1,1]
	v_pk_fma_f32 v[28:29], v[18:19], v[52:53], v[28:29] op_sel_hi:[0,1,1]
	v_pk_fma_f32 v[44:45], v[10:11], v[68:69], v[106:107] op_sel_hi:[0,1,1]
	v_pk_fma_f32 v[52:53], v[18:19], v[68:69], v[108:109] op_sel_hi:[0,1,1]
	s_waitcnt vmcnt(3)
	v_mov_b32_e32 v64, v142
	s_waitcnt vmcnt(2)
	v_mov_b32_e32 v68, v143
	v_pk_fma_f32 v[48:49], v[10:11], v[6:7], v[98:99] op_sel_hi:[0,1,1]
	v_pk_fma_f32 v[6:7], v[18:19], v[6:7], v[100:101] op_sel_hi:[0,1,1]
	v_pk_fma_f32 v[34:35], v[10:11], v[14:15], v[34:35] op_sel_hi:[0,1,1]
	v_pk_fma_f32 v[14:15], v[18:19], v[14:15], v[36:37] op_sel_hi:[0,1,1]
	v_pk_fma_f32 v[30:31], v[10:11], v[22:23], v[30:31] op_sel_hi:[0,1,1]
	v_pk_fma_f32 v[22:23], v[18:19], v[22:23], v[32:33] op_sel_hi:[0,1,1]
	v_pk_fma_f32 v[32:33], v[10:11], v[60:61], v[102:103] op_sel_hi:[0,1,1]
	v_pk_fma_f32 v[36:37], v[18:19], v[60:61], v[104:105] op_sel_hi:[0,1,1]
	v_pk_fma_f32 v[56:57], v[10:11], v[76:77], v[110:111] op_sel_hi:[0,1,1]
	v_pk_fma_f32 v[60:61], v[18:19], v[76:77], v[112:113] op_sel_hi:[0,1,1]
	v_pk_fma_f32 v[10:11], v[10:11], v[84:85], v[90:91] op_sel_hi:[0,1,1]
	v_pk_fma_f32 v[18:19], v[18:19], v[84:85], v[92:93] op_sel_hi:[0,1,1]
	v_pk_fma_f32 v[48:49], v[64:65], v[72:73], v[48:49] op_sel_hi:[0,1,1]
	v_pk_fma_f32 v[6:7], v[68:69], v[72:73], v[6:7] op_sel_hi:[0,1,1]
	v_mov_b32_e32 v72, v12
	v_mov_b32_e32 v73, v16
	v_pk_fma_f32 v[76:77], v[64:65], v[72:73], v[34:35] op_sel_hi:[0,1,1]
	v_mov_b32_e32 v34, v20
	v_mov_b32_e32 v35, v24
	v_pk_fma_f32 v[14:15], v[68:69], v[72:73], v[14:15] op_sel_hi:[0,1,1]
	v_pk_fma_f32 v[72:73], v[64:65], v[34:35], v[30:31] op_sel_hi:[0,1,1]
	v_mov_b32_e32 v30, v46
	s_waitcnt vmcnt(1)
	v_mov_b32_e32 v38, v144
	s_nop 0
	s_waitcnt vmcnt(0)
	v_mov_b32_e32 v46, v145
	v_mov_b32_e32 v31, v54
	v_pk_fma_f32 v[80:81], v[64:65], v[30:31], v[26:27] op_sel_hi:[0,1,1]
	v_mov_b32_e32 v26, v58
	v_mov_b32_e32 v27, v62
	v_pk_fma_f32 v[90:91], v[64:65], v[26:27], v[32:33] op_sel_hi:[0,1,1]
	v_pk_fma_f32 v[92:93], v[68:69], v[26:27], v[36:37] op_sel_hi:[0,1,1]
	v_mov_b32_e32 v26, v66
	v_mov_b32_e32 v27, v70
	v_pk_fma_f32 v[44:45], v[64:65], v[26:27], v[44:45] op_sel_hi:[0,1,1]
	v_pk_fma_f32 v[52:53], v[68:69], v[26:27], v[52:53] op_sel_hi:[0,1,1]
	v_mov_b32_e32 v26, v74
	v_mov_b32_e32 v27, v78
	v_pk_fma_f32 v[56:57], v[64:65], v[26:27], v[56:57] op_sel_hi:[0,1,1]
	v_pk_fma_f32 v[60:61], v[68:69], v[26:27], v[60:61] op_sel_hi:[0,1,1]
	v_mov_b32_e32 v26, v82
	v_mov_b32_e32 v27, v86
	v_pk_fma_f32 v[22:23], v[68:69], v[34:35], v[22:23] op_sel_hi:[0,1,1]
	v_pk_fma_f32 v[84:85], v[68:69], v[30:31], v[28:29] op_sel_hi:[0,1,1]
	v_pk_fma_f32 v[64:65], v[64:65], v[26:27], v[10:11] op_sel_hi:[0,1,1]
	v_pk_fma_f32 v[68:69], v[68:69], v[26:27], v[18:19] op_sel_hi:[0,1,1]
	v_mov_b32_e32 v16, v13
	v_mov_b32_e32 v24, v21
	v_mov_b32_e32 v54, v47
	v_mov_b32_e32 v62, v59
	v_mov_b32_e32 v70, v67
	v_mov_b32_e32 v78, v75
	v_mov_b32_e32 v86, v83
	v_pk_fma_f32 v[36:37], v[38:39], v[8:9], v[48:49] op_sel_hi:[0,1,1]
	v_pk_fma_f32 v[34:35], v[46:47], v[8:9], v[6:7] op_sel_hi:[0,1,1]
	v_pk_fma_f32 v[32:33], v[38:39], v[16:17], v[76:77] op_sel_hi:[0,1,1]
	v_pk_fma_f32 v[30:31], v[46:47], v[16:17], v[14:15] op_sel_hi:[0,1,1]
	v_pk_fma_f32 v[28:29], v[38:39], v[24:25], v[72:73] op_sel_hi:[0,1,1]
	v_pk_fma_f32 v[26:27], v[46:47], v[24:25], v[22:23] op_sel_hi:[0,1,1]
	v_pk_fma_f32 v[24:25], v[38:39], v[54:55], v[80:81] op_sel_hi:[0,1,1]
	v_pk_fma_f32 v[22:23], v[46:47], v[54:55], v[84:85] op_sel_hi:[0,1,1]
	v_pk_fma_f32 v[20:21], v[38:39], v[62:63], v[90:91] op_sel_hi:[0,1,1]
	v_pk_fma_f32 v[18:19], v[46:47], v[62:63], v[92:93] op_sel_hi:[0,1,1]
	v_pk_fma_f32 v[16:17], v[38:39], v[70:71], v[44:45] op_sel_hi:[0,1,1]
	v_pk_fma_f32 v[14:15], v[46:47], v[70:71], v[52:53] op_sel_hi:[0,1,1]
	v_pk_fma_f32 v[12:13], v[38:39], v[78:79], v[56:57] op_sel_hi:[0,1,1]
	v_pk_fma_f32 v[10:11], v[46:47], v[78:79], v[60:61] op_sel_hi:[0,1,1]
	v_pk_fma_f32 v[8:9], v[38:39], v[86:87], v[64:65] op_sel_hi:[0,1,1]
	v_pk_fma_f32 v[6:7], v[46:47], v[86:87], v[68:69] op_sel_hi:[0,1,1]
	s_cbranch_scc0 .LBB0_216
	s_cmp_lt_i32 s15, s10
	s_cbranch_scc0 .LBB0_233
	v_add_f32_e32 v36, v41, v36
	v_mul_f32_e32 v36, 0xbfb8aa3b, v36
	v_exp_f32_e32 v36, v36
	v_add_f32_e32 v34, v42, v34
	v_mul_f32_e32 v34, 0xbfb8aa3b, v34
	v_exp_f32_e32 v34, v34
	v_add_f32_e32 v36, 1.0, v36
	v_div_scale_f32 v38, s[2:3], v36, v36, 1.0
	v_rcp_f32_e32 v39, v38
	v_add_f32_e32 v34, 1.0, v34
	v_fma_f32 v44, -v38, v39, 1.0
	v_fmac_f32_e32 v39, v44, v39
	v_div_scale_f32 v44, vcc, 1.0, v36, 1.0
	v_mul_f32_e32 v45, v44, v39
	v_fma_f32 v46, -v38, v45, v44
	v_fmac_f32_e32 v45, v46, v39
	v_fma_f32 v38, -v38, v45, v44
	v_div_fmas_f32 v38, v38, v39, v45
	v_div_fixup_f32 v36, v38, v36, 1.0
	v_div_scale_f32 v38, s[2:3], v34, v34, 1.0
	v_rcp_f32_e32 v39, v38
	v_mul_f32_e32 v36, 0xc1000000, v36
	v_mul_f32_e32 v36, v43, v36
	s_add_i32 s2, s15, s12
	v_fma_f32 v44, -v38, v39, 1.0
	v_fmac_f32_e32 v39, v44, v39
	v_div_scale_f32 v44, vcc, 1.0, v34, 1.0
	v_mul_f32_e32 v45, v44, v39
	v_fma_f32 v46, -v38, v45, v44
	v_fmac_f32_e32 v45, v46, v39
	v_fma_f32 v38, -v38, v45, v44
	v_div_fmas_f32 v38, v38, v39, v45
	v_div_fixup_f32 v34, v38, v34, 1.0
	v_add_f32_e32 v38, v36, v36
	v_mul_f32_e32 v39, 0x3fb8aa3b, v38
	v_rndne_f32_e32 v39, v39
	v_fmamk_f32 v44, v39, 0xbf317218, v38
	v_fmac_f32_e32 v44, 0x3102e308, v39
	v_fmamk_f32 v45, v44, 0x395133b1, v230
	v_cmp_eq_f32_e32 vcc, s25, v39
	v_cvt_i32_f32_e32 v39, v39
	v_fmaak_f32 v45, v44, v45, 0x3c0887f9
	v_fmaak_f32 v45, v44, v45, 0x3d2aaa81
	v_fmaak_f32 v45, v44, v45, 0x3e2aaaab
	v_fma_f32 v45, v44, v45, 0.5
	v_ldexp_f32 v39, 1.0, v39
	v_mul_f32_e32 v45, v44, v45
	v_cndmask_b32_e32 v39, v39, v238, vcc
	v_fmac_f32_e32 v44, v44, v45
	v_add_f32_e32 v45, -1.0, v39
	v_fmac_f32_e32 v45, v39, v44
	v_add_f32_e32 v39, v45, v45
	v_cndmask_b32_e32 v39, v45, v39, vcc
	v_cmp_nlt_f32_e32 vcc, s70, v38
	s_ashr_i32 s3, s2, 31
	s_lshl_b64 s[2:3], s[2:3], 8
	v_cndmask_b32_e64 v39, v237, -v39, vcc
	v_cmp_gt_f32_e32 vcc, s26, v39
	v_mul_f32_e32 v44, 0x4f800000, v39
	s_nop 0
	v_cndmask_b32_e32 v39, v39, v44, vcc
	v_sqrt_f32_e32 v44, v39
	s_nop 0
	v_add_u32_e32 v45, -1, v44
	v_fma_f32 v46, -v45, v44, v39
	v_cmp_ge_f32_e64 s[8:9], 0, v46
	v_add_u32_e32 v46, 1, v44
	s_nop 0
	v_cndmask_b32_e64 v45, v44, v45, s[8:9]
	v_fma_f32 v44, -v46, v44, v39
	v_cmp_lt_f32_e64 s[8:9], 0, v44
	s_nop 1
	v_cndmask_b32_e64 v44, v45, v46, s[8:9]
	v_mul_f32_e32 v45, 0x37800000, v44
	v_cndmask_b32_e32 v44, v44, v45, vcc
	v_cmp_class_f32_e32 vcc, v39, v231
	s_nop 1
	v_cndmask_b32_e32 v39, v44, v39, vcc
	v_cmp_ngt_f32_e32 vcc, s27, v38
	s_nop 1
	v_cndmask_b32_e32 v38, 1.0, v39, vcc
	v_lshl_add_u32 v39, s15, 10, v40
	ds_read_b32 v39, v39
	s_waitcnt lgkmcnt(0)
	v_mul_f32_e32 v34, v34, v39
	v_mul_f32_e32 v34, v38, v34
	v_bfe_u32 v38, v36, 16, 1
	v_add3_u32 v36, v36, v38, s69
	v_lshl_add_u64 v[38:39], s[2:3], 0, v[0:1]
	v_lshlrev_b64 v[38:39], 1, v[38:39]
	v_lshl_add_u64 v[44:45], s[6:7], 0, v[38:39]
	global_store_short_d16_hi v[44:45], v36, off
	v_bfe_u32 v36, v34, 16, 1
	v_add3_u32 v34, v34, v36, s69
	v_lshl_add_u64 v[38:39], s[22:23], 0, v[38:39]
	global_store_short_d16_hi v[38:39], v34, off
	s_or_b32 s2, s15, 1
	s_cmp_ge_i32 s2, s10
	s_cbranch_scc0 .LBB0_234

.LBB0_509:
	s_andn2_b64 vcc, exec, s[2:3]
	s_cbranch_vccnz .LBB0_503
	v_readlane_b32 s11, v255, 8
	v_readlane_b32 s12, v255, 6
	v_readlane_b32 s2, v253, 4
	v_readlane_b32 s3, v253, 5
	s_lshl_b32 s13, s11, 18
	s_add_u32 s2, s2, s13
	s_addc_u32 s3, s3, 0
	s_lshl_b32 s13, s12, 19
	s_add_u32 s4, s50, 0x5510000
	s_addc_u32 s5, s51, 0
	s_add_u32 s4, s4, s13
	s_addc_u32 s5, s5, 0
	v_and_b32_e32 v92, 63, v216
	v_lshrrev_b32_e32 v93, 6, v216
	v_lshrrev_b32_e32 v94, 2, v92
	v_and_b32_e32 v95, 3, v92
	v_readfirstlane_b32 s11, v93
	v_lshrrev_b32_e32 v100, 3, v94
	v_mul_u32_u24_e32 v100, 3, v100
	v_xor_b32_e32 v100, v95, v100
	v_lshlrev_b32_e32 v100, 4, v100
	v_lshl_add_u32 v101, v93, 5, v94
	v_lshl_add_u32 v203, v101, 11, v100
	v_add_u32_e32 v204, 0x8000, v203
	v_lshl_add_u32 v101, v93, 6, v94
	v_lshlrev_b32_e32 v111, 4, v92
	v_lshl_add_u32 v205, v93, 12, v111
	v_add_u32_e32 v206, 0x400, v205
	v_add_u32_e32 v207, 0x800, v205
	v_add_u32_e32 v208, 0xc00, v205
	v_and_b32_e32 v102, 15, v92
	v_lshrrev_b32_e32 v103, 4, v92
	v_lshrrev_b32_e32 v108, 3, v102
	v_mul_u32_u24_e32 v108, 3, v108
	v_xor_b32_e32 v108, v103, v108
	v_lshlrev_b32_e32 v108, 4, v108
	v_lshl_add_u32 v108, v102, 6, v108
	v_lshrrev_b32_e32 v109, 1, v93
	v_and_b32_e32 v110, 1, v93
	v_lshl_add_u32 v209, v109, 12, v108
	v_lshl_add_u32 v210, v110, 13, v108
	s_lshl_b32 s12, s11, 12
	s_lshl_b32 s11, s11, 11
	s_barrier
	s_add_u32 m0, s11, 0x0
	s_nop 0
	global_load_lds_dwordx4 v203, s[2:3]
	s_add_u32 m0, s11, 0x400
	s_nop 0
	global_load_lds_dwordx4 v204, s[2:3]
	s_add_u32 m0, s12, 0x2000
	s_nop 0
	global_load_lds_dwordx4 v205, s[4:5]
	s_add_u32 m0, s12, 0x2400
	s_nop 0
	global_load_lds_dwordx4 v206, s[4:5]
	s_add_u32 m0, s12, 0x2800
	s_nop 0
	global_load_lds_dwordx4 v207, s[4:5]
	s_add_u32 m0, s12, 0x2c00
	s_nop 0
	global_load_lds_dwordx4 v208, s[4:5]
	s_add_u32 s2, s2, 0x40
	s_addc_u32 s3, s3, 0
	s_add_u32 s4, s4, 0x4000
	s_addc_u32 s5, s5, 0
	s_add_u32 m0, s11, 0x6000
	s_nop 0
	global_load_lds_dwordx4 v203, s[2:3]
	s_add_u32 m0, s11, 0x6400
	s_nop 0
	global_load_lds_dwordx4 v204, s[2:3]
	s_add_u32 m0, s12, 0x8000
	s_nop 0
	global_load_lds_dwordx4 v205, s[4:5]
	s_add_u32 m0, s12, 0x8400
	s_nop 0
	global_load_lds_dwordx4 v206, s[4:5]
	s_add_u32 m0, s12, 0x8800
	s_nop 0
	global_load_lds_dwordx4 v207, s[4:5]
	s_add_u32 m0, s12, 0x8c00
	s_nop 0
	global_load_lds_dwordx4 v208, s[4:5]
	s_add_u32 s2, s2, 0x40
	s_addc_u32 s3, s3, 0
	s_add_u32 s4, s4, 0x4000
	s_addc_u32 s5, s5, 0
	v_mov_b32_e32 v156, 0
	v_mov_b32_e32 v157, 0
	v_mov_b32_e32 v158, 0
	v_mov_b32_e32 v159, 0
	v_mov_b32_e32 v152, 0
	v_mov_b32_e32 v153, 0
	v_mov_b32_e32 v154, 0
	v_mov_b32_e32 v155, 0
	v_mov_b32_e32 v148, 0
	v_mov_b32_e32 v149, 0
	v_mov_b32_e32 v150, 0
	v_mov_b32_e32 v151, 0
	v_mov_b32_e32 v144, 0
	v_mov_b32_e32 v145, 0
	v_mov_b32_e32 v146, 0
	v_mov_b32_e32 v147, 0
	v_mov_b32_e32 v172, 0
	v_mov_b32_e32 v173, 0
	v_mov_b32_e32 v174, 0
	v_mov_b32_e32 v175, 0
	v_mov_b32_e32 v168, 0
	v_mov_b32_e32 v169, 0
	v_mov_b32_e32 v170, 0
	v_mov_b32_e32 v171, 0
	v_mov_b32_e32 v164, 0
	v_mov_b32_e32 v165, 0
	v_mov_b32_e32 v166, 0
	v_mov_b32_e32 v167, 0
	v_mov_b32_e32 v160, 0
	v_mov_b32_e32 v161, 0
	v_mov_b32_e32 v162, 0
	v_mov_b32_e32 v163, 0
	v_mov_b32_e32 v124, 0
	v_mov_b32_e32 v125, 0
	v_mov_b32_e32 v126, 0
	v_mov_b32_e32 v127, 0
	v_mov_b32_e32 v120, 0
	v_mov_b32_e32 v121, 0
	v_mov_b32_e32 v122, 0
	v_mov_b32_e32 v123, 0
	v_mov_b32_e32 v112, 0
	v_mov_b32_e32 v113, 0
	v_mov_b32_e32 v114, 0
	v_mov_b32_e32 v115, 0
	v_mov_b32_e32 v104, 0
	v_mov_b32_e32 v105, 0
	v_mov_b32_e32 v106, 0
	v_mov_b32_e32 v107, 0
	v_mov_b32_e32 v140, 0
	v_mov_b32_e32 v141, 0
	v_mov_b32_e32 v142, 0
	v_mov_b32_e32 v143, 0
	v_mov_b32_e32 v136, 0
	v_mov_b32_e32 v137, 0
	v_mov_b32_e32 v138, 0
	v_mov_b32_e32 v139, 0
	v_mov_b32_e32 v132, 0
	v_mov_b32_e32 v133, 0
	v_mov_b32_e32 v134, 0
	v_mov_b32_e32 v135, 0
	v_mov_b32_e32 v128, 0
	v_mov_b32_e32 v129, 0
	v_mov_b32_e32 v130, 0
	v_mov_b32_e32 v131, 0
	v_mov_b32_e32 v52, 0
	v_mov_b32_e32 v53, 0
	v_mov_b32_e32 v54, 0
	v_mov_b32_e32 v55, 0
	v_mov_b32_e32 v40, 0
	v_mov_b32_e32 v41, 0
	v_mov_b32_e32 v42, 0
	v_mov_b32_e32 v43, 0
	v_mov_b32_e32 v36, 0
	v_mov_b32_e32 v37, 0
	v_mov_b32_e32 v38, 0
	v_mov_b32_e32 v39, 0
	v_mov_b32_e32 v32, 0
	v_mov_b32_e32 v33, 0
	v_mov_b32_e32 v34, 0
	v_mov_b32_e32 v35, 0
	v_mov_b32_e32 v96, 0
	v_mov_b32_e32 v97, 0
	v_mov_b32_e32 v98, 0
	v_mov_b32_e32 v99, 0
	v_mov_b32_e32 v88, 0
	v_mov_b32_e32 v89, 0
	v_mov_b32_e32 v90, 0
	v_mov_b32_e32 v91, 0
	v_mov_b32_e32 v76, 0
	v_mov_b32_e32 v77, 0
	v_mov_b32_e32 v78, 0
	v_mov_b32_e32 v79, 0
	v_mov_b32_e32 v68, 0
	v_mov_b32_e32 v69, 0
	v_mov_b32_e32 v70, 0
	v_mov_b32_e32 v71, 0
	v_mov_b32_e32 v12, 0
	v_mov_b32_e32 v13, 0
	v_mov_b32_e32 v14, 0
	v_mov_b32_e32 v15, 0
	v_mov_b32_e32 v8, 0
	v_mov_b32_e32 v9, 0
	v_mov_b32_e32 v10, 0
	v_mov_b32_e32 v11, 0
	v_mov_b32_e32 v4, 0
	v_mov_b32_e32 v5, 0
	v_mov_b32_e32 v6, 0
	v_mov_b32_e32 v7, 0
	v_mov_b32_e32 v0, 0
	v_mov_b32_e32 v1, 0
	v_mov_b32_e32 v2, 0
	v_mov_b32_e32 v3, 0
	v_mov_b32_e32 v28, 0
	v_mov_b32_e32 v29, 0
	v_mov_b32_e32 v30, 0
	v_mov_b32_e32 v31, 0
	v_mov_b32_e32 v24, 0
	v_mov_b32_e32 v25, 0
	v_mov_b32_e32 v26, 0
	v_mov_b32_e32 v27, 0
	v_mov_b32_e32 v20, 0
	v_mov_b32_e32 v21, 0
	v_mov_b32_e32 v22, 0
	v_mov_b32_e32 v23, 0
	v_mov_b32_e32 v16, 0
	v_mov_b32_e32 v17, 0
	v_mov_b32_e32 v18, 0
	v_mov_b32_e32 v19, 0
	s_waitcnt vmcnt(6)
	s_barrier
	ds_read_b128 v[44:47], v209 offset:0
	ds_read_b128 v[48:51], v209 offset:1024
	ds_read_b128 v[56:59], v209 offset:2048
	ds_read_b128 v[60:63], v209 offset:3072
	ds_read_b128 v[92:95], v210 offset:8192
	ds_read_b128 v[100:103], v210 offset:9216
	ds_read_b128 v[108:111], v210 offset:10240
	ds_read_b128 v[116:119], v210 offset:11264
	ds_read_b128 v[176:179], v210 offset:12288
	ds_read_b128 v[180:183], v210 offset:13312
	s_add_u32 m0, s11, 0xc000
	s_nop 0
	global_load_lds_dwordx4 v203, s[2:3]
	s_add_u32 m0, s11, 0xc400
	s_nop 0
	global_load_lds_dwordx4 v204, s[2:3]
	s_add_u32 m0, s12, 0xe000
	s_nop 0
	global_load_lds_dwordx4 v205, s[4:5]
	s_add_u32 m0, s12, 0xe400
	s_nop 0
	global_load_lds_dwordx4 v206, s[4:5]
	s_add_u32 m0, s12, 0xe800
	s_nop 0
	global_load_lds_dwordx4 v207, s[4:5]
	s_add_u32 m0, s12, 0xec00
	s_nop 0
	global_load_lds_dwordx4 v208, s[4:5]
	s_add_u32 s2, s2, 0x40
	s_addc_u32 s3, s3, 0
	s_add_u32 s4, s4, 0x4000
	s_addc_u32 s5, s5, 0
	ds_read_b128 v[184:187], v210 offset:14336
	ds_read_b128 v[188:191], v210 offset:15360
	s_waitcnt lgkmcnt(7)
	v_mfma_f32_16x16x32_bf16 v[156:159], v[92:95], v[44:47], v[156:159]
	v_mfma_f32_16x16x32_bf16 v[124:127], v[92:95], v[48:51], v[124:127]
	v_mfma_f32_16x16x32_bf16 v[52:55], v[92:95], v[56:59], v[52:55]
	v_mfma_f32_16x16x32_bf16 v[12:15], v[92:95], v[60:63], v[12:15]
	s_waitcnt lgkmcnt(6)
	v_mfma_f32_16x16x32_bf16 v[152:155], v[100:103], v[44:47], v[152:155]
	v_mfma_f32_16x16x32_bf16 v[120:123], v[100:103], v[48:51], v[120:123]
	v_mfma_f32_16x16x32_bf16 v[40:43], v[100:103], v[56:59], v[40:43]
	v_mfma_f32_16x16x32_bf16 v[8:11], v[100:103], v[60:63], v[8:11]
	s_waitcnt lgkmcnt(5)
	v_mfma_f32_16x16x32_bf16 v[148:151], v[108:111], v[44:47], v[148:151]
	v_mfma_f32_16x16x32_bf16 v[112:115], v[108:111], v[48:51], v[112:115]
	v_mfma_f32_16x16x32_bf16 v[36:39], v[108:111], v[56:59], v[36:39]
	v_mfma_f32_16x16x32_bf16 v[4:7], v[108:111], v[60:63], v[4:7]
	s_waitcnt lgkmcnt(4)
	v_mfma_f32_16x16x32_bf16 v[144:147], v[116:119], v[44:47], v[144:147]
	v_mfma_f32_16x16x32_bf16 v[104:107], v[116:119], v[48:51], v[104:107]
	v_mfma_f32_16x16x32_bf16 v[32:35], v[116:119], v[56:59], v[32:35]
	v_mfma_f32_16x16x32_bf16 v[0:3], v[116:119], v[60:63], v[0:3]
	s_waitcnt lgkmcnt(3)
	v_mfma_f32_16x16x32_bf16 v[172:175], v[176:179], v[44:47], v[172:175]
	v_mfma_f32_16x16x32_bf16 v[140:143], v[176:179], v[48:51], v[140:143]
	v_mfma_f32_16x16x32_bf16 v[96:99], v[176:179], v[56:59], v[96:99]
	v_mfma_f32_16x16x32_bf16 v[28:31], v[176:179], v[60:63], v[28:31]
	s_waitcnt lgkmcnt(2)
	v_mfma_f32_16x16x32_bf16 v[168:171], v[180:183], v[44:47], v[168:171]
	v_mfma_f32_16x16x32_bf16 v[136:139], v[180:183], v[48:51], v[136:139]
	v_mfma_f32_16x16x32_bf16 v[88:91], v[180:183], v[56:59], v[88:91]
	v_mfma_f32_16x16x32_bf16 v[24:27], v[180:183], v[60:63], v[24:27]
	s_waitcnt lgkmcnt(0)
	s_mov_b32 s13, 5
.Lg2_loop:
	s_waitcnt vmcnt(6)
	s_barrier
	ds_read_b128 v[64:67], v209 offset:24576
	ds_read_b128 v[72:75], v209 offset:25600
	ds_read_b128 v[80:83], v209 offset:26624
	ds_read_b128 v[84:87], v209 offset:27648
	ds_read_b128 v[92:95], v210 offset:32768
	ds_read_b128 v[100:103], v210 offset:33792
	ds_read_b128 v[108:111], v210 offset:34816
	ds_read_b128 v[116:119], v210 offset:35840
	ds_read_b128 v[176:179], v210 offset:36864
	ds_read_b128 v[180:183], v210 offset:37888
	v_mfma_f32_16x16x32_bf16 v[164:167], v[184:187], v[44:47], v[164:167]
	s_add_u32 m0, s11, 0x0
	v_mfma_f32_16x16x32_bf16 v[132:135], v[184:187], v[48:51], v[132:135]
	global_load_lds_dwordx4 v203, s[2:3]
	s_add_u32 m0, s11, 0x400
	v_mfma_f32_16x16x32_bf16 v[76:79], v[184:187], v[56:59], v[76:79]
	global_load_lds_dwordx4 v204, s[2:3]
	s_add_u32 m0, s12, 0x2000
	v_mfma_f32_16x16x32_bf16 v[20:23], v[184:187], v[60:63], v[20:23]
	global_load_lds_dwordx4 v205, s[4:5]
	s_add_u32 m0, s12, 0x2400
	v_mfma_f32_16x16x32_bf16 v[160:163], v[188:191], v[44:47], v[160:163]
	global_load_lds_dwordx4 v206, s[4:5]
	s_add_u32 m0, s12, 0x2800
	v_mfma_f32_16x16x32_bf16 v[128:131], v[188:191], v[48:51], v[128:131]
	global_load_lds_dwordx4 v207, s[4:5]
	s_add_u32 m0, s12, 0x2c00
	v_mfma_f32_16x16x32_bf16 v[68:71], v[188:191], v[56:59], v[68:71]
	global_load_lds_dwordx4 v208, s[4:5]
	v_mfma_f32_16x16x32_bf16 v[16:19], v[188:191], v[60:63], v[16:19]
	s_add_u32 s2, s2, 0x40
	s_addc_u32 s3, s3, 0
	s_add_u32 s4, s4, 0x4000
	s_addc_u32 s5, s5, 0
	ds_read_b128 v[184:187], v210 offset:38912
	ds_read_b128 v[188:191], v210 offset:39936
	s_waitcnt lgkmcnt(7)
	v_mfma_f32_16x16x32_bf16 v[156:159], v[92:95], v[64:67], v[156:159]
	v_mfma_f32_16x16x32_bf16 v[124:127], v[92:95], v[72:75], v[124:127]
	v_mfma_f32_16x16x32_bf16 v[52:55], v[92:95], v[80:83], v[52:55]
	v_mfma_f32_16x16x32_bf16 v[12:15], v[92:95], v[84:87], v[12:15]
	s_waitcnt lgkmcnt(6)
	v_mfma_f32_16x16x32_bf16 v[152:155], v[100:103], v[64:67], v[152:155]
	v_mfma_f32_16x16x32_bf16 v[120:123], v[100:103], v[72:75], v[120:123]
	v_mfma_f32_16x16x32_bf16 v[40:43], v[100:103], v[80:83], v[40:43]
	v_mfma_f32_16x16x32_bf16 v[8:11], v[100:103], v[84:87], v[8:11]
	s_waitcnt lgkmcnt(5)
	v_mfma_f32_16x16x32_bf16 v[148:151], v[108:111], v[64:67], v[148:151]
	v_mfma_f32_16x16x32_bf16 v[112:115], v[108:111], v[72:75], v[112:115]
	v_mfma_f32_16x16x32_bf16 v[36:39], v[108:111], v[80:83], v[36:39]
	v_mfma_f32_16x16x32_bf16 v[4:7], v[108:111], v[84:87], v[4:7]
	s_waitcnt lgkmcnt(4)
	v_mfma_f32_16x16x32_bf16 v[144:147], v[116:119], v[64:67], v[144:147]
	v_mfma_f32_16x16x32_bf16 v[104:107], v[116:119], v[72:75], v[104:107]
	v_mfma_f32_16x16x32_bf16 v[32:35], v[116:119], v[80:83], v[32:35]
	v_mfma_f32_16x16x32_bf16 v[0:3], v[116:119], v[84:87], v[0:3]
	s_waitcnt lgkmcnt(3)
	v_mfma_f32_16x16x32_bf16 v[172:175], v[176:179], v[64:67], v[172:175]
	v_mfma_f32_16x16x32_bf16 v[140:143], v[176:179], v[72:75], v[140:143]
	v_mfma_f32_16x16x32_bf16 v[96:99], v[176:179], v[80:83], v[96:99]
	v_mfma_f32_16x16x32_bf16 v[28:31], v[176:179], v[84:87], v[28:31]
	s_waitcnt lgkmcnt(2)
	v_mfma_f32_16x16x32_bf16 v[168:171], v[180:183], v[64:67], v[168:171]
	v_mfma_f32_16x16x32_bf16 v[136:139], v[180:183], v[72:75], v[136:139]
	v_mfma_f32_16x16x32_bf16 v[88:91], v[180:183], v[80:83], v[88:91]
	v_mfma_f32_16x16x32_bf16 v[24:27], v[180:183], v[84:87], v[24:27]
	s_waitcnt lgkmcnt(0)
	s_waitcnt vmcnt(6)
	s_barrier
	ds_read_b128 v[44:47], v209 offset:49152
	ds_read_b128 v[48:51], v209 offset:50176
	ds_read_b128 v[56:59], v209 offset:51200
	ds_read_b128 v[60:63], v209 offset:52224
	ds_read_b128 v[92:95], v210 offset:57344
	ds_read_b128 v[100:103], v210 offset:58368
	ds_read_b128 v[108:111], v210 offset:59392
	ds_read_b128 v[116:119], v210 offset:60416
	ds_read_b128 v[176:179], v210 offset:61440
	ds_read_b128 v[180:183], v210 offset:62464
	v_mfma_f32_16x16x32_bf16 v[164:167], v[184:187], v[64:67], v[164:167]
	s_add_u32 m0, s11, 0x6000
	v_mfma_f32_16x16x32_bf16 v[132:135], v[184:187], v[72:75], v[132:135]
	global_load_lds_dwordx4 v203, s[2:3]
	s_add_u32 m0, s11, 0x6400
	v_mfma_f32_16x16x32_bf16 v[76:79], v[184:187], v[80:83], v[76:79]
	global_load_lds_dwordx4 v204, s[2:3]
	s_add_u32 m0, s12, 0x8000
	v_mfma_f32_16x16x32_bf16 v[20:23], v[184:187], v[84:87], v[20:23]
	global_load_lds_dwordx4 v205, s[4:5]
	s_add_u32 m0, s12, 0x8400
	v_mfma_f32_16x16x32_bf16 v[160:163], v[188:191], v[64:67], v[160:163]
	global_load_lds_dwordx4 v206, s[4:5]
	s_add_u32 m0, s12, 0x8800
	v_mfma_f32_16x16x32_bf16 v[128:131], v[188:191], v[72:75], v[128:131]
	global_load_lds_dwordx4 v207, s[4:5]
	s_add_u32 m0, s12, 0x8c00
	v_mfma_f32_16x16x32_bf16 v[68:71], v[188:191], v[80:83], v[68:71]
	global_load_lds_dwordx4 v208, s[4:5]
	v_mfma_f32_16x16x32_bf16 v[16:19], v[188:191], v[84:87], v[16:19]
	s_add_u32 s2, s2, 0x40
	s_addc_u32 s3, s3, 0
	s_add_u32 s4, s4, 0x4000
	s_addc_u32 s5, s5, 0
	ds_read_b128 v[184:187], v210 offset:63488
	ds_read_b128 v[188:191], v210 offset:64512
	s_waitcnt lgkmcnt(7)
	v_mfma_f32_16x16x32_bf16 v[156:159], v[92:95], v[44:47], v[156:159]
	v_mfma_f32_16x16x32_bf16 v[124:127], v[92:95], v[48:51], v[124:127]
	v_mfma_f32_16x16x32_bf16 v[52:55], v[92:95], v[56:59], v[52:55]
	v_mfma_f32_16x16x32_bf16 v[12:15], v[92:95], v[60:63], v[12:15]
	s_waitcnt lgkmcnt(6)
	v_mfma_f32_16x16x32_bf16 v[152:155], v[100:103], v[44:47], v[152:155]
	v_mfma_f32_16x16x32_bf16 v[120:123], v[100:103], v[48:51], v[120:123]
	v_mfma_f32_16x16x32_bf16 v[40:43], v[100:103], v[56:59], v[40:43]
	v_mfma_f32_16x16x32_bf16 v[8:11], v[100:103], v[60:63], v[8:11]
	s_waitcnt lgkmcnt(5)
	v_mfma_f32_16x16x32_bf16 v[148:151], v[108:111], v[44:47], v[148:151]
	v_mfma_f32_16x16x32_bf16 v[112:115], v[108:111], v[48:51], v[112:115]
	v_mfma_f32_16x16x32_bf16 v[36:39], v[108:111], v[56:59], v[36:39]
	v_mfma_f32_16x16x32_bf16 v[4:7], v[108:111], v[60:63], v[4:7]
	s_waitcnt lgkmcnt(4)
	v_mfma_f32_16x16x32_bf16 v[144:147], v[116:119], v[44:47], v[144:147]
	v_mfma_f32_16x16x32_bf16 v[104:107], v[116:119], v[48:51], v[104:107]
	v_mfma_f32_16x16x32_bf16 v[32:35], v[116:119], v[56:59], v[32:35]
	v_mfma_f32_16x16x32_bf16 v[0:3], v[116:119], v[60:63], v[0:3]
	s_waitcnt lgkmcnt(3)
	v_mfma_f32_16x16x32_bf16 v[172:175], v[176:179], v[44:47], v[172:175]
	v_mfma_f32_16x16x32_bf16 v[140:143], v[176:179], v[48:51], v[140:143]
	v_mfma_f32_16x16x32_bf16 v[96:99], v[176:179], v[56:59], v[96:99]
	v_mfma_f32_16x16x32_bf16 v[28:31], v[176:179], v[60:63], v[28:31]
	s_waitcnt lgkmcnt(2)
	v_mfma_f32_16x16x32_bf16 v[168:171], v[180:183], v[44:47], v[168:171]
	v_mfma_f32_16x16x32_bf16 v[136:139], v[180:183], v[48:51], v[136:139]
	v_mfma_f32_16x16x32_bf16 v[88:91], v[180:183], v[56:59], v[88:91]
	v_mfma_f32_16x16x32_bf16 v[24:27], v[180:183], v[60:63], v[24:27]
	s_waitcnt lgkmcnt(0)
	s_waitcnt vmcnt(6)
	s_barrier
	ds_read_b128 v[64:67], v209 offset:0
	ds_read_b128 v[72:75], v209 offset:1024
	ds_read_b128 v[80:83], v209 offset:2048
	ds_read_b128 v[84:87], v209 offset:3072
	ds_read_b128 v[92:95], v210 offset:8192
	ds_read_b128 v[100:103], v210 offset:9216
	ds_read_b128 v[108:111], v210 offset:10240
	ds_read_b128 v[116:119], v210 offset:11264
	ds_read_b128 v[176:179], v210 offset:12288
	ds_read_b128 v[180:183], v210 offset:13312
	v_mfma_f32_16x16x32_bf16 v[164:167], v[184:187], v[44:47], v[164:167]
	s_add_u32 m0, s11, 0xc000
	v_mfma_f32_16x16x32_bf16 v[132:135], v[184:187], v[48:51], v[132:135]
	global_load_lds_dwordx4 v203, s[2:3]
	s_add_u32 m0, s11, 0xc400
	v_mfma_f32_16x16x32_bf16 v[76:79], v[184:187], v[56:59], v[76:79]
	global_load_lds_dwordx4 v204, s[2:3]
	s_add_u32 m0, s12, 0xe000
	v_mfma_f32_16x16x32_bf16 v[20:23], v[184:187], v[60:63], v[20:23]
	global_load_lds_dwordx4 v205, s[4:5]
	s_add_u32 m0, s12, 0xe400
	v_mfma_f32_16x16x32_bf16 v[160:163], v[188:191], v[44:47], v[160:163]
	global_load_lds_dwordx4 v206, s[4:5]
	s_add_u32 m0, s12, 0xe800
	v_mfma_f32_16x16x32_bf16 v[128:131], v[188:191], v[48:51], v[128:131]
	global_load_lds_dwordx4 v207, s[4:5]
	s_add_u32 m0, s12, 0xec00
	v_mfma_f32_16x16x32_bf16 v[68:71], v[188:191], v[56:59], v[68:71]
	global_load_lds_dwordx4 v208, s[4:5]
	v_mfma_f32_16x16x32_bf16 v[16:19], v[188:191], v[60:63], v[16:19]
	s_add_u32 s2, s2, 0x40
	s_addc_u32 s3, s3, 0
	s_add_u32 s4, s4, 0x4000
	s_addc_u32 s5, s5, 0
	ds_read_b128 v[184:187], v210 offset:14336
	ds_read_b128 v[188:191], v210 offset:15360
	s_waitcnt lgkmcnt(7)
	v_mfma_f32_16x16x32_bf16 v[156:159], v[92:95], v[64:67], v[156:159]
	v_mfma_f32_16x16x32_bf16 v[124:127], v[92:95], v[72:75], v[124:127]
	v_mfma_f32_16x16x32_bf16 v[52:55], v[92:95], v[80:83], v[52:55]
	v_mfma_f32_16x16x32_bf16 v[12:15], v[92:95], v[84:87], v[12:15]
	s_waitcnt lgkmcnt(6)
	v_mfma_f32_16x16x32_bf16 v[152:155], v[100:103], v[64:67], v[152:155]
	v_mfma_f32_16x16x32_bf16 v[120:123], v[100:103], v[72:75], v[120:123]
	v_mfma_f32_16x16x32_bf16 v[40:43], v[100:103], v[80:83], v[40:43]
	v_mfma_f32_16x16x32_bf16 v[8:11], v[100:103], v[84:87], v[8:11]
	s_waitcnt lgkmcnt(5)
	v_mfma_f32_16x16x32_bf16 v[148:151], v[108:111], v[64:67], v[148:151]
	v_mfma_f32_16x16x32_bf16 v[112:115], v[108:111], v[72:75], v[112:115]
	v_mfma_f32_16x16x32_bf16 v[36:39], v[108:111], v[80:83], v[36:39]
	v_mfma_f32_16x16x32_bf16 v[4:7], v[108:111], v[84:87], v[4:7]
	s_waitcnt lgkmcnt(4)
	v_mfma_f32_16x16x32_bf16 v[144:147], v[116:119], v[64:67], v[144:147]
	v_mfma_f32_16x16x32_bf16 v[104:107], v[116:119], v[72:75], v[104:107]
	v_mfma_f32_16x16x32_bf16 v[32:35], v[116:119], v[80:83], v[32:35]
	v_mfma_f32_16x16x32_bf16 v[0:3], v[116:119], v[84:87], v[0:3]
	s_waitcnt lgkmcnt(3)
	v_mfma_f32_16x16x32_bf16 v[172:175], v[176:179], v[64:67], v[172:175]
	v_mfma_f32_16x16x32_bf16 v[140:143], v[176:179], v[72:75], v[140:143]
	v_mfma_f32_16x16x32_bf16 v[96:99], v[176:179], v[80:83], v[96:99]
	v_mfma_f32_16x16x32_bf16 v[28:31], v[176:179], v[84:87], v[28:31]
	s_waitcnt lgkmcnt(2)
	v_mfma_f32_16x16x32_bf16 v[168:171], v[180:183], v[64:67], v[168:171]
	v_mfma_f32_16x16x32_bf16 v[136:139], v[180:183], v[72:75], v[136:139]
	v_mfma_f32_16x16x32_bf16 v[88:91], v[180:183], v[80:83], v[88:91]
	v_mfma_f32_16x16x32_bf16 v[24:27], v[180:183], v[84:87], v[24:27]
	s_waitcnt lgkmcnt(0)
	s_waitcnt vmcnt(6)
	s_barrier
	ds_read_b128 v[44:47], v209 offset:24576
	ds_read_b128 v[48:51], v209 offset:25600
	ds_read_b128 v[56:59], v209 offset:26624
	ds_read_b128 v[60:63], v209 offset:27648
	ds_read_b128 v[92:95], v210 offset:32768
	ds_read_b128 v[100:103], v210 offset:33792
	ds_read_b128 v[108:111], v210 offset:34816
	ds_read_b128 v[116:119], v210 offset:35840
	ds_read_b128 v[176:179], v210 offset:36864
	ds_read_b128 v[180:183], v210 offset:37888
	v_mfma_f32_16x16x32_bf16 v[164:167], v[184:187], v[64:67], v[164:167]
	s_add_u32 m0, s11, 0x0
	v_mfma_f32_16x16x32_bf16 v[132:135], v[184:187], v[72:75], v[132:135]
	global_load_lds_dwordx4 v203, s[2:3]
	s_add_u32 m0, s11, 0x400
	v_mfma_f32_16x16x32_bf16 v[76:79], v[184:187], v[80:83], v[76:79]
	global_load_lds_dwordx4 v204, s[2:3]
	s_add_u32 m0, s12, 0x2000
	v_mfma_f32_16x16x32_bf16 v[20:23], v[184:187], v[84:87], v[20:23]
	global_load_lds_dwordx4 v205, s[4:5]
	s_add_u32 m0, s12, 0x2400
	v_mfma_f32_16x16x32_bf16 v[160:163], v[188:191], v[64:67], v[160:163]
	global_load_lds_dwordx4 v206, s[4:5]
	s_add_u32 m0, s12, 0x2800
	v_mfma_f32_16x16x32_bf16 v[128:131], v[188:191], v[72:75], v[128:131]
	global_load_lds_dwordx4 v207, s[4:5]
	s_add_u32 m0, s12, 0x2c00
	v_mfma_f32_16x16x32_bf16 v[68:71], v[188:191], v[80:83], v[68:71]
	global_load_lds_dwordx4 v208, s[4:5]
	v_mfma_f32_16x16x32_bf16 v[16:19], v[188:191], v[84:87], v[16:19]
	s_add_u32 s2, s2, 0x40
	s_addc_u32 s3, s3, 0
	s_add_u32 s4, s4, 0x4000
	s_addc_u32 s5, s5, 0
	ds_read_b128 v[184:187], v210 offset:38912
	ds_read_b128 v[188:191], v210 offset:39936
	s_waitcnt lgkmcnt(7)
	v_mfma_f32_16x16x32_bf16 v[156:159], v[92:95], v[44:47], v[156:159]
	v_mfma_f32_16x16x32_bf16 v[124:127], v[92:95], v[48:51], v[124:127]
	v_mfma_f32_16x16x32_bf16 v[52:55], v[92:95], v[56:59], v[52:55]
	v_mfma_f32_16x16x32_bf16 v[12:15], v[92:95], v[60:63], v[12:15]
	s_waitcnt lgkmcnt(6)
	v_mfma_f32_16x16x32_bf16 v[152:155], v[100:103], v[44:47], v[152:155]
	v_mfma_f32_16x16x32_bf16 v[120:123], v[100:103], v[48:51], v[120:123]
	v_mfma_f32_16x16x32_bf16 v[40:43], v[100:103], v[56:59], v[40:43]
	v_mfma_f32_16x16x32_bf16 v[8:11], v[100:103], v[60:63], v[8:11]
	s_waitcnt lgkmcnt(5)
	v_mfma_f32_16x16x32_bf16 v[148:151], v[108:111], v[44:47], v[148:151]
	v_mfma_f32_16x16x32_bf16 v[112:115], v[108:111], v[48:51], v[112:115]
	v_mfma_f32_16x16x32_bf16 v[36:39], v[108:111], v[56:59], v[36:39]
	v_mfma_f32_16x16x32_bf16 v[4:7], v[108:111], v[60:63], v[4:7]
	s_waitcnt lgkmcnt(4)
	v_mfma_f32_16x16x32_bf16 v[144:147], v[116:119], v[44:47], v[144:147]
	v_mfma_f32_16x16x32_bf16 v[104:107], v[116:119], v[48:51], v[104:107]
	v_mfma_f32_16x16x32_bf16 v[32:35], v[116:119], v[56:59], v[32:35]
	v_mfma_f32_16x16x32_bf16 v[0:3], v[116:119], v[60:63], v[0:3]
	s_waitcnt lgkmcnt(3)
	v_mfma_f32_16x16x32_bf16 v[172:175], v[176:179], v[44:47], v[172:175]
	v_mfma_f32_16x16x32_bf16 v[140:143], v[176:179], v[48:51], v[140:143]
	v_mfma_f32_16x16x32_bf16 v[96:99], v[176:179], v[56:59], v[96:99]
	v_mfma_f32_16x16x32_bf16 v[28:31], v[176:179], v[60:63], v[28:31]
	s_waitcnt lgkmcnt(2)
	v_mfma_f32_16x16x32_bf16 v[168:171], v[180:183], v[44:47], v[168:171]
	v_mfma_f32_16x16x32_bf16 v[136:139], v[180:183], v[48:51], v[136:139]
	v_mfma_f32_16x16x32_bf16 v[88:91], v[180:183], v[56:59], v[88:91]
	v_mfma_f32_16x16x32_bf16 v[24:27], v[180:183], v[60:63], v[24:27]
	s_waitcnt lgkmcnt(0)
	s_waitcnt vmcnt(6)
	s_barrier
	ds_read_b128 v[64:67], v209 offset:49152
	ds_read_b128 v[72:75], v209 offset:50176
	ds_read_b128 v[80:83], v209 offset:51200
	ds_read_b128 v[84:87], v209 offset:52224
	ds_read_b128 v[92:95], v210 offset:57344
	ds_read_b128 v[100:103], v210 offset:58368
	ds_read_b128 v[108:111], v210 offset:59392
	ds_read_b128 v[116:119], v210 offset:60416
	ds_read_b128 v[176:179], v210 offset:61440
	ds_read_b128 v[180:183], v210 offset:62464
	v_mfma_f32_16x16x32_bf16 v[164:167], v[184:187], v[44:47], v[164:167]
	s_add_u32 m0, s11, 0x6000
	v_mfma_f32_16x16x32_bf16 v[132:135], v[184:187], v[48:51], v[132:135]
	global_load_lds_dwordx4 v203, s[2:3]
	s_add_u32 m0, s11, 0x6400
	v_mfma_f32_16x16x32_bf16 v[76:79], v[184:187], v[56:59], v[76:79]
	global_load_lds_dwordx4 v204, s[2:3]
	s_add_u32 m0, s12, 0x8000
	v_mfma_f32_16x16x32_bf16 v[20:23], v[184:187], v[60:63], v[20:23]
	global_load_lds_dwordx4 v205, s[4:5]
	s_add_u32 m0, s12, 0x8400
	v_mfma_f32_16x16x32_bf16 v[160:163], v[188:191], v[44:47], v[160:163]
	global_load_lds_dwordx4 v206, s[4:5]
	s_add_u32 m0, s12, 0x8800
	v_mfma_f32_16x16x32_bf16 v[128:131], v[188:191], v[48:51], v[128:131]
	global_load_lds_dwordx4 v207, s[4:5]
	s_add_u32 m0, s12, 0x8c00
	v_mfma_f32_16x16x32_bf16 v[68:71], v[188:191], v[56:59], v[68:71]
	global_load_lds_dwordx4 v208, s[4:5]
	v_mfma_f32_16x16x32_bf16 v[16:19], v[188:191], v[60:63], v[16:19]
	s_add_u32 s2, s2, 0x40
	s_addc_u32 s3, s3, 0
	s_add_u32 s4, s4, 0x4000
	s_addc_u32 s5, s5, 0
	ds_read_b128 v[184:187], v210 offset:63488
	ds_read_b128 v[188:191], v210 offset:64512
	s_waitcnt lgkmcnt(7)
	v_mfma_f32_16x16x32_bf16 v[156:159], v[92:95], v[64:67], v[156:159]
	v_mfma_f32_16x16x32_bf16 v[124:127], v[92:95], v[72:75], v[124:127]
	v_mfma_f32_16x16x32_bf16 v[52:55], v[92:95], v[80:83], v[52:55]
	v_mfma_f32_16x16x32_bf16 v[12:15], v[92:95], v[84:87], v[12:15]
	s_waitcnt lgkmcnt(6)
	v_mfma_f32_16x16x32_bf16 v[152:155], v[100:103], v[64:67], v[152:155]
	v_mfma_f32_16x16x32_bf16 v[120:123], v[100:103], v[72:75], v[120:123]
	v_mfma_f32_16x16x32_bf16 v[40:43], v[100:103], v[80:83], v[40:43]
	v_mfma_f32_16x16x32_bf16 v[8:11], v[100:103], v[84:87], v[8:11]
	s_waitcnt lgkmcnt(5)
	v_mfma_f32_16x16x32_bf16 v[148:151], v[108:111], v[64:67], v[148:151]
	v_mfma_f32_16x16x32_bf16 v[112:115], v[108:111], v[72:75], v[112:115]
	v_mfma_f32_16x16x32_bf16 v[36:39], v[108:111], v[80:83], v[36:39]
	v_mfma_f32_16x16x32_bf16 v[4:7], v[108:111], v[84:87], v[4:7]
	s_waitcnt lgkmcnt(4)
	v_mfma_f32_16x16x32_bf16 v[144:147], v[116:119], v[64:67], v[144:147]
	v_mfma_f32_16x16x32_bf16 v[104:107], v[116:119], v[72:75], v[104:107]
	v_mfma_f32_16x16x32_bf16 v[32:35], v[116:119], v[80:83], v[32:35]
	v_mfma_f32_16x16x32_bf16 v[0:3], v[116:119], v[84:87], v[0:3]
	s_waitcnt lgkmcnt(3)
	v_mfma_f32_16x16x32_bf16 v[172:175], v[176:179], v[64:67], v[172:175]
	v_mfma_f32_16x16x32_bf16 v[140:143], v[176:179], v[72:75], v[140:143]
	v_mfma_f32_16x16x32_bf16 v[96:99], v[176:179], v[80:83], v[96:99]
	v_mfma_f32_16x16x32_bf16 v[28:31], v[176:179], v[84:87], v[28:31]
	s_waitcnt lgkmcnt(2)
	v_mfma_f32_16x16x32_bf16 v[168:171], v[180:183], v[64:67], v[168:171]
	v_mfma_f32_16x16x32_bf16 v[136:139], v[180:183], v[72:75], v[136:139]
	v_mfma_f32_16x16x32_bf16 v[88:91], v[180:183], v[80:83], v[88:91]
	v_mfma_f32_16x16x32_bf16 v[24:27], v[180:183], v[84:87], v[24:27]
	s_waitcnt lgkmcnt(0)
	s_waitcnt vmcnt(6)
	s_barrier
	ds_read_b128 v[44:47], v209 offset:0
	ds_read_b128 v[48:51], v209 offset:1024
	ds_read_b128 v[56:59], v209 offset:2048
	ds_read_b128 v[60:63], v209 offset:3072
	ds_read_b128 v[92:95], v210 offset:8192
	ds_read_b128 v[100:103], v210 offset:9216
	ds_read_b128 v[108:111], v210 offset:10240
	ds_read_b128 v[116:119], v210 offset:11264
	ds_read_b128 v[176:179], v210 offset:12288
	ds_read_b128 v[180:183], v210 offset:13312
	v_mfma_f32_16x16x32_bf16 v[164:167], v[184:187], v[64:67], v[164:167]
	s_add_u32 m0, s11, 0xc000
	v_mfma_f32_16x16x32_bf16 v[132:135], v[184:187], v[72:75], v[132:135]
	global_load_lds_dwordx4 v203, s[2:3]
	s_add_u32 m0, s11, 0xc400
	v_mfma_f32_16x16x32_bf16 v[76:79], v[184:187], v[80:83], v[76:79]
	global_load_lds_dwordx4 v204, s[2:3]
	s_add_u32 m0, s12, 0xe000
	v_mfma_f32_16x16x32_bf16 v[20:23], v[184:187], v[84:87], v[20:23]
	global_load_lds_dwordx4 v205, s[4:5]
	s_add_u32 m0, s12, 0xe400
	v_mfma_f32_16x16x32_bf16 v[160:163], v[188:191], v[64:67], v[160:163]
	global_load_lds_dwordx4 v206, s[4:5]
	s_add_u32 m0, s12, 0xe800
	v_mfma_f32_16x16x32_bf16 v[128:131], v[188:191], v[72:75], v[128:131]
	global_load_lds_dwordx4 v207, s[4:5]
	s_add_u32 m0, s12, 0xec00
	v_mfma_f32_16x16x32_bf16 v[68:71], v[188:191], v[80:83], v[68:71]
	global_load_lds_dwordx4 v208, s[4:5]
	v_mfma_f32_16x16x32_bf16 v[16:19], v[188:191], v[84:87], v[16:19]
	s_add_u32 s2, s2, 0x40
	s_addc_u32 s3, s3, 0
	s_add_u32 s4, s4, 0x4000
	s_addc_u32 s5, s5, 0
	ds_read_b128 v[184:187], v210 offset:14336
	ds_read_b128 v[188:191], v210 offset:15360
	s_waitcnt lgkmcnt(7)
	v_mfma_f32_16x16x32_bf16 v[156:159], v[92:95], v[44:47], v[156:159]
	v_mfma_f32_16x16x32_bf16 v[124:127], v[92:95], v[48:51], v[124:127]
	v_mfma_f32_16x16x32_bf16 v[52:55], v[92:95], v[56:59], v[52:55]
	v_mfma_f32_16x16x32_bf16 v[12:15], v[92:95], v[60:63], v[12:15]
	s_waitcnt lgkmcnt(6)
	v_mfma_f32_16x16x32_bf16 v[152:155], v[100:103], v[44:47], v[152:155]
	v_mfma_f32_16x16x32_bf16 v[120:123], v[100:103], v[48:51], v[120:123]
	v_mfma_f32_16x16x32_bf16 v[40:43], v[100:103], v[56:59], v[40:43]
	v_mfma_f32_16x16x32_bf16 v[8:11], v[100:103], v[60:63], v[8:11]
	s_waitcnt lgkmcnt(5)
	v_mfma_f32_16x16x32_bf16 v[148:151], v[108:111], v[44:47], v[148:151]
	v_mfma_f32_16x16x32_bf16 v[112:115], v[108:111], v[48:51], v[112:115]
	v_mfma_f32_16x16x32_bf16 v[36:39], v[108:111], v[56:59], v[36:39]
	v_mfma_f32_16x16x32_bf16 v[4:7], v[108:111], v[60:63], v[4:7]
	s_waitcnt lgkmcnt(4)
	v_mfma_f32_16x16x32_bf16 v[144:147], v[116:119], v[44:47], v[144:147]
	v_mfma_f32_16x16x32_bf16 v[104:107], v[116:119], v[48:51], v[104:107]
	v_mfma_f32_16x16x32_bf16 v[32:35], v[116:119], v[56:59], v[32:35]
	v_mfma_f32_16x16x32_bf16 v[0:3], v[116:119], v[60:63], v[0:3]
	s_waitcnt lgkmcnt(3)
	v_mfma_f32_16x16x32_bf16 v[172:175], v[176:179], v[44:47], v[172:175]
	v_mfma_f32_16x16x32_bf16 v[140:143], v[176:179], v[48:51], v[140:143]
	v_mfma_f32_16x16x32_bf16 v[96:99], v[176:179], v[56:59], v[96:99]
	v_mfma_f32_16x16x32_bf16 v[28:31], v[176:179], v[60:63], v[28:31]
	s_waitcnt lgkmcnt(2)
	v_mfma_f32_16x16x32_bf16 v[168:171], v[180:183], v[44:47], v[168:171]
	v_mfma_f32_16x16x32_bf16 v[136:139], v[180:183], v[48:51], v[136:139]
	v_mfma_f32_16x16x32_bf16 v[88:91], v[180:183], v[56:59], v[88:91]
	v_mfma_f32_16x16x32_bf16 v[24:27], v[180:183], v[60:63], v[24:27]
	s_waitcnt lgkmcnt(0)
	s_sub_u32 s13, s13, 1
	s_cmp_lg_u32 s13, 0
	s_cbranch_scc1 .Lg2_loop
	s_waitcnt vmcnt(6)
	s_barrier
	ds_read_b128 v[64:67], v209 offset:24576
	ds_read_b128 v[72:75], v209 offset:25600
	ds_read_b128 v[80:83], v209 offset:26624
	ds_read_b128 v[84:87], v209 offset:27648
	ds_read_b128 v[92:95], v210 offset:32768
	ds_read_b128 v[100:103], v210 offset:33792
	ds_read_b128 v[108:111], v210 offset:34816
	ds_read_b128 v[116:119], v210 offset:35840
	ds_read_b128 v[176:179], v210 offset:36864
	ds_read_b128 v[180:183], v210 offset:37888
	v_mfma_f32_16x16x32_bf16 v[164:167], v[184:187], v[44:47], v[164:167]
	v_mfma_f32_16x16x32_bf16 v[132:135], v[184:187], v[48:51], v[132:135]
	v_mfma_f32_16x16x32_bf16 v[76:79], v[184:187], v[56:59], v[76:79]
	v_mfma_f32_16x16x32_bf16 v[20:23], v[184:187], v[60:63], v[20:23]
	v_mfma_f32_16x16x32_bf16 v[160:163], v[188:191], v[44:47], v[160:163]
	v_mfma_f32_16x16x32_bf16 v[128:131], v[188:191], v[48:51], v[128:131]
	v_mfma_f32_16x16x32_bf16 v[68:71], v[188:191], v[56:59], v[68:71]
	v_mfma_f32_16x16x32_bf16 v[16:19], v[188:191], v[60:63], v[16:19]
	ds_read_b128 v[184:187], v210 offset:38912
	ds_read_b128 v[188:191], v210 offset:39936
	s_waitcnt lgkmcnt(7)
	v_mfma_f32_16x16x32_bf16 v[156:159], v[92:95], v[64:67], v[156:159]
	v_mfma_f32_16x16x32_bf16 v[124:127], v[92:95], v[72:75], v[124:127]
	v_mfma_f32_16x16x32_bf16 v[52:55], v[92:95], v[80:83], v[52:55]
	v_mfma_f32_16x16x32_bf16 v[12:15], v[92:95], v[84:87], v[12:15]
	s_waitcnt lgkmcnt(6)
	v_mfma_f32_16x16x32_bf16 v[152:155], v[100:103], v[64:67], v[152:155]
	v_mfma_f32_16x16x32_bf16 v[120:123], v[100:103], v[72:75], v[120:123]
	v_mfma_f32_16x16x32_bf16 v[40:43], v[100:103], v[80:83], v[40:43]
	v_mfma_f32_16x16x32_bf16 v[8:11], v[100:103], v[84:87], v[8:11]
	s_waitcnt lgkmcnt(5)
	v_mfma_f32_16x16x32_bf16 v[148:151], v[108:111], v[64:67], v[148:151]
	v_mfma_f32_16x16x32_bf16 v[112:115], v[108:111], v[72:75], v[112:115]
	v_mfma_f32_16x16x32_bf16 v[36:39], v[108:111], v[80:83], v[36:39]
	v_mfma_f32_16x16x32_bf16 v[4:7], v[108:111], v[84:87], v[4:7]
	s_waitcnt lgkmcnt(4)
	v_mfma_f32_16x16x32_bf16 v[144:147], v[116:119], v[64:67], v[144:147]
	v_mfma_f32_16x16x32_bf16 v[104:107], v[116:119], v[72:75], v[104:107]
	v_mfma_f32_16x16x32_bf16 v[32:35], v[116:119], v[80:83], v[32:35]
	v_mfma_f32_16x16x32_bf16 v[0:3], v[116:119], v[84:87], v[0:3]
	s_waitcnt lgkmcnt(3)
	v_mfma_f32_16x16x32_bf16 v[172:175], v[176:179], v[64:67], v[172:175]
	v_mfma_f32_16x16x32_bf16 v[140:143], v[176:179], v[72:75], v[140:143]
	v_mfma_f32_16x16x32_bf16 v[96:99], v[176:179], v[80:83], v[96:99]
	v_mfma_f32_16x16x32_bf16 v[28:31], v[176:179], v[84:87], v[28:31]
	s_waitcnt lgkmcnt(2)
	v_mfma_f32_16x16x32_bf16 v[168:171], v[180:183], v[64:67], v[168:171]
	v_mfma_f32_16x16x32_bf16 v[136:139], v[180:183], v[72:75], v[136:139]
	v_mfma_f32_16x16x32_bf16 v[88:91], v[180:183], v[80:83], v[88:91]
	v_mfma_f32_16x16x32_bf16 v[24:27], v[180:183], v[84:87], v[24:27]
	s_waitcnt lgkmcnt(0)
	v_mfma_f32_16x16x32_bf16 v[164:167], v[184:187], v[64:67], v[164:167]
	v_mfma_f32_16x16x32_bf16 v[132:135], v[184:187], v[72:75], v[132:135]
	v_mfma_f32_16x16x32_bf16 v[76:79], v[184:187], v[80:83], v[76:79]
	v_mfma_f32_16x16x32_bf16 v[20:23], v[184:187], v[84:87], v[20:23]
	v_mfma_f32_16x16x32_bf16 v[160:163], v[188:191], v[64:67], v[160:163]
	v_mfma_f32_16x16x32_bf16 v[128:131], v[188:191], v[72:75], v[128:131]
	v_mfma_f32_16x16x32_bf16 v[68:71], v[188:191], v[80:83], v[68:71]
	v_mfma_f32_16x16x32_bf16 v[16:19], v[188:191], v[84:87], v[16:19]
	s_waitcnt vmcnt(0)
	s_nop 7
	s_nop 7
	s_branch .LBB0_502

.LBB0_896:
	s_andn2_b64 vcc, exec, s[2:3]
	s_cbranch_vccnz .LBB0_890
	v_readlane_b32 s11, v254, 62
	v_readlane_b32 s12, v254, 60
	v_readlane_b32 s2, v253, 4
	v_readlane_b32 s3, v253, 5
	s_lshl_b32 s13, s11, 18
	s_add_u32 s2, s2, s13
	s_addc_u32 s3, s3, 0
	s_lshl_b32 s13, s12, 19
	s_add_u32 s4, s50, 0x65d0000
	s_addc_u32 s5, s51, 0
	s_add_u32 s4, s4, s13
	s_addc_u32 s5, s5, 0
	v_and_b32_e32 v152, 63, v216
	v_lshrrev_b32_e32 v153, 6, v216
	v_lshrrev_b32_e32 v154, 2, v152
	v_and_b32_e32 v155, 3, v152
	v_readfirstlane_b32 s11, v153
	v_lshrrev_b32_e32 v156, 3, v154
	v_mul_u32_u24_e32 v156, 3, v156
	v_xor_b32_e32 v156, v155, v156
	v_lshlrev_b32_e32 v156, 4, v156
	v_lshl_add_u32 v157, v153, 5, v154
	v_lshl_add_u32 v203, v157, 11, v156
	v_add_u32_e32 v204, 0x8000, v203
	v_lshl_add_u32 v157, v153, 6, v154
	v_lshlrev_b32_e32 v163, 4, v152
	v_lshl_add_u32 v205, v153, 12, v163
	v_add_u32_e32 v206, 0x400, v205
	v_add_u32_e32 v207, 0x800, v205
	v_add_u32_e32 v208, 0xc00, v205
	v_and_b32_e32 v158, 15, v152
	v_lshrrev_b32_e32 v159, 4, v152
	v_lshrrev_b32_e32 v160, 3, v158
	v_mul_u32_u24_e32 v160, 3, v160
	v_xor_b32_e32 v160, v159, v160
	v_lshlrev_b32_e32 v160, 4, v160
	v_lshl_add_u32 v160, v158, 6, v160
	v_lshrrev_b32_e32 v161, 1, v153
	v_and_b32_e32 v162, 1, v153
	v_lshl_add_u32 v209, v161, 12, v160
	v_lshl_add_u32 v210, v162, 13, v160
	s_lshl_b32 s12, s11, 12
	s_lshl_b32 s11, s11, 11
	s_barrier
	s_add_u32 m0, s11, 0x0
	s_nop 0
	global_load_lds_dwordx4 v203, s[2:3]
	s_add_u32 m0, s11, 0x400
	s_nop 0
	global_load_lds_dwordx4 v204, s[2:3]
	s_add_u32 m0, s12, 0x2000
	s_nop 0
	global_load_lds_dwordx4 v205, s[4:5]
	s_add_u32 m0, s12, 0x2400
	s_nop 0
	global_load_lds_dwordx4 v206, s[4:5]
	s_add_u32 m0, s12, 0x2800
	s_nop 0
	global_load_lds_dwordx4 v207, s[4:5]
	s_add_u32 m0, s12, 0x2c00
	s_nop 0
	global_load_lds_dwordx4 v208, s[4:5]
	s_add_u32 s2, s2, 0x40
	s_addc_u32 s3, s3, 0
	s_add_u32 s4, s4, 0x4000
	s_addc_u32 s5, s5, 0
	s_add_u32 m0, s11, 0x6000
	s_nop 0
	global_load_lds_dwordx4 v203, s[2:3]
	s_add_u32 m0, s11, 0x6400
	s_nop 0
	global_load_lds_dwordx4 v204, s[2:3]
	s_add_u32 m0, s12, 0x8000
	s_nop 0
	global_load_lds_dwordx4 v205, s[4:5]
	s_add_u32 m0, s12, 0x8400
	s_nop 0
	global_load_lds_dwordx4 v206, s[4:5]
	s_add_u32 m0, s12, 0x8800
	s_nop 0
	global_load_lds_dwordx4 v207, s[4:5]
	s_add_u32 m0, s12, 0x8c00
	s_nop 0
	global_load_lds_dwordx4 v208, s[4:5]
	s_add_u32 s2, s2, 0x40
	s_addc_u32 s3, s3, 0
	s_add_u32 s4, s4, 0x4000
	s_addc_u32 s5, s5, 0
	v_mov_b32_e32 v172, 0
	v_mov_b32_e32 v173, 0
	v_mov_b32_e32 v174, 0
	v_mov_b32_e32 v175, 0
	v_mov_b32_e32 v168, 0
	v_mov_b32_e32 v169, 0
	v_mov_b32_e32 v170, 0
	v_mov_b32_e32 v171, 0
	v_mov_b32_e32 v116, 0
	v_mov_b32_e32 v117, 0
	v_mov_b32_e32 v118, 0
	v_mov_b32_e32 v119, 0
	v_mov_b32_e32 v112, 0
	v_mov_b32_e32 v113, 0
	v_mov_b32_e32 v114, 0
	v_mov_b32_e32 v115, 0
	v_mov_b32_e32 v108, 0
	v_mov_b32_e32 v109, 0
	v_mov_b32_e32 v110, 0
	v_mov_b32_e32 v111, 0
	v_mov_b32_e32 v104, 0
	v_mov_b32_e32 v105, 0
	v_mov_b32_e32 v106, 0
	v_mov_b32_e32 v107, 0
	v_mov_b32_e32 v100, 0
	v_mov_b32_e32 v101, 0
	v_mov_b32_e32 v102, 0
	v_mov_b32_e32 v103, 0
	v_mov_b32_e32 v96, 0
	v_mov_b32_e32 v97, 0
	v_mov_b32_e32 v98, 0
	v_mov_b32_e32 v99, 0
	v_mov_b32_e32 v92, 0
	v_mov_b32_e32 v93, 0
	v_mov_b32_e32 v94, 0
	v_mov_b32_e32 v95, 0
	v_mov_b32_e32 v88, 0
	v_mov_b32_e32 v89, 0
	v_mov_b32_e32 v90, 0
	v_mov_b32_e32 v91, 0
	v_mov_b32_e32 v84, 0
	v_mov_b32_e32 v85, 0
	v_mov_b32_e32 v86, 0
	v_mov_b32_e32 v87, 0
	v_mov_b32_e32 v80, 0
	v_mov_b32_e32 v81, 0
	v_mov_b32_e32 v82, 0
	v_mov_b32_e32 v83, 0
	v_mov_b32_e32 v76, 0
	v_mov_b32_e32 v77, 0
	v_mov_b32_e32 v78, 0
	v_mov_b32_e32 v79, 0
	v_mov_b32_e32 v72, 0
	v_mov_b32_e32 v73, 0
	v_mov_b32_e32 v74, 0
	v_mov_b32_e32 v75, 0
	v_mov_b32_e32 v68, 0
	v_mov_b32_e32 v69, 0
	v_mov_b32_e32 v70, 0
	v_mov_b32_e32 v71, 0
	v_mov_b32_e32 v64, 0
	v_mov_b32_e32 v65, 0
	v_mov_b32_e32 v66, 0
	v_mov_b32_e32 v67, 0
	v_mov_b32_e32 v60, 0
	v_mov_b32_e32 v61, 0
	v_mov_b32_e32 v62, 0
	v_mov_b32_e32 v63, 0
	v_mov_b32_e32 v56, 0
	v_mov_b32_e32 v57, 0
	v_mov_b32_e32 v58, 0
	v_mov_b32_e32 v59, 0
	v_mov_b32_e32 v52, 0
	v_mov_b32_e32 v53, 0
	v_mov_b32_e32 v54, 0
	v_mov_b32_e32 v55, 0
	v_mov_b32_e32 v48, 0
	v_mov_b32_e32 v49, 0
	v_mov_b32_e32 v50, 0
	v_mov_b32_e32 v51, 0
	v_mov_b32_e32 v44, 0
	v_mov_b32_e32 v45, 0
	v_mov_b32_e32 v46, 0
	v_mov_b32_e32 v47, 0
	v_mov_b32_e32 v40, 0
	v_mov_b32_e32 v41, 0
	v_mov_b32_e32 v42, 0
	v_mov_b32_e32 v43, 0
	v_mov_b32_e32 v36, 0
	v_mov_b32_e32 v37, 0
	v_mov_b32_e32 v38, 0
	v_mov_b32_e32 v39, 0
	v_mov_b32_e32 v32, 0
	v_mov_b32_e32 v33, 0
	v_mov_b32_e32 v34, 0
	v_mov_b32_e32 v35, 0
	v_mov_b32_e32 v28, 0
	v_mov_b32_e32 v29, 0
	v_mov_b32_e32 v30, 0
	v_mov_b32_e32 v31, 0
	v_mov_b32_e32 v24, 0
	v_mov_b32_e32 v25, 0
	v_mov_b32_e32 v26, 0
	v_mov_b32_e32 v27, 0
	v_mov_b32_e32 v20, 0
	v_mov_b32_e32 v21, 0
	v_mov_b32_e32 v22, 0
	v_mov_b32_e32 v23, 0
	v_mov_b32_e32 v16, 0
	v_mov_b32_e32 v17, 0
	v_mov_b32_e32 v18, 0
	v_mov_b32_e32 v19, 0
	v_mov_b32_e32 v12, 0
	v_mov_b32_e32 v13, 0
	v_mov_b32_e32 v14, 0
	v_mov_b32_e32 v15, 0
	v_mov_b32_e32 v8, 0
	v_mov_b32_e32 v9, 0
	v_mov_b32_e32 v10, 0
	v_mov_b32_e32 v11, 0
	v_mov_b32_e32 v4, 0
	v_mov_b32_e32 v5, 0
	v_mov_b32_e32 v6, 0
	v_mov_b32_e32 v7, 0
	v_mov_b32_e32 v0, 0
	v_mov_b32_e32 v1, 0
	v_mov_b32_e32 v2, 0
	v_mov_b32_e32 v3, 0
	s_waitcnt vmcnt(6)
	s_barrier
	ds_read_b128 v[120:123], v209 offset:0
	ds_read_b128 v[124:127], v209 offset:1024
	ds_read_b128 v[128:131], v209 offset:2048
	ds_read_b128 v[132:135], v209 offset:3072
	ds_read_b128 v[152:155], v210 offset:8192
	ds_read_b128 v[156:159], v210 offset:9216
	ds_read_b128 v[160:163], v210 offset:10240
	ds_read_b128 v[164:167], v210 offset:11264
	ds_read_b128 v[176:179], v210 offset:12288
	ds_read_b128 v[180:183], v210 offset:13312
	s_add_u32 m0, s11, 0xc000
	s_nop 0
	global_load_lds_dwordx4 v203, s[2:3]
	s_add_u32 m0, s11, 0xc400
	s_nop 0
	global_load_lds_dwordx4 v204, s[2:3]
	s_add_u32 m0, s12, 0xe000
	s_nop 0
	global_load_lds_dwordx4 v205, s[4:5]
	s_add_u32 m0, s12, 0xe400
	s_nop 0
	global_load_lds_dwordx4 v206, s[4:5]
	s_add_u32 m0, s12, 0xe800
	s_nop 0
	global_load_lds_dwordx4 v207, s[4:5]
	s_add_u32 m0, s12, 0xec00
	s_nop 0
	global_load_lds_dwordx4 v208, s[4:5]
	s_add_u32 s2, s2, 0x40
	s_addc_u32 s3, s3, 0
	s_add_u32 s4, s4, 0x4000
	s_addc_u32 s5, s5, 0
	ds_read_b128 v[184:187], v210 offset:14336
	ds_read_b128 v[188:191], v210 offset:15360
	s_waitcnt lgkmcnt(7)
	v_mfma_f32_16x16x32_bf16 v[172:175], v[152:155], v[120:123], v[172:175]
	v_mfma_f32_16x16x32_bf16 v[92:95], v[152:155], v[124:127], v[92:95]
	v_mfma_f32_16x16x32_bf16 v[60:63], v[152:155], v[128:131], v[60:63]
	v_mfma_f32_16x16x32_bf16 v[28:31], v[152:155], v[132:135], v[28:31]
	s_waitcnt lgkmcnt(6)
	v_mfma_f32_16x16x32_bf16 v[168:171], v[156:159], v[120:123], v[168:171]
	v_mfma_f32_16x16x32_bf16 v[88:91], v[156:159], v[124:127], v[88:91]
	v_mfma_f32_16x16x32_bf16 v[56:59], v[156:159], v[128:131], v[56:59]
	v_mfma_f32_16x16x32_bf16 v[24:27], v[156:159], v[132:135], v[24:27]
	s_waitcnt lgkmcnt(5)
	v_mfma_f32_16x16x32_bf16 v[116:119], v[160:163], v[120:123], v[116:119]
	v_mfma_f32_16x16x32_bf16 v[84:87], v[160:163], v[124:127], v[84:87]
	v_mfma_f32_16x16x32_bf16 v[52:55], v[160:163], v[128:131], v[52:55]
	v_mfma_f32_16x16x32_bf16 v[20:23], v[160:163], v[132:135], v[20:23]
	s_waitcnt lgkmcnt(4)
	v_mfma_f32_16x16x32_bf16 v[112:115], v[164:167], v[120:123], v[112:115]
	v_mfma_f32_16x16x32_bf16 v[80:83], v[164:167], v[124:127], v[80:83]
	v_mfma_f32_16x16x32_bf16 v[48:51], v[164:167], v[128:131], v[48:51]
	v_mfma_f32_16x16x32_bf16 v[16:19], v[164:167], v[132:135], v[16:19]
	s_waitcnt lgkmcnt(3)
	v_mfma_f32_16x16x32_bf16 v[108:111], v[176:179], v[120:123], v[108:111]
	v_mfma_f32_16x16x32_bf16 v[76:79], v[176:179], v[124:127], v[76:79]
	v_mfma_f32_16x16x32_bf16 v[44:47], v[176:179], v[128:131], v[44:47]
	v_mfma_f32_16x16x32_bf16 v[12:15], v[176:179], v[132:135], v[12:15]
	s_waitcnt lgkmcnt(2)
	v_mfma_f32_16x16x32_bf16 v[104:107], v[180:183], v[120:123], v[104:107]
	v_mfma_f32_16x16x32_bf16 v[72:75], v[180:183], v[124:127], v[72:75]
	v_mfma_f32_16x16x32_bf16 v[40:43], v[180:183], v[128:131], v[40:43]
	v_mfma_f32_16x16x32_bf16 v[8:11], v[180:183], v[132:135], v[8:11]
	s_waitcnt lgkmcnt(0)
	s_mov_b32 s13, 5
